# plus 16-byte merged bf16 stores in the gelu (phase 1) and QKV (phase 7) epilogues
# speedup vs baseline: 1.0900x; 1.0039x over previous
.LBB0_231:
	ds_read_b128 v[142:145], v172
	ds_read_b128 v[146:149], v172 offset:1024
	ds_read_b128 v[150:153], v172 offset:2048
	ds_read_b128 v[154:157], v172 offset:3072
	ds_read_b128 v[158:161], v173
	ds_read_b128 v[176:179], v173 offset:1024
	ds_read_b128 v[180:183], v173 offset:2048
	ds_read_b128 v[184:187], v173 offset:3072
	s_add_u32 s46, s30, 0xfffc0080
	s_addc_u32 s47, s31, -1
	s_cmp_eq_u32 s66, 12
	s_cselect_b32 s49, s7, s47
	s_cselect_b32 s48, s25, s46
	s_cselect_b32 s47, s9, s65
	s_cselect_b32 s46, s63, s64
	v_lshl_add_u64 v[162:163], s[30:31], 0, v[136:137]
	s_add_i32 m0, s15, 0xc000
	ds_read_b128 v[188:191], v174
	ds_read_b128 v[192:195], v174 offset:1024
	ds_read_b128 v[196:199], v174 offset:2048
	ds_read_b128 v[200:203], v174 offset:3072
	ds_read_b128 v[204:207], v174 offset:4096
	ds_read_b128 v[208:211], v174 offset:5120
	ds_read_b128 v[216:219], v174 offset:6144
	ds_read_b128 v[220:223], v174 offset:7168
	global_load_lds_dwordx4 v[162:163], off
	v_lshl_add_u64 v[162:163], s[30:31], 0, v[138:139]
	s_add_i32 m0, s15, 0xe000
	s_nop 0
	global_load_lds_dwordx4 v[162:163], off
	s_waitcnt vmcnt(8)
	s_waitcnt lgkmcnt(0)
	s_barrier
	s_setprio 1
	s_waitcnt lgkmcnt(0)
	v_mfma_f32_16x16x32_bf16 v[124:127], v[142:145], v[188:191], v[124:127]
	v_mfma_f32_16x16x32_bf16 v[120:123], v[150:153], v[188:191], v[120:123]
	v_mfma_f32_16x16x32_bf16 v[108:111], v[142:145], v[196:199], v[108:111]
	v_mfma_f32_16x16x32_bf16 v[104:107], v[150:153], v[196:199], v[104:107]
	v_mfma_f32_16x16x32_bf16 v[92:95], v[142:145], v[204:207], v[92:95]
	v_mfma_f32_16x16x32_bf16 v[88:91], v[150:153], v[204:207], v[88:91]
	v_mfma_f32_16x16x32_bf16 v[76:79], v[142:145], v[216:219], v[76:79]
	v_mfma_f32_16x16x32_bf16 v[72:75], v[150:153], v[216:219], v[72:75]
	v_mfma_f32_16x16x32_bf16 v[124:127], v[146:149], v[192:195], v[124:127]
	v_mfma_f32_16x16x32_bf16 v[120:123], v[154:157], v[192:195], v[120:123]
	v_mfma_f32_16x16x32_bf16 v[108:111], v[146:149], v[200:203], v[108:111]
	v_mfma_f32_16x16x32_bf16 v[104:107], v[154:157], v[200:203], v[104:107]
	v_mfma_f32_16x16x32_bf16 v[92:95], v[146:149], v[208:211], v[92:95]
	v_mfma_f32_16x16x32_bf16 v[88:91], v[154:157], v[208:211], v[88:91]
	v_mfma_f32_16x16x32_bf16 v[76:79], v[146:149], v[220:223], v[76:79]
	v_mfma_f32_16x16x32_bf16 v[72:75], v[154:157], v[220:223], v[72:75]
	s_setprio 0
	s_setprio 1
	v_mfma_f32_16x16x32_bf16 v[116:119], v[158:161], v[188:191], v[116:119]
	v_mfma_f32_16x16x32_bf16 v[112:115], v[180:183], v[188:191], v[112:115]
	v_mfma_f32_16x16x32_bf16 v[100:103], v[158:161], v[196:199], v[100:103]
	v_mfma_f32_16x16x32_bf16 v[96:99], v[180:183], v[196:199], v[96:99]
	v_mfma_f32_16x16x32_bf16 v[84:87], v[158:161], v[204:207], v[84:87]
	v_mfma_f32_16x16x32_bf16 v[80:83], v[180:183], v[204:207], v[80:83]
	v_mfma_f32_16x16x32_bf16 v[68:71], v[158:161], v[216:219], v[68:71]
	v_mfma_f32_16x16x32_bf16 v[64:67], v[180:183], v[216:219], v[64:67]
	v_mfma_f32_16x16x32_bf16 v[116:119], v[176:179], v[192:195], v[116:119]
	v_mfma_f32_16x16x32_bf16 v[112:115], v[184:187], v[192:195], v[112:115]
	v_mfma_f32_16x16x32_bf16 v[100:103], v[176:179], v[200:203], v[100:103]
	v_mfma_f32_16x16x32_bf16 v[96:99], v[184:187], v[200:203], v[96:99]
	v_mfma_f32_16x16x32_bf16 v[84:87], v[176:179], v[208:211], v[84:87]
	v_mfma_f32_16x16x32_bf16 v[80:83], v[184:187], v[208:211], v[80:83]
	v_mfma_f32_16x16x32_bf16 v[68:71], v[176:179], v[220:223], v[68:71]
	v_mfma_f32_16x16x32_bf16 v[64:67], v[184:187], v[220:223], v[64:67]
	s_setprio 0
	s_barrier
	s_add_i32 s67, s12, s53
	v_lshl_add_u64 v[162:163], s[46:47], 0, v[128:129]
	s_mov_b32 m0, s67
	ds_read_b128 v[188:191], v174 offset:16384
	ds_read_b128 v[192:195], v174 offset:17408
	ds_read_b128 v[196:199], v174 offset:18432
	ds_read_b128 v[200:203], v174 offset:19456
	ds_read_b128 v[204:207], v174 offset:20480
	ds_read_b128 v[208:211], v174 offset:21504
	ds_read_b128 v[216:219], v174 offset:22528
	ds_read_b128 v[220:223], v174 offset:23552
	global_load_lds_dwordx4 v[162:163], off
	s_add_i32 m0, s67, 0x2000
	s_add_u32 s68, s46, 0x40000
	v_lshl_add_u64 v[212:213], s[46:47], 0, v[130:131]
	s_addc_u32 s69, s47, 0
	s_add_i32 s67, s62, s53
	global_load_lds_dwordx4 v[212:213], off
	v_lshl_add_u64 v[224:225], s[68:69], 0, v[128:129]
	s_mov_b32 m0, s67
	v_lshl_add_u64 v[226:227], s[48:49], 0, v[130:131]
	global_load_lds_dwordx4 v[224:225], off
	v_lshl_add_u64 v[224:225], s[68:69], 0, v[130:131]
	s_add_i32 m0, s67, 0x2000
	s_nop 0
	global_load_lds_dwordx4 v[224:225], off
	v_lshl_add_u64 v[224:225], s[48:49], 0, v[128:129]
	s_mov_b32 m0, s15
	s_nop 0
	global_load_lds_dwordx4 v[224:225], off
	s_mov_b32 m0, s54
	s_nop 0
	global_load_lds_dwordx4 v[226:227], off
	s_waitcnt vmcnt(8)
	s_waitcnt lgkmcnt(0)
	s_barrier
	s_setprio 1
	s_waitcnt lgkmcnt(0)
	v_mfma_f32_16x16x32_bf16 v[60:63], v[142:145], v[188:191], v[60:63]
	v_mfma_f32_16x16x32_bf16 v[56:59], v[150:153], v[188:191], v[56:59]
	v_mfma_f32_16x16x32_bf16 v[44:47], v[142:145], v[196:199], v[44:47]
	v_mfma_f32_16x16x32_bf16 v[40:43], v[150:153], v[196:199], v[40:43]
	v_mfma_f32_16x16x32_bf16 v[28:31], v[142:145], v[204:207], v[28:31]
	v_mfma_f32_16x16x32_bf16 v[24:27], v[150:153], v[204:207], v[24:27]
	v_mfma_f32_16x16x32_bf16 v[12:15], v[142:145], v[216:219], v[12:15]
	v_mfma_f32_16x16x32_bf16 v[8:11], v[150:153], v[216:219], v[8:11]
	v_mfma_f32_16x16x32_bf16 v[60:63], v[146:149], v[192:195], v[60:63]
	v_mfma_f32_16x16x32_bf16 v[56:59], v[154:157], v[192:195], v[56:59]
	v_mfma_f32_16x16x32_bf16 v[44:47], v[146:149], v[200:203], v[44:47]
	v_mfma_f32_16x16x32_bf16 v[40:43], v[154:157], v[200:203], v[40:43]
	v_mfma_f32_16x16x32_bf16 v[28:31], v[146:149], v[208:211], v[28:31]
	v_mfma_f32_16x16x32_bf16 v[24:27], v[154:157], v[208:211], v[24:27]
	v_mfma_f32_16x16x32_bf16 v[12:15], v[146:149], v[220:223], v[12:15]
	v_mfma_f32_16x16x32_bf16 v[8:11], v[154:157], v[220:223], v[8:11]
	s_setprio 0
	s_setprio 1
	v_mfma_f32_16x16x32_bf16 v[52:55], v[158:161], v[188:191], v[52:55]
	v_mfma_f32_16x16x32_bf16 v[48:51], v[180:183], v[188:191], v[48:51]
	v_mfma_f32_16x16x32_bf16 v[36:39], v[158:161], v[196:199], v[36:39]
	v_mfma_f32_16x16x32_bf16 v[32:35], v[180:183], v[196:199], v[32:35]
	v_mfma_f32_16x16x32_bf16 v[20:23], v[158:161], v[204:207], v[20:23]
	v_mfma_f32_16x16x32_bf16 v[16:19], v[180:183], v[204:207], v[16:19]
	v_mfma_f32_16x16x32_bf16 v[4:7], v[158:161], v[216:219], v[4:7]
	v_mfma_f32_16x16x32_bf16 v[0:3], v[180:183], v[216:219], v[0:3]
	v_mfma_f32_16x16x32_bf16 v[52:55], v[176:179], v[192:195], v[52:55]
	v_mfma_f32_16x16x32_bf16 v[48:51], v[184:187], v[192:195], v[48:51]
	v_mfma_f32_16x16x32_bf16 v[36:39], v[176:179], v[200:203], v[36:39]
	v_mfma_f32_16x16x32_bf16 v[32:35], v[184:187], v[200:203], v[32:35]
	v_mfma_f32_16x16x32_bf16 v[20:23], v[176:179], v[208:211], v[20:23]
	v_mfma_f32_16x16x32_bf16 v[16:19], v[184:187], v[208:211], v[16:19]
	v_mfma_f32_16x16x32_bf16 v[4:7], v[176:179], v[220:223], v[4:7]
	v_mfma_f32_16x16x32_bf16 v[0:3], v[184:187], v[220:223], v[0:3]
	s_setprio 0
	s_barrier
	s_add_i32 s67, 0, 0x18000
	v_add_u32_e32 v132, s67, v167
	s_add_i32 s68, 0, 0x1c000
	ds_read_b128 v[142:145], v132
	ds_read_b128 v[146:149], v132 offset:1024
	ds_read_b128 v[150:153], v132 offset:2048
	ds_read_b128 v[154:157], v132 offset:3072
	v_add_u32_e32 v132, s68, v167
	ds_read_b128 v[158:161], v132
	ds_read_b128 v[176:179], v132 offset:1024
	ds_read_b128 v[180:183], v132 offset:2048
	ds_read_b128 v[184:187], v132 offset:3072
	s_add_u32 s48, s48, 0x40000
	s_addc_u32 s49, s49, 0
	s_mov_b32 m0, s55
	v_lshl_add_u64 v[228:229], s[48:49], 0, v[128:129]
	ds_read_b128 v[188:191], v174 offset:32768
	ds_read_b128 v[192:195], v174 offset:33792
	ds_read_b128 v[196:199], v174 offset:34816
	ds_read_b128 v[200:203], v174 offset:35840
	ds_read_b128 v[204:207], v174 offset:36864
	ds_read_b128 v[208:211], v174 offset:37888
	ds_read_b128 v[216:219], v174 offset:38912
	ds_read_b128 v[220:223], v174 offset:39936
	global_load_lds_dwordx4 v[228:229], off
	v_lshl_add_u64 v[228:229], s[48:49], 0, v[130:131]
	s_mov_b32 m0, s56
	s_nop 0
	global_load_lds_dwordx4 v[228:229], off
	s_waitcnt vmcnt(8)
	s_waitcnt lgkmcnt(0)
	s_barrier
	s_setprio 1
	s_waitcnt lgkmcnt(0)
	v_mfma_f32_16x16x32_bf16 v[124:127], v[142:145], v[188:191], v[124:127]
	v_mfma_f32_16x16x32_bf16 v[120:123], v[150:153], v[188:191], v[120:123]
	v_mfma_f32_16x16x32_bf16 v[108:111], v[142:145], v[196:199], v[108:111]
	v_mfma_f32_16x16x32_bf16 v[104:107], v[150:153], v[196:199], v[104:107]
	v_mfma_f32_16x16x32_bf16 v[92:95], v[142:145], v[204:207], v[92:95]
	v_mfma_f32_16x16x32_bf16 v[88:91], v[150:153], v[204:207], v[88:91]
	v_mfma_f32_16x16x32_bf16 v[76:79], v[142:145], v[216:219], v[76:79]
	v_mfma_f32_16x16x32_bf16 v[72:75], v[150:153], v[216:219], v[72:75]
	v_mfma_f32_16x16x32_bf16 v[124:127], v[146:149], v[192:195], v[124:127]
	v_mfma_f32_16x16x32_bf16 v[120:123], v[154:157], v[192:195], v[120:123]
	v_mfma_f32_16x16x32_bf16 v[108:111], v[146:149], v[200:203], v[108:111]
	v_mfma_f32_16x16x32_bf16 v[104:107], v[154:157], v[200:203], v[104:107]
	v_mfma_f32_16x16x32_bf16 v[92:95], v[146:149], v[208:211], v[92:95]
	v_mfma_f32_16x16x32_bf16 v[88:91], v[154:157], v[208:211], v[88:91]
	v_mfma_f32_16x16x32_bf16 v[76:79], v[146:149], v[220:223], v[76:79]
	v_mfma_f32_16x16x32_bf16 v[72:75], v[154:157], v[220:223], v[72:75]
	s_setprio 0
	s_setprio 1
	v_mfma_f32_16x16x32_bf16 v[116:119], v[158:161], v[188:191], v[116:119]
	v_mfma_f32_16x16x32_bf16 v[112:115], v[180:183], v[188:191], v[112:115]
	v_mfma_f32_16x16x32_bf16 v[100:103], v[158:161], v[196:199], v[100:103]
	v_mfma_f32_16x16x32_bf16 v[96:99], v[180:183], v[196:199], v[96:99]
	v_mfma_f32_16x16x32_bf16 v[84:87], v[158:161], v[204:207], v[84:87]
	v_mfma_f32_16x16x32_bf16 v[80:83], v[180:183], v[204:207], v[80:83]
	v_mfma_f32_16x16x32_bf16 v[68:71], v[158:161], v[216:219], v[68:71]
	v_mfma_f32_16x16x32_bf16 v[64:67], v[180:183], v[216:219], v[64:67]
	v_mfma_f32_16x16x32_bf16 v[116:119], v[176:179], v[192:195], v[116:119]
	v_mfma_f32_16x16x32_bf16 v[112:115], v[184:187], v[192:195], v[112:115]
	v_mfma_f32_16x16x32_bf16 v[100:103], v[176:179], v[200:203], v[100:103]
	v_mfma_f32_16x16x32_bf16 v[96:99], v[184:187], v[200:203], v[96:99]
	v_mfma_f32_16x16x32_bf16 v[84:87], v[176:179], v[208:211], v[84:87]
	v_mfma_f32_16x16x32_bf16 v[80:83], v[184:187], v[208:211], v[80:83]
	v_mfma_f32_16x16x32_bf16 v[68:71], v[176:179], v[220:223], v[68:71]
	v_mfma_f32_16x16x32_bf16 v[64:67], v[184:187], v[220:223], v[64:67]
	s_setprio 0
	s_barrier
	s_add_i32 s48, s67, s53
	v_lshl_add_u64 v[162:163], v[162:163], 0, s[20:21]
	s_mov_b32 m0, s48
	ds_read_b128 v[188:191], v174 offset:49152
	ds_read_b128 v[192:195], v174 offset:50176
	ds_read_b128 v[196:199], v174 offset:51200
	ds_read_b128 v[200:203], v174 offset:52224
	ds_read_b128 v[204:207], v174 offset:53248
	ds_read_b128 v[208:211], v174 offset:54272
	ds_read_b128 v[216:219], v174 offset:55296
	ds_read_b128 v[220:223], v174 offset:56320
	global_load_lds_dwordx4 v[162:163], off
	s_add_i32 m0, s48, 0x2000
	s_add_u32 s46, s46, 0x40080
	v_lshl_add_u64 v[162:163], v[212:213], 0, s[20:21]
	s_addc_u32 s47, s47, 0
	s_add_i32 s48, s68, s53
	global_load_lds_dwordx4 v[162:163], off
	v_lshl_add_u64 v[162:163], s[46:47], 0, v[128:129]
	s_mov_b32 m0, s48
	s_nop 0
	global_load_lds_dwordx4 v[162:163], off
	v_lshl_add_u64 v[162:163], s[46:47], 0, v[130:131]
	s_add_i32 m0, s48, 0x2000
	s_nop 0
	global_load_lds_dwordx4 v[162:163], off
	v_lshl_add_u64 v[162:163], v[224:225], 0, s[20:21]
	s_mov_b32 m0, s60
	s_nop 0
	global_load_lds_dwordx4 v[162:163], off
	v_lshl_add_u64 v[162:163], v[226:227], 0, s[20:21]
	s_mov_b32 m0, s61
	s_nop 0
	global_load_lds_dwordx4 v[162:163], off
	s_waitcnt vmcnt(8)
	s_waitcnt lgkmcnt(0)
	s_barrier
	s_setprio 1
	s_waitcnt lgkmcnt(0)
	v_mfma_f32_16x16x32_bf16 v[60:63], v[142:145], v[188:191], v[60:63]
	v_mfma_f32_16x16x32_bf16 v[56:59], v[150:153], v[188:191], v[56:59]
	v_mfma_f32_16x16x32_bf16 v[44:47], v[142:145], v[196:199], v[44:47]
	v_mfma_f32_16x16x32_bf16 v[40:43], v[150:153], v[196:199], v[40:43]
	v_mfma_f32_16x16x32_bf16 v[28:31], v[142:145], v[204:207], v[28:31]
	v_mfma_f32_16x16x32_bf16 v[24:27], v[150:153], v[204:207], v[24:27]
	v_mfma_f32_16x16x32_bf16 v[12:15], v[142:145], v[216:219], v[12:15]
	v_mfma_f32_16x16x32_bf16 v[8:11], v[150:153], v[216:219], v[8:11]
	v_mfma_f32_16x16x32_bf16 v[60:63], v[146:149], v[192:195], v[60:63]
	v_mfma_f32_16x16x32_bf16 v[56:59], v[154:157], v[192:195], v[56:59]
	v_mfma_f32_16x16x32_bf16 v[44:47], v[146:149], v[200:203], v[44:47]
	v_mfma_f32_16x16x32_bf16 v[40:43], v[154:157], v[200:203], v[40:43]
	v_mfma_f32_16x16x32_bf16 v[28:31], v[146:149], v[208:211], v[28:31]
	v_mfma_f32_16x16x32_bf16 v[24:27], v[154:157], v[208:211], v[24:27]
	v_mfma_f32_16x16x32_bf16 v[12:15], v[146:149], v[220:223], v[12:15]
	v_mfma_f32_16x16x32_bf16 v[8:11], v[154:157], v[220:223], v[8:11]
	s_setprio 0
	s_setprio 1
	v_mfma_f32_16x16x32_bf16 v[52:55], v[158:161], v[188:191], v[52:55]
	v_mfma_f32_16x16x32_bf16 v[48:51], v[180:183], v[188:191], v[48:51]
	v_mfma_f32_16x16x32_bf16 v[36:39], v[158:161], v[196:199], v[36:39]
	v_mfma_f32_16x16x32_bf16 v[32:35], v[180:183], v[196:199], v[32:35]
	v_mfma_f32_16x16x32_bf16 v[20:23], v[158:161], v[204:207], v[20:23]
	v_mfma_f32_16x16x32_bf16 v[16:19], v[180:183], v[204:207], v[16:19]
	v_mfma_f32_16x16x32_bf16 v[4:7], v[158:161], v[216:219], v[4:7]
	v_mfma_f32_16x16x32_bf16 v[0:3], v[180:183], v[216:219], v[0:3]
	v_mfma_f32_16x16x32_bf16 v[52:55], v[176:179], v[192:195], v[52:55]
	v_mfma_f32_16x16x32_bf16 v[48:51], v[184:187], v[192:195], v[48:51]
	v_mfma_f32_16x16x32_bf16 v[36:39], v[176:179], v[200:203], v[36:39]
	v_mfma_f32_16x16x32_bf16 v[32:35], v[184:187], v[200:203], v[32:35]
	v_mfma_f32_16x16x32_bf16 v[20:23], v[176:179], v[208:211], v[20:23]
	v_mfma_f32_16x16x32_bf16 v[16:19], v[184:187], v[208:211], v[16:19]
	v_mfma_f32_16x16x32_bf16 v[4:7], v[176:179], v[220:223], v[4:7]
	v_mfma_f32_16x16x32_bf16 v[0:3], v[184:187], v[220:223], v[0:3]
	s_setprio 0
	s_barrier
	s_add_i32 s66, s66, 2
	s_add_u32 s30, s30, 0x100
	s_addc_u32 s31, s31, 0
	s_add_u32 s64, s64, 0x100
	s_addc_u32 s65, s65, 0
	s_cmp_gt_u32 s66, 13
	s_cbranch_scc0 .LBB0_231
	v_mbcnt_lo_u32_b32 v238, -1, 0
	v_mbcnt_hi_u32_b32 v238, -1, v238
	v_bfe_u32 v238, v238, 4, 1
	v_mul_u32_u24_e32 v238, 24, v238
	v_mov_b32_e32 v239, 0
	s_and_b64 vcc, exec, s[22:23]
	s_cbranch_vccz .LBB0_234
	s_barrier
.LBB0_234:
	s_cmp_gt_i32 s14, 3
	s_cselect_b64 s[30:31], -1, 0
	s_and_b64 s[46:47], s[30:31], exec
	s_cselect_b32 s46, s44, s40
	s_cselect_b32 s47, s45, s41
	s_lshl_b32 s9, s6, 8
	v_add_u32_e32 v152, s9, v166
	v_or_b32_e32 v144, 16, v152
	v_ashrrev_i32_e32 v153, 31, v152
	v_ashrrev_i32_e32 v145, 31, v144
	v_lshlrev_b64 v[142:143], 6, v[152:153]
	v_lshlrev_b64 v[144:145], 6, v[144:145]
	v_or_b32_e32 v150, 32, v152
	v_lshl_add_u64 v[142:143], v[134:135], 0, v[142:143]
	v_lshl_add_u64 v[146:147], v[134:135], 0, v[144:145]
	v_ashrrev_i32_e32 v151, 31, v150
	global_load_dwordx4 v[142:145], v[142:143], off
	s_nop 0
	global_load_dwordx4 v[146:149], v[146:147], off
	v_lshlrev_b64 v[150:151], 6, v[150:151]
	v_lshl_add_u64 v[150:151], v[134:135], 0, v[150:151]
	global_load_dwordx4 v[154:157], v[150:151], off
	v_or_b32_e32 v150, 48, v152
	v_ashrrev_i32_e32 v151, 31, v150
	v_lshlrev_b64 v[150:151], 6, v[150:151]
	v_lshl_add_u64 v[150:151], v[134:135], 0, v[150:151]
	global_load_dwordx4 v[158:161], v[150:151], off
	s_lshl_b32 s6, s14, 8
	s_and_b32 s6, s6, 0x300
	s_cmp_lt_i32 s14, 4
	s_waitcnt vmcnt(0)
	v_mov_b32_e32 v150, v143
	v_mov_b32_e32 v151, v144
	v_mov_b32_e32 v143, v145
	v_pk_add_f32 v[142:143], v[150:151], v[142:143]
	v_add_f32_e32 v132, v146, v147
	v_add_f32_e32 v144, v148, v149
	v_add_f32_e32 v142, v142, v143
	v_add_f32_e32 v145, v154, v155
	v_add_f32_e32 v146, v156, v157
	v_add_f32_e32 v132, v132, v144
	ds_bpermute_b32 v144, v164, v142
	v_add_f32_e32 v143, v145, v146
	ds_bpermute_b32 v145, v164, v132
	v_add_f32_e32 v147, v158, v159
	v_add_f32_e32 v148, v160, v161
	v_add_f32_e32 v146, v147, v148
	s_waitcnt lgkmcnt(1)
	v_add_f32_e32 v142, v142, v144
	ds_bpermute_b32 v147, v164, v143
	ds_bpermute_b32 v148, v164, v146
	s_waitcnt lgkmcnt(2)
	v_add_f32_e32 v188, v132, v145
	ds_bpermute_b32 v132, v165, v142
	ds_bpermute_b32 v189, v165, v188
	s_waitcnt lgkmcnt(3)
	v_add_f32_e32 v186, v143, v147
	s_waitcnt lgkmcnt(2)
	v_add_f32_e32 v184, v146, v148
	ds_bpermute_b32 v187, v165, v186
	s_waitcnt lgkmcnt(2)
	v_add_f32_e32 v132, v142, v132
	v_fmamk_f32 v132, v132, 0x3a800000, v175
	ds_bpermute_b32 v185, v165, v184
	v_rsq_f32_e32 v154, v132
	v_or_b32_e32 v132, s6, v171
	v_add_u32_e32 v150, 0x80, v152
	v_add_u32_e32 v148, 0x90, v152
	v_ashrrev_i32_e32 v151, 31, v150
	v_ashrrev_i32_e32 v149, 31, v148
	v_lshlrev_b64 v[142:143], 6, v[150:151]
	v_lshlrev_b64 v[144:145], 6, v[148:149]
	v_lshl_add_u64 v[142:143], v[134:135], 0, v[142:143]
	v_lshl_add_u64 v[144:145], v[134:135], 0, v[144:145]
	global_load_dwordx4 v[156:159], v[142:143], off
	global_load_dwordx4 v[160:163], v[144:145], off
	v_add_u32_e32 v144, 0xa0, v152
	v_ashrrev_i32_e32 v145, 31, v144
	v_lshlrev_b64 v[142:143], 6, v[144:145]
	v_lshl_add_u64 v[142:143], v[134:135], 0, v[142:143]
	global_load_dwordx4 v[176:179], v[142:143], off
	v_add_u32_e32 v142, 0xb0, v152
	v_ashrrev_i32_e32 v143, 31, v142
	v_lshlrev_b64 v[146:147], 6, v[142:143]
	v_lshl_add_u64 v[146:147], v[134:135], 0, v[146:147]
	global_load_dwordx4 v[180:183], v[146:147], off
	s_waitcnt vmcnt(3)
	v_add_f32_e32 v146, v156, v157
	v_add_f32_e32 v147, v158, v159
	s_waitcnt vmcnt(2)
	v_add_f32_e32 v155, v160, v161
	v_add_f32_e32 v156, v162, v163
	v_add_f32_e32 v146, v146, v147
	v_add_f32_e32 v147, v155, v156
	s_waitcnt vmcnt(1)
	v_add_f32_e32 v157, v176, v177
	v_add_f32_e32 v158, v178, v179
	v_add_f32_e32 v155, v157, v158
	ds_bpermute_b32 v157, v164, v146
	ds_bpermute_b32 v158, v164, v147
	s_waitcnt vmcnt(0)
	v_add_f32_e32 v159, v180, v181
	v_add_f32_e32 v160, v182, v183
	v_add_f32_e32 v156, v159, v160
	ds_bpermute_b32 v159, v164, v155
	ds_bpermute_b32 v160, v164, v156
	s_waitcnt lgkmcnt(3)
	v_add_f32_e32 v182, v146, v157
	s_waitcnt lgkmcnt(2)
	v_add_f32_e32 v180, v147, v158
	ds_bpermute_b32 v183, v165, v182
	s_waitcnt lgkmcnt(2)
	v_add_f32_e32 v178, v155, v159
	s_waitcnt lgkmcnt(1)
	v_add_f32_e32 v176, v156, v160
	ds_bpermute_b32 v181, v165, v180
	ds_bpermute_b32 v179, v165, v178
	ds_bpermute_b32 v177, v165, v176
	v_lshlrev_b32_e32 v132, 1, v132
	v_pk_mul_f32 v[124:125], v[124:125], v[154:155] op_sel_hi:[1,0]
	v_lshl_add_u64 v[146:147], s[46:47], 0, v[132:133]
	v_mul_f32_e32 v132, 0x3d372713, v124
	v_mul_f32_e32 v155, 0x3d372713, v125
	v_mul_f32_e32 v132, v124, v132
	v_mul_f32_e32 v155, v125, v155
	v_fma_f32 v132, v124, v132, v124
	v_fma_f32 v155, v125, v155, v125
	v_mul_f32_e32 v132, 0x3f4c422a, v132
	v_mul_f32_e32 v155, 0x3f4c422a, v155
	v_mul_f32_e32 v132, 0xc038aa3b, v132
	v_mul_f32_e32 v155, 0xc038aa3b, v155
	v_exp_f32_e32 v132, v132
	v_exp_f32_e32 v155, v155
	v_lshlrev_b64 v[156:157], 11, v[152:153]
	v_lshl_add_u64 v[190:191], v[146:147], 0, v[156:157]
	v_add_f32_e32 v132, 1.0, v132
	v_pk_mul_f32 v[126:127], v[126:127], v[154:155] op_sel_hi:[1,0]
	v_rcp_f32_e32 v156, v132
	v_add_f32_e32 v132, 1.0, v155
	v_mul_f32_e32 v155, 0x3d372713, v126
	v_mul_f32_e32 v155, v126, v155
	v_fma_f32 v155, v126, v155, v126
	v_mul_f32_e32 v155, 0x3f4c422a, v155
	v_mul_f32_e32 v155, 0xc038aa3b, v155
	v_exp_f32_e32 v155, v155
	v_mul_f32_e32 v157, 0x3d372713, v127
	v_mul_f32_e32 v157, v127, v157
	v_fma_f32 v157, v127, v157, v127
	v_pk_mul_f32 v[192:193], v[120:121], v[154:155] op_sel_hi:[1,0]
	v_mul_f32_e32 v157, 0x3f4c422a, v157
	v_mul_f32_e32 v120, 0x3d372713, v192
	v_mul_f32_e32 v120, v192, v120
	v_mul_f32_e32 v121, 0x3d372713, v193
	v_fma_f32 v120, v192, v120, v192
	v_mul_f32_e32 v121, v193, v121
	v_mul_f32_e32 v120, 0x3f4c422a, v120
	v_fma_f32 v121, v193, v121, v193
	v_mul_f32_e32 v120, 0xc038aa3b, v120
	v_mul_f32_e32 v121, 0x3f4c422a, v121
	v_mul_f32_e32 v157, 0xc038aa3b, v157
	v_exp_f32_e32 v120, v120
	v_mul_f32_e32 v121, 0xc038aa3b, v121
	v_exp_f32_e32 v157, v157
	v_exp_f32_e32 v121, v121
	v_rcp_f32_e32 v158, v132
	v_add_f32_e32 v132, 1.0, v155
	v_add_f32_e32 v120, 1.0, v120
	v_rcp_f32_e32 v160, v132
	v_add_f32_e32 v132, 1.0, v157
	v_rcp_f32_e32 v157, v120
	v_add_f32_e32 v120, 1.0, v121
	v_rcp_f32_e32 v161, v120
	v_pk_mul_f32 v[194:195], v[122:123], v[154:155] op_sel_hi:[1,0]
	v_mov_b32_e32 v121, v192
	v_pk_mov_b32 v[122:123], v[124:125], v[192:193] op_sel:[1,0]
	v_mov_b32_e32 v159, v157
	v_mov_b32_e32 v192, v126
	v_mov_b32_e32 v120, v124
	v_pk_mul_f32 v[124:125], v[122:123], v[158:159]
	v_pk_mul_f32 v[122:123], v[192:193], v[160:161]
	v_mov_b32_e32 v192, v127
	v_mul_f32_e32 v126, 0x3d372713, v194
	v_mul_f32_e32 v127, 0x3d372713, v195
	v_mul_f32_e32 v126, v194, v126
	v_mul_f32_e32 v127, v195, v127
	v_fma_f32 v126, v194, v126, v194
	v_fma_f32 v127, v195, v127, v195
	v_mul_f32_e32 v126, 0x3f4c422a, v126
	v_mul_f32_e32 v127, 0x3f4c422a, v127
	v_pk_mul_f32 v[116:117], v[116:117], v[154:155] op_sel_hi:[1,0]
	v_mul_f32_e32 v126, 0xc038aa3b, v126
	v_mul_f32_e32 v127, 0xc038aa3b, v127
	v_mul_f32_e32 v155, 0x3d372713, v117
	v_exp_f32_e32 v126, v126
	v_exp_f32_e32 v127, v127
	v_mul_f32_e32 v155, v117, v155
	v_fma_f32 v155, v117, v155, v117
	v_mul_f32_e32 v155, 0x3f4c422a, v155
	v_mul_f32_e32 v155, 0xc038aa3b, v155
	v_rcp_f32_e32 v162, v132
	v_add_f32_e32 v126, 1.0, v126
	v_add_f32_e32 v127, 1.0, v127
	v_exp_f32_e32 v155, v155
	v_rcp_f32_e32 v126, v126
	v_rcp_f32_e32 v127, v127
	v_pk_mul_f32 v[120:121], v[120:121], v[156:157]
	v_mov_b32_e32 v163, v161
	v_cvt_pk_bf16_f32 v232, v120, v124
	v_pk_mul_f32 v[156:157], v[192:193], v[162:163]
	v_pk_mul_f32 v[118:119], v[118:119], v[154:155] op_sel_hi:[1,0]
	v_cvt_pk_bf16_f32 v233, v122, v156
	v_cvt_pk_bf16_f32 v234, v121, v123
	v_pk_mul_f32 v[126:127], v[194:195], v[126:127]
	v_mul_f32_e32 v132, 0x3d372713, v116
	v_cvt_pk_bf16_f32 v235, v126, v127
	s_nop 1
	v_permlane16_swap_b32_e32 v232, v234
	v_permlane16_swap_b32_e32 v233, v235
	v_lshl_add_u64 v[236:237], v[190:191], 0, v[238:239]
	global_store_dwordx4 v[236:237], v[232:235], off
	s_nop 1
	v_mul_f32_e32 v158, 0x3d372713, v118
	v_mul_f32_e32 v158, v118, v158
	v_mul_f32_e32 v159, 0x3d372713, v119
	v_mul_f32_e32 v132, v116, v132
	v_fma_f32 v158, v118, v158, v118
	v_mul_f32_e32 v159, v119, v159
	v_fma_f32 v132, v116, v132, v116
	v_mul_f32_e32 v158, 0x3f4c422a, v158
	v_fma_f32 v159, v119, v159, v119
	v_mul_f32_e32 v132, 0x3f4c422a, v132
	v_mul_f32_e32 v158, 0xc038aa3b, v158
	v_mul_f32_e32 v159, 0x3f4c422a, v159
	v_mul_f32_e32 v132, 0xc038aa3b, v132
	v_exp_f32_e32 v158, v158
	v_mul_f32_e32 v159, 0xc038aa3b, v159
	v_exp_f32_e32 v132, v132
	v_exp_f32_e32 v159, v159
	v_add_f32_e32 v155, 1.0, v155
	v_add_f32_e32 v158, 1.0, v158
	v_add_f32_e32 v132, 1.0, v132
	v_rcp_f32_e32 v155, v155
	v_rcp_f32_e32 v161, v158
	v_add_f32_e32 v158, 1.0, v159
	v_rcp_f32_e32 v132, v132
	v_rcp_f32_e32 v159, v158
	v_pk_mul_f32 v[112:113], v[112:113], v[154:155] op_sel_hi:[1,0]
	v_pk_mul_f32 v[114:115], v[114:115], v[154:155] op_sel_hi:[1,0]
	v_mul_f32_e32 v158, v116, v132
	v_mul_f32_e32 v160, v117, v155
	v_mul_f32_e32 v116, v118, v161
	v_mul_f32_e32 v118, v119, v159
	v_mul_f32_e32 v117, 0x3d372713, v112
	v_mul_f32_e32 v119, 0x3d372713, v113
	v_mul_f32_e32 v132, 0x3d372713, v114
	v_mul_f32_e32 v154, 0x3d372713, v115
	v_mul_f32_e32 v117, v112, v117
	v_mul_f32_e32 v119, v113, v119
	v_mul_f32_e32 v132, v114, v132
	v_mul_f32_e32 v154, v115, v154
	v_fma_f32 v117, v112, v117, v112
	v_fma_f32 v119, v113, v119, v113
	v_fma_f32 v132, v114, v132, v114
	v_fma_f32 v154, v115, v154, v115
	v_mul_f32_e32 v117, 0x3f4c422a, v117
	v_mul_f32_e32 v119, 0x3f4c422a, v119
	v_mul_f32_e32 v132, 0x3f4c422a, v132
	v_mul_f32_e32 v154, 0x3f4c422a, v154
	v_mul_f32_e32 v117, 0xc038aa3b, v117
	v_mul_f32_e32 v119, 0xc038aa3b, v119
	v_mul_f32_e32 v132, 0xc038aa3b, v132
	v_mul_f32_e32 v154, 0xc038aa3b, v154
	v_exp_f32_e32 v117, v117
	v_exp_f32_e32 v119, v119
	v_exp_f32_e32 v132, v132
	v_exp_f32_e32 v154, v154
	v_add_f32_e32 v117, 1.0, v117
	v_add_f32_e32 v119, 1.0, v119
	v_add_f32_e32 v132, 1.0, v132
	v_add_f32_e32 v154, 1.0, v154
	v_rcp_f32_e32 v117, v117
	v_rcp_f32_e32 v119, v119
	v_rcp_f32_e32 v132, v132
	v_rcp_f32_e32 v155, v154
	v_cvt_pk_bf16_f32 v232, v158, v160
	v_cvt_pk_bf16_f32 v233, v116, v118
	v_mul_f32_e32 v154, v112, v117
	v_mul_f32_e32 v162, v113, v119
	v_mul_f32_e32 v112, v114, v132
	v_mul_f32_e32 v114, v115, v155
	v_cvt_pk_bf16_f32 v234, v154, v162
	v_cvt_pk_bf16_f32 v235, v112, v114
	s_nop 1
	v_permlane16_swap_b32_e32 v232, v234
	v_permlane16_swap_b32_e32 v233, v235
	v_lshl_add_u64 v[236:237], v[190:191], 0, v[238:239]
	global_store_dwordx4 v[236:237], v[232:235], off offset:256
	s_nop 1
	s_cbranch_scc1 .LBB0_238
	v_pk_mul_f32 v[190:191], v[120:121], v[120:121]
	v_pk_mul_f32 v[192:193], v[124:125], v[124:125]
	v_pk_add_f32 v[198:199], v[120:121], v[124:125]
	v_pk_mul_f32 v[124:125], v[120:121], v[124:125]
	v_pk_mul_f32 v[194:195], v[122:123], v[122:123]
	v_pk_mul_f32 v[196:197], v[156:157], v[156:157]
	v_mov_b32_e32 v199, v125
	v_pk_add_f32 v[124:125], v[122:123], v[156:157]
	v_pk_mul_f32 v[156:157], v[122:123], v[156:157]
	v_mul_f32_e32 v132, v126, v126
	v_pk_mov_b32 v[120:121], v[120:121], v[190:191] op_sel:[1,0]
	v_pk_mov_b32 v[122:123], v[122:123], v[192:193] op_sel:[1,0]
	v_mov_b32_e32 v125, v157
	v_pk_fma_f32 v[156:157], v[126:127], v[126:127], v[132:133] op_sel_hi:[1,1,0]
	v_pk_add_f32 v[120:121], v[120:121], v[122:123]
	v_mov_b32_e32 v122, v126
	v_mov_b32_e32 v123, v194
	v_pk_mov_b32 v[126:127], v[126:127], v[196:197] op_sel:[1,0]
	v_mul_f32_e32 v159, v158, v158
	v_mul_f32_e32 v161, v160, v160
	v_mul_f32_e32 v117, v116, v116
	v_mul_f32_e32 v119, v118, v118
	v_pk_add_f32 v[124:125], v[198:199], v[124:125]
	v_mov_b32_e32 v156, v133
	v_pk_add_f32 v[122:123], v[122:123], v[126:127]
	v_mul_f32_e32 v155, v154, v154
	v_mul_f32_e32 v163, v162, v162
	v_mul_f32_e32 v113, v112, v112
	v_mul_f32_e32 v115, v114, v114
	v_pk_add_f32 v[124:125], v[124:125], v[156:157]
	v_pk_add_f32 v[120:121], v[120:121], v[122:123]
	v_pk_add_f32 v[122:123], v[158:159], v[160:161]
	v_pk_add_f32 v[116:117], v[116:117], v[118:119]
	v_pk_add_f32 v[120:121], v[120:121], v[124:125]
	v_pk_add_f32 v[116:117], v[122:123], v[116:117]
	v_pk_add_f32 v[118:119], v[154:155], v[162:163]
	v_pk_add_f32 v[112:113], v[112:113], v[114:115]
	v_pk_add_f32 v[116:117], v[116:117], v[120:121]
	v_pk_add_f32 v[112:113], v[118:119], v[112:113]
	s_nop 0
	v_pk_add_f32 v[112:113], v[112:113], v[116:117]
	ds_bpermute_b32 v114, v164, v112
	ds_bpermute_b32 v115, v164, v113
	s_waitcnt lgkmcnt(0)
	v_pk_add_f32 v[112:113], v[112:113], v[114:115]
	ds_bpermute_b32 v114, v165, v112
	ds_bpermute_b32 v115, v165, v113
	s_and_saveexec_b64 s[6:7], s[2:3]
	s_cbranch_execz .LBB0_237
	s_lshl_b32 s25, s14, 2
	s_add_i32 s25, s25, -16
	v_mov_b32_e32 v132, s25
	v_lshl_add_u64 v[116:117], v[152:153], 4, v[132:133]
	v_or_b32_e32 v116, s59, v116
	v_lshl_add_u64 v[116:117], v[116:117], 3, s[18:19]
	s_waitcnt lgkmcnt(0)
	v_pk_add_f32 v[112:113], v[112:113], v[114:115]
	global_store_dwordx2 v[116:117], v[112:113], off

.LBB0_238:
	v_add_f32_e32 v112, v188, v189
	v_fmamk_f32 v112, v112, 0x3a800000, v175
	v_rsq_f32_e32 v120, v112
	v_add_u32_e32 v112, s9, v168
	v_ashrrev_i32_e32 v113, 31, v112
	s_waitcnt lgkmcnt(0)
	v_lshlrev_b64 v[114:115], 11, v[112:113]
	v_pk_mul_f32 v[110:111], v[110:111], v[120:121] op_sel_hi:[1,0]
	v_pk_mul_f32 v[108:109], v[108:109], v[120:121] op_sel_hi:[1,0]
	v_mul_f32_e32 v116, 0x3d372713, v110
	v_mul_f32_e32 v116, v110, v116
	v_fma_f32 v116, v110, v116, v110
	v_lshl_add_u64 v[124:125], v[146:147], 0, v[114:115]
	v_mul_f32_e32 v115, 0x3d372713, v109
	v_mul_f32_e32 v116, 0x3f4c422a, v116
	v_mul_f32_e32 v115, v109, v115
	v_mul_f32_e32 v116, 0xc038aa3b, v116
	v_pk_mul_f32 v[126:127], v[104:105], v[120:121] op_sel_hi:[1,0]
	v_fma_f32 v115, v109, v115, v109
	v_exp_f32_e32 v117, v116
	v_mul_f32_e32 v116, 0x3d372713, v111
	v_mul_f32_e32 v104, 0x3d372713, v126
	v_mul_f32_e32 v115, 0x3f4c422a, v115
	v_mul_f32_e32 v116, v111, v116
	v_mul_f32_e32 v104, v126, v104
	v_mul_f32_e32 v105, 0x3d372713, v127
	v_mul_f32_e32 v115, 0xc038aa3b, v115
	v_fma_f32 v116, v111, v116, v111
	v_fma_f32 v104, v126, v104, v126
	v_mul_f32_e32 v105, v127, v105
	v_exp_f32_e32 v115, v115
	v_mul_f32_e32 v116, 0x3f4c422a, v116
	v_mul_f32_e32 v104, 0x3f4c422a, v104
	v_fma_f32 v105, v127, v105, v127
	v_mul_f32_e32 v116, 0xc038aa3b, v116
	v_mul_f32_e32 v104, 0xc038aa3b, v104
	v_mul_f32_e32 v105, 0x3f4c422a, v105
	v_exp_f32_e32 v119, v116
	v_exp_f32_e32 v104, v104
	v_mul_f32_e32 v105, 0xc038aa3b, v105
	v_exp_f32_e32 v105, v105
	v_add_f32_e32 v115, 1.0, v115
	v_rcp_f32_e32 v116, v115
	v_add_f32_e32 v115, 1.0, v117
	v_rcp_f32_e32 v118, v115
	v_add_f32_e32 v115, 1.0, v119
	v_add_f32_e32 v104, 1.0, v104
	v_rcp_f32_e32 v122, v115
	v_rcp_f32_e32 v115, v104
	v_add_f32_e32 v104, 1.0, v105
	v_rcp_f32_e32 v119, v104
	v_mul_f32_e32 v114, 0x3d372713, v108
	v_mul_f32_e32 v114, v108, v114
	v_pk_mul_f32 v[152:153], v[106:107], v[120:121] op_sel_hi:[1,0]
	v_mov_b32_e32 v105, v126
	v_pk_mov_b32 v[106:107], v[108:109], v[126:127] op_sel:[1,0]
	v_mov_b32_e32 v117, v115
	v_mov_b32_e32 v126, v110
	v_fma_f32 v114, v108, v114, v108
	v_mov_b32_e32 v104, v108
	v_pk_mul_f32 v[108:109], v[106:107], v[116:117]
	v_pk_mul_f32 v[106:107], v[126:127], v[118:119]
	v_mov_b32_e32 v126, v111
	v_mul_f32_e32 v110, 0x3d372713, v152
	v_mul_f32_e32 v111, 0x3d372713, v153
	v_mul_f32_e32 v114, 0x3f4c422a, v114
	v_mul_f32_e32 v110, v152, v110
	v_mul_f32_e32 v111, v153, v111
	v_mul_f32_e32 v114, 0xc038aa3b, v114
	v_fma_f32 v110, v152, v110, v152
	v_fma_f32 v111, v153, v111, v153
	v_exp_f32_e32 v114, v114
	v_mul_f32_e32 v110, 0x3f4c422a, v110
	v_mul_f32_e32 v111, 0x3f4c422a, v111
	v_mul_f32_e32 v110, 0xc038aa3b, v110
	v_mul_f32_e32 v111, 0xc038aa3b, v111
	v_exp_f32_e32 v110, v110
	v_exp_f32_e32 v111, v111
	v_add_f32_e32 v114, 1.0, v114
	v_rcp_f32_e32 v114, v114
	v_add_f32_e32 v110, 1.0, v110
	v_add_f32_e32 v111, 1.0, v111
	v_rcp_f32_e32 v110, v110
	v_rcp_f32_e32 v111, v111
	v_pk_mul_f32 v[104:105], v[104:105], v[114:115]
	v_mov_b32_e32 v123, v119
	v_cvt_pk_bf16_f32 v232, v104, v108
	v_pk_mul_f32 v[102:103], v[102:103], v[120:121] op_sel_hi:[1,0]
	v_pk_mul_f32 v[114:115], v[126:127], v[122:123]
	v_pk_mul_f32 v[100:101], v[100:101], v[120:121] op_sel_hi:[1,0]
	v_cvt_pk_bf16_f32 v233, v106, v114
	v_cvt_pk_bf16_f32 v234, v105, v107
	v_mul_f32_e32 v118, 0x3d372713, v102
	v_pk_mul_f32 v[110:111], v[152:153], v[110:111]
	v_mul_f32_e32 v118, v102, v118
	v_cvt_pk_bf16_f32 v235, v110, v111
	s_nop 1
	v_permlane16_swap_b32_e32 v232, v234
	v_permlane16_swap_b32_e32 v233, v235
	v_lshl_add_u64 v[236:237], v[124:125], 0, v[238:239]
	global_store_dwordx4 v[236:237], v[232:235], off
	s_nop 1
	v_mul_f32_e32 v116, 0x3d372713, v100
	v_mul_f32_e32 v119, 0x3d372713, v103
	v_mul_f32_e32 v116, v100, v116
	v_mul_f32_e32 v117, 0x3d372713, v101
	v_fma_f32 v118, v102, v118, v102
	v_mul_f32_e32 v119, v103, v119
	v_fma_f32 v116, v100, v116, v100
	v_mul_f32_e32 v117, v101, v117
	v_mul_f32_e32 v118, 0x3f4c422a, v118
	v_fma_f32 v119, v103, v119, v103
	v_mul_f32_e32 v116, 0x3f4c422a, v116
	v_fma_f32 v117, v101, v117, v101
	v_mul_f32_e32 v118, 0xc038aa3b, v118
	v_mul_f32_e32 v119, 0x3f4c422a, v119
	v_mul_f32_e32 v116, 0xc038aa3b, v116
	v_mul_f32_e32 v117, 0x3f4c422a, v117
	v_exp_f32_e32 v118, v118
	v_mul_f32_e32 v119, 0xc038aa3b, v119
	v_exp_f32_e32 v116, v116
	v_mul_f32_e32 v117, 0xc038aa3b, v117
	v_exp_f32_e32 v119, v119
	v_exp_f32_e32 v117, v117
	v_add_f32_e32 v118, 1.0, v118
	v_add_f32_e32 v116, 1.0, v116
	v_rcp_f32_e32 v121, v118
	v_add_f32_e32 v118, 1.0, v119
	v_rcp_f32_e32 v116, v116
	v_add_f32_e32 v117, 1.0, v117
	v_rcp_f32_e32 v119, v118
	v_rcp_f32_e32 v117, v117
	v_pk_mul_f32 v[96:97], v[96:97], v[120:121] op_sel_hi:[1,0]
	v_mul_f32_e32 v116, v100, v116
	v_mul_f32_e32 v100, v102, v121
	v_mul_f32_e32 v102, v103, v119
	v_mul_f32_e32 v103, 0x3d372713, v97
	v_pk_mul_f32 v[98:99], v[98:99], v[120:121] op_sel_hi:[1,0]
	v_mul_f32_e32 v118, v101, v117
	v_mul_f32_e32 v101, 0x3d372713, v96
	v_mul_f32_e32 v103, v97, v103
	v_mul_f32_e32 v117, 0x3d372713, v98
	v_mul_f32_e32 v119, 0x3d372713, v99
	v_mul_f32_e32 v101, v96, v101
	v_fma_f32 v103, v97, v103, v97
	v_mul_f32_e32 v117, v98, v117
	v_mul_f32_e32 v119, v99, v119
	v_fma_f32 v101, v96, v101, v96
	v_mul_f32_e32 v103, 0x3f4c422a, v103
	v_fma_f32 v117, v98, v117, v98
	v_fma_f32 v119, v99, v119, v99
	v_mul_f32_e32 v101, 0x3f4c422a, v101
	v_mul_f32_e32 v103, 0xc038aa3b, v103
	v_mul_f32_e32 v117, 0x3f4c422a, v117
	v_mul_f32_e32 v119, 0x3f4c422a, v119
	v_mul_f32_e32 v101, 0xc038aa3b, v101
	v_exp_f32_e32 v103, v103
	v_mul_f32_e32 v117, 0xc038aa3b, v117
	v_mul_f32_e32 v119, 0xc038aa3b, v119
	v_exp_f32_e32 v101, v101
	v_exp_f32_e32 v117, v117
	v_exp_f32_e32 v119, v119
	v_add_f32_e32 v103, 1.0, v103
	v_add_f32_e32 v101, 1.0, v101
	v_rcp_f32_e32 v103, v103
	v_add_f32_e32 v117, 1.0, v117
	v_add_f32_e32 v119, 1.0, v119
	v_rcp_f32_e32 v101, v101
	v_rcp_f32_e32 v117, v117
	v_rcp_f32_e32 v119, v119
	v_cvt_pk_bf16_f32 v232, v116, v118
	v_cvt_pk_bf16_f32 v233, v100, v102
	v_mul_f32_e32 v122, v97, v103
	v_cndmask_b32_e64 v97, 0, 1, s[30:31]
	v_mul_f32_e32 v120, v96, v101
	v_mul_f32_e32 v96, v98, v117
	v_mul_f32_e32 v98, v99, v119
	v_cmp_ne_u32_e64 s[6:7], 1, v97
	s_andn2_b64 vcc, exec, s[30:31]
	v_cvt_pk_bf16_f32 v234, v120, v122
	v_cvt_pk_bf16_f32 v235, v96, v98
	s_nop 1
	v_permlane16_swap_b32_e32 v232, v234
	v_permlane16_swap_b32_e32 v233, v235
	v_lshl_add_u64 v[236:237], v[124:125], 0, v[238:239]
	global_store_dwordx4 v[236:237], v[232:235], off offset:256
	s_nop 1
	s_cbranch_vccnz .LBB0_242
	v_pk_mul_f32 v[126:127], v[108:109], v[108:109]
	v_pk_add_f32 v[156:157], v[104:105], v[108:109]
	v_pk_mul_f32 v[108:109], v[104:105], v[108:109]
	v_pk_mul_f32 v[124:125], v[104:105], v[104:105]
	v_pk_mul_f32 v[154:155], v[114:115], v[114:115]
	v_mov_b32_e32 v157, v109
	v_pk_add_f32 v[108:109], v[106:107], v[114:115]
	v_pk_mul_f32 v[114:115], v[106:107], v[114:115]
	v_pk_mul_f32 v[152:153], v[106:107], v[106:107]
	v_mul_f32_e32 v114, v110, v110
	v_pk_mov_b32 v[104:105], v[104:105], v[124:125] op_sel:[1,0]
	v_pk_mov_b32 v[106:107], v[106:107], v[126:127] op_sel:[1,0]
	v_mov_b32_e32 v109, v115
	v_pk_fma_f32 v[114:115], v[110:111], v[110:111], v[114:115] op_sel_hi:[1,1,0]
	v_pk_add_f32 v[104:105], v[104:105], v[106:107]
	v_mov_b32_e32 v106, v110
	v_mov_b32_e32 v107, v152
	v_pk_mov_b32 v[110:111], v[110:111], v[154:155] op_sel:[1,0]
	v_mul_f32_e32 v117, v116, v116
	v_mul_f32_e32 v119, v118, v118
	v_mul_f32_e32 v101, v100, v100
	v_mul_f32_e32 v103, v102, v102
	v_pk_add_f32 v[108:109], v[156:157], v[108:109]
	v_mov_b32_e32 v114, v133
	v_pk_add_f32 v[106:107], v[106:107], v[110:111]
	v_mul_f32_e32 v121, v120, v120
	v_mul_f32_e32 v123, v122, v122
	v_mul_f32_e32 v97, v96, v96
	v_mul_f32_e32 v99, v98, v98
	v_pk_add_f32 v[108:109], v[108:109], v[114:115]
	v_pk_add_f32 v[104:105], v[104:105], v[106:107]
	v_pk_add_f32 v[106:107], v[116:117], v[118:119]
	v_pk_add_f32 v[100:101], v[100:101], v[102:103]
	v_pk_add_f32 v[104:105], v[104:105], v[108:109]
	v_pk_add_f32 v[100:101], v[106:107], v[100:101]
	v_pk_add_f32 v[102:103], v[120:121], v[122:123]
	v_pk_add_f32 v[96:97], v[96:97], v[98:99]
	v_pk_add_f32 v[100:101], v[100:101], v[104:105]
	v_pk_add_f32 v[96:97], v[102:103], v[96:97]
	s_nop 0
	v_pk_add_f32 v[96:97], v[96:97], v[100:101]
	ds_bpermute_b32 v98, v164, v96
	ds_bpermute_b32 v99, v164, v97
	s_waitcnt lgkmcnt(0)
	v_pk_add_f32 v[96:97], v[96:97], v[98:99]
	ds_bpermute_b32 v98, v165, v96
	ds_bpermute_b32 v99, v165, v97
	s_and_saveexec_b64 s[30:31], s[2:3]
	s_cbranch_execz .LBB0_241
	s_lshl_b32 s25, s14, 2
	s_add_i32 s25, s25, -16
	v_mov_b32_e32 v132, s25
	v_lshl_add_u64 v[100:101], v[112:113], 4, v[132:133]
	v_or_b32_e32 v100, s59, v100
	v_lshl_add_u64 v[100:101], v[100:101], 3, s[18:19]
	s_waitcnt lgkmcnt(0)
	v_pk_add_f32 v[96:97], v[96:97], v[98:99]
	global_store_dwordx2 v[100:101], v[96:97], off

.LBB0_242:
	v_add_f32_e32 v96, v186, v187
	v_fmamk_f32 v96, v96, 0x3a800000, v175
	v_rsq_f32_e32 v104, v96
	v_add_u32_e32 v96, s9, v169
	v_ashrrev_i32_e32 v97, 31, v96
	s_waitcnt lgkmcnt(0)
	v_lshlrev_b64 v[98:99], 11, v[96:97]
	v_pk_mul_f32 v[94:95], v[94:95], v[104:105] op_sel_hi:[1,0]
	v_pk_mul_f32 v[92:93], v[92:93], v[104:105] op_sel_hi:[1,0]
	v_mul_f32_e32 v100, 0x3d372713, v94
	v_mul_f32_e32 v100, v94, v100
	v_fma_f32 v100, v94, v100, v94
	v_lshl_add_u64 v[108:109], v[146:147], 0, v[98:99]
	v_mul_f32_e32 v99, 0x3d372713, v93
	v_mul_f32_e32 v100, 0x3f4c422a, v100
	v_mul_f32_e32 v99, v93, v99
	v_mul_f32_e32 v100, 0xc038aa3b, v100
	v_pk_mul_f32 v[110:111], v[88:89], v[104:105] op_sel_hi:[1,0]
	v_fma_f32 v99, v93, v99, v93
	v_exp_f32_e32 v101, v100
	v_mul_f32_e32 v100, 0x3d372713, v95
	v_mul_f32_e32 v88, 0x3d372713, v110
	v_mul_f32_e32 v99, 0x3f4c422a, v99
	v_mul_f32_e32 v100, v95, v100
	v_mul_f32_e32 v88, v110, v88
	v_mul_f32_e32 v89, 0x3d372713, v111
	v_mul_f32_e32 v99, 0xc038aa3b, v99
	v_fma_f32 v100, v95, v100, v95
	v_fma_f32 v88, v110, v88, v110
	v_mul_f32_e32 v89, v111, v89
	v_exp_f32_e32 v99, v99
	v_mul_f32_e32 v100, 0x3f4c422a, v100
	v_mul_f32_e32 v88, 0x3f4c422a, v88
	v_fma_f32 v89, v111, v89, v111
	v_mul_f32_e32 v100, 0xc038aa3b, v100
	v_mul_f32_e32 v88, 0xc038aa3b, v88
	v_mul_f32_e32 v89, 0x3f4c422a, v89
	v_exp_f32_e32 v103, v100
	v_exp_f32_e32 v88, v88
	v_mul_f32_e32 v89, 0xc038aa3b, v89
	v_exp_f32_e32 v89, v89
	v_add_f32_e32 v99, 1.0, v99
	v_rcp_f32_e32 v100, v99
	v_add_f32_e32 v99, 1.0, v101
	v_rcp_f32_e32 v102, v99
	v_add_f32_e32 v99, 1.0, v103
	v_add_f32_e32 v88, 1.0, v88
	v_rcp_f32_e32 v106, v99
	v_rcp_f32_e32 v99, v88
	v_add_f32_e32 v88, 1.0, v89
	v_rcp_f32_e32 v103, v88
	v_mul_f32_e32 v98, 0x3d372713, v92
	v_mul_f32_e32 v98, v92, v98
	v_pk_mul_f32 v[112:113], v[90:91], v[104:105] op_sel_hi:[1,0]
	v_mov_b32_e32 v89, v110
	v_pk_mov_b32 v[90:91], v[92:93], v[110:111] op_sel:[1,0]
	v_mov_b32_e32 v101, v99
	v_mov_b32_e32 v110, v94
	v_fma_f32 v98, v92, v98, v92
	v_mov_b32_e32 v88, v92
	v_pk_mul_f32 v[92:93], v[90:91], v[100:101]
	v_pk_mul_f32 v[90:91], v[110:111], v[102:103]
	v_mov_b32_e32 v110, v95
	v_mul_f32_e32 v94, 0x3d372713, v112
	v_mul_f32_e32 v95, 0x3d372713, v113
	v_mul_f32_e32 v94, v112, v94
	v_mul_f32_e32 v95, v113, v95
	v_mul_f32_e32 v98, 0x3f4c422a, v98
	v_fma_f32 v94, v112, v94, v112
	v_fma_f32 v95, v113, v95, v113
	v_mul_f32_e32 v98, 0xc038aa3b, v98
	v_mul_f32_e32 v94, 0x3f4c422a, v94
	v_mul_f32_e32 v95, 0x3f4c422a, v95
	v_exp_f32_e32 v98, v98
	v_mul_f32_e32 v94, 0xc038aa3b, v94
	v_mul_f32_e32 v95, 0xc038aa3b, v95
	v_exp_f32_e32 v94, v94
	v_exp_f32_e32 v95, v95
	v_add_f32_e32 v98, 1.0, v98
	v_rcp_f32_e32 v98, v98
	v_add_f32_e32 v94, 1.0, v94
	v_add_f32_e32 v95, 1.0, v95
	v_rcp_f32_e32 v94, v94
	v_rcp_f32_e32 v95, v95
	v_mov_b32_e32 v107, v103
	v_pk_mul_f32 v[88:89], v[88:89], v[98:99]
	v_pk_mul_f32 v[98:99], v[110:111], v[106:107]
	v_cvt_pk_bf16_f32 v232, v88, v92
	v_pk_mul_f32 v[86:87], v[86:87], v[104:105] op_sel_hi:[1,0]
	v_cvt_pk_bf16_f32 v233, v90, v98
	v_pk_mul_f32 v[94:95], v[112:113], v[94:95]
	v_cvt_pk_bf16_f32 v234, v89, v91
	v_pk_mul_f32 v[84:85], v[84:85], v[104:105] op_sel_hi:[1,0]
	v_cvt_pk_bf16_f32 v235, v94, v95
	v_mul_f32_e32 v102, 0x3d372713, v86
	s_nop 1
	v_permlane16_swap_b32_e32 v232, v234
	v_permlane16_swap_b32_e32 v233, v235
	v_lshl_add_u64 v[236:237], v[108:109], 0, v[238:239]
	global_store_dwordx4 v[236:237], v[232:235], off
	s_nop 1
	v_mul_f32_e32 v100, 0x3d372713, v84
	v_mul_f32_e32 v101, 0x3d372713, v85
	v_mul_f32_e32 v102, v86, v102
	v_mul_f32_e32 v103, 0x3d372713, v87
	v_mul_f32_e32 v100, v84, v100
	v_mul_f32_e32 v101, v85, v101
	v_fma_f32 v102, v86, v102, v86
	v_mul_f32_e32 v103, v87, v103
	v_fma_f32 v100, v84, v100, v84
	v_fma_f32 v101, v85, v101, v85
	v_mul_f32_e32 v102, 0x3f4c422a, v102
	v_fma_f32 v103, v87, v103, v87
	v_mul_f32_e32 v100, 0x3f4c422a, v100
	v_mul_f32_e32 v101, 0x3f4c422a, v101
	v_mul_f32_e32 v102, 0xc038aa3b, v102
	v_mul_f32_e32 v103, 0x3f4c422a, v103
	v_mul_f32_e32 v100, 0xc038aa3b, v100
	v_mul_f32_e32 v101, 0xc038aa3b, v101
	v_exp_f32_e32 v102, v102
	v_mul_f32_e32 v103, 0xc038aa3b, v103
	v_exp_f32_e32 v100, v100
	v_exp_f32_e32 v101, v101
	v_exp_f32_e32 v103, v103
	v_add_f32_e32 v102, 1.0, v102
	v_add_f32_e32 v100, 1.0, v100
	v_add_f32_e32 v101, 1.0, v101
	v_rcp_f32_e32 v105, v102
	v_add_f32_e32 v102, 1.0, v103
	v_rcp_f32_e32 v100, v100
	v_rcp_f32_e32 v101, v101
	v_rcp_f32_e32 v103, v102
	v_pk_mul_f32 v[80:81], v[80:81], v[104:105] op_sel_hi:[1,0]
	v_pk_mul_f32 v[82:83], v[82:83], v[104:105] op_sel_hi:[1,0]
	v_mul_f32_e32 v100, v84, v100
	v_mul_f32_e32 v102, v85, v101
	v_mul_f32_e32 v84, v86, v105
	v_mul_f32_e32 v86, v87, v103
	v_mul_f32_e32 v85, 0x3d372713, v80
	v_mul_f32_e32 v87, 0x3d372713, v81
	v_mul_f32_e32 v101, 0x3d372713, v82
	v_mul_f32_e32 v103, 0x3d372713, v83
	v_mul_f32_e32 v85, v80, v85
	v_mul_f32_e32 v87, v81, v87
	v_mul_f32_e32 v101, v82, v101
	v_mul_f32_e32 v103, v83, v103
	v_fma_f32 v85, v80, v85, v80
	v_fma_f32 v87, v81, v87, v81
	v_fma_f32 v101, v82, v101, v82
	v_fma_f32 v103, v83, v103, v83
	v_mul_f32_e32 v85, 0x3f4c422a, v85
	v_mul_f32_e32 v87, 0x3f4c422a, v87
	v_mul_f32_e32 v101, 0x3f4c422a, v101
	v_mul_f32_e32 v103, 0x3f4c422a, v103
	v_mul_f32_e32 v85, 0xc038aa3b, v85
	v_mul_f32_e32 v87, 0xc038aa3b, v87
	v_mul_f32_e32 v101, 0xc038aa3b, v101
	v_mul_f32_e32 v103, 0xc038aa3b, v103
	v_exp_f32_e32 v85, v85
	v_exp_f32_e32 v87, v87
	v_exp_f32_e32 v101, v101
	v_exp_f32_e32 v103, v103
	v_add_f32_e32 v85, 1.0, v85
	v_add_f32_e32 v87, 1.0, v87
	v_add_f32_e32 v101, 1.0, v101
	v_add_f32_e32 v103, 1.0, v103
	v_rcp_f32_e32 v85, v85
	v_rcp_f32_e32 v87, v87
	v_rcp_f32_e32 v101, v101
	v_rcp_f32_e32 v103, v103
	v_cvt_pk_bf16_f32 v232, v100, v102
	v_cvt_pk_bf16_f32 v233, v84, v86
	v_mul_f32_e32 v104, v80, v85
	v_mul_f32_e32 v106, v81, v87
	v_mul_f32_e32 v80, v82, v101
	v_mul_f32_e32 v82, v83, v103
	s_and_b64 vcc, exec, s[6:7]
	v_cvt_pk_bf16_f32 v234, v104, v106
	v_cvt_pk_bf16_f32 v235, v80, v82
	s_nop 1
	v_permlane16_swap_b32_e32 v232, v234
	v_permlane16_swap_b32_e32 v233, v235
	v_lshl_add_u64 v[236:237], v[108:109], 0, v[238:239]
	global_store_dwordx4 v[236:237], v[232:235], off offset:256
	s_nop 1
	s_cbranch_vccnz .LBB0_246
	v_pk_mul_f32 v[110:111], v[92:93], v[92:93]
	v_pk_add_f32 v[116:117], v[88:89], v[92:93]
	v_pk_mul_f32 v[92:93], v[88:89], v[92:93]
	v_pk_mul_f32 v[108:109], v[88:89], v[88:89]
	v_pk_mul_f32 v[114:115], v[98:99], v[98:99]
	v_mov_b32_e32 v117, v93
	v_pk_add_f32 v[92:93], v[90:91], v[98:99]
	v_pk_mul_f32 v[98:99], v[90:91], v[98:99]
	v_pk_mul_f32 v[112:113], v[90:91], v[90:91]
	v_mul_f32_e32 v98, v94, v94
	v_pk_mov_b32 v[88:89], v[88:89], v[108:109] op_sel:[1,0]
	v_pk_mov_b32 v[90:91], v[90:91], v[110:111] op_sel:[1,0]
	v_mov_b32_e32 v93, v99
	v_pk_fma_f32 v[98:99], v[94:95], v[94:95], v[98:99] op_sel_hi:[1,1,0]
	v_pk_add_f32 v[88:89], v[88:89], v[90:91]
	v_mov_b32_e32 v90, v94
	v_mov_b32_e32 v91, v112
	v_pk_mov_b32 v[94:95], v[94:95], v[114:115] op_sel:[1,0]
	v_mul_f32_e32 v101, v100, v100
	v_mul_f32_e32 v103, v102, v102
	v_mul_f32_e32 v85, v84, v84
	v_mul_f32_e32 v87, v86, v86
	v_pk_add_f32 v[92:93], v[116:117], v[92:93]
	v_mov_b32_e32 v98, v133
	v_pk_add_f32 v[90:91], v[90:91], v[94:95]
	v_mul_f32_e32 v105, v104, v104
	v_mul_f32_e32 v107, v106, v106
	v_mul_f32_e32 v81, v80, v80
	v_mul_f32_e32 v83, v82, v82
	v_pk_add_f32 v[92:93], v[92:93], v[98:99]
	v_pk_add_f32 v[88:89], v[88:89], v[90:91]
	v_pk_add_f32 v[90:91], v[100:101], v[102:103]
	v_pk_add_f32 v[84:85], v[84:85], v[86:87]
	v_pk_add_f32 v[88:89], v[88:89], v[92:93]
	v_pk_add_f32 v[84:85], v[90:91], v[84:85]
	v_pk_add_f32 v[86:87], v[104:105], v[106:107]
	v_pk_add_f32 v[80:81], v[80:81], v[82:83]
	v_pk_add_f32 v[84:85], v[84:85], v[88:89]
	v_pk_add_f32 v[80:81], v[86:87], v[80:81]
	s_nop 0
	v_pk_add_f32 v[80:81], v[80:81], v[84:85]
	ds_bpermute_b32 v82, v164, v80
	ds_bpermute_b32 v83, v164, v81
	s_waitcnt lgkmcnt(0)
	v_pk_add_f32 v[80:81], v[80:81], v[82:83]
	ds_bpermute_b32 v82, v165, v80
	ds_bpermute_b32 v83, v165, v81
	s_and_saveexec_b64 s[30:31], s[2:3]
	s_cbranch_execz .LBB0_245
	s_lshl_b32 s25, s14, 2
	s_add_i32 s25, s25, -16
	v_mov_b32_e32 v132, s25
	v_lshl_add_u64 v[84:85], v[96:97], 4, v[132:133]
	v_or_b32_e32 v84, s59, v84
	v_lshl_add_u64 v[84:85], v[84:85], 3, s[18:19]
	s_waitcnt lgkmcnt(0)
	v_pk_add_f32 v[80:81], v[80:81], v[82:83]
	global_store_dwordx2 v[84:85], v[80:81], off

.LBB0_246:
	v_add_f32_e32 v80, v184, v185
	v_fmamk_f32 v80, v80, 0x3a800000, v175
	v_rsq_f32_e32 v88, v80
	v_add_u32_e32 v80, s9, v170
	v_ashrrev_i32_e32 v81, 31, v80
	s_waitcnt lgkmcnt(0)
	v_lshlrev_b64 v[82:83], 11, v[80:81]
	v_pk_mul_f32 v[78:79], v[78:79], v[88:89] op_sel_hi:[1,0]
	v_pk_mul_f32 v[76:77], v[76:77], v[88:89] op_sel_hi:[1,0]
	v_mul_f32_e32 v84, 0x3d372713, v78
	v_mul_f32_e32 v84, v78, v84
	v_fma_f32 v84, v78, v84, v78
	v_lshl_add_u64 v[92:93], v[146:147], 0, v[82:83]
	v_mul_f32_e32 v83, 0x3d372713, v77
	v_mul_f32_e32 v84, 0x3f4c422a, v84
	v_mul_f32_e32 v83, v77, v83
	v_mul_f32_e32 v84, 0xc038aa3b, v84
	v_pk_mul_f32 v[94:95], v[72:73], v[88:89] op_sel_hi:[1,0]
	v_fma_f32 v83, v77, v83, v77
	v_exp_f32_e32 v85, v84
	v_mul_f32_e32 v84, 0x3d372713, v79
	v_mul_f32_e32 v72, 0x3d372713, v94
	v_mul_f32_e32 v83, 0x3f4c422a, v83
	v_mul_f32_e32 v84, v79, v84
	v_mul_f32_e32 v72, v94, v72
	v_mul_f32_e32 v73, 0x3d372713, v95
	v_mul_f32_e32 v83, 0xc038aa3b, v83
	v_fma_f32 v84, v79, v84, v79
	v_fma_f32 v72, v94, v72, v94
	v_mul_f32_e32 v73, v95, v73
	v_exp_f32_e32 v83, v83
	v_mul_f32_e32 v84, 0x3f4c422a, v84
	v_mul_f32_e32 v72, 0x3f4c422a, v72
	v_fma_f32 v73, v95, v73, v95
	v_mul_f32_e32 v84, 0xc038aa3b, v84
	v_mul_f32_e32 v72, 0xc038aa3b, v72
	v_mul_f32_e32 v73, 0x3f4c422a, v73
	v_exp_f32_e32 v87, v84
	v_exp_f32_e32 v72, v72
	v_mul_f32_e32 v73, 0xc038aa3b, v73
	v_exp_f32_e32 v73, v73
	v_add_f32_e32 v83, 1.0, v83
	v_rcp_f32_e32 v84, v83
	v_add_f32_e32 v83, 1.0, v85
	v_rcp_f32_e32 v86, v83
	v_add_f32_e32 v83, 1.0, v87
	v_add_f32_e32 v72, 1.0, v72
	v_rcp_f32_e32 v90, v83
	v_rcp_f32_e32 v83, v72
	v_add_f32_e32 v72, 1.0, v73
	v_rcp_f32_e32 v87, v72
	v_mul_f32_e32 v82, 0x3d372713, v76
	v_mul_f32_e32 v82, v76, v82
	v_pk_mul_f32 v[96:97], v[74:75], v[88:89] op_sel_hi:[1,0]
	v_mov_b32_e32 v73, v94
	v_pk_mov_b32 v[74:75], v[76:77], v[94:95] op_sel:[1,0]
	v_mov_b32_e32 v85, v83
	v_mov_b32_e32 v94, v78
	v_fma_f32 v82, v76, v82, v76
	v_mov_b32_e32 v72, v76
	v_pk_mul_f32 v[76:77], v[74:75], v[84:85]
	v_pk_mul_f32 v[74:75], v[94:95], v[86:87]
	v_mov_b32_e32 v94, v79
	v_mul_f32_e32 v78, 0x3d372713, v96
	v_mul_f32_e32 v79, 0x3d372713, v97
	v_mul_f32_e32 v78, v96, v78
	v_mul_f32_e32 v79, v97, v79
	v_mul_f32_e32 v82, 0x3f4c422a, v82
	v_fma_f32 v78, v96, v78, v96
	v_fma_f32 v79, v97, v79, v97
	v_mul_f32_e32 v82, 0xc038aa3b, v82
	v_mul_f32_e32 v78, 0x3f4c422a, v78
	v_mul_f32_e32 v79, 0x3f4c422a, v79
	v_exp_f32_e32 v82, v82
	v_mul_f32_e32 v78, 0xc038aa3b, v78
	v_mul_f32_e32 v79, 0xc038aa3b, v79
	v_exp_f32_e32 v78, v78
	v_exp_f32_e32 v79, v79
	v_add_f32_e32 v82, 1.0, v82
	v_rcp_f32_e32 v82, v82
	v_add_f32_e32 v78, 1.0, v78
	v_add_f32_e32 v79, 1.0, v79
	v_rcp_f32_e32 v78, v78
	v_rcp_f32_e32 v79, v79
	v_mov_b32_e32 v91, v87
	v_pk_mul_f32 v[72:73], v[72:73], v[82:83]
	v_pk_mul_f32 v[82:83], v[94:95], v[90:91]
	v_cvt_pk_bf16_f32 v232, v72, v76
	v_pk_mul_f32 v[70:71], v[70:71], v[88:89] op_sel_hi:[1,0]
	v_cvt_pk_bf16_f32 v233, v74, v82
	v_pk_mul_f32 v[78:79], v[96:97], v[78:79]
	v_cvt_pk_bf16_f32 v234, v73, v75
	v_pk_mul_f32 v[68:69], v[68:69], v[88:89] op_sel_hi:[1,0]
	v_cvt_pk_bf16_f32 v235, v78, v79
	v_mul_f32_e32 v86, 0x3d372713, v70
	s_nop 1
	v_permlane16_swap_b32_e32 v232, v234
	v_permlane16_swap_b32_e32 v233, v235
	v_lshl_add_u64 v[236:237], v[92:93], 0, v[238:239]
	global_store_dwordx4 v[236:237], v[232:235], off
	s_nop 1
	v_mul_f32_e32 v84, 0x3d372713, v68
	v_mul_f32_e32 v85, 0x3d372713, v69
	v_mul_f32_e32 v86, v70, v86
	v_mul_f32_e32 v87, 0x3d372713, v71
	v_mul_f32_e32 v84, v68, v84
	v_mul_f32_e32 v85, v69, v85
	v_fma_f32 v86, v70, v86, v70
	v_mul_f32_e32 v87, v71, v87
	v_fma_f32 v84, v68, v84, v68
	v_fma_f32 v85, v69, v85, v69
	v_mul_f32_e32 v86, 0x3f4c422a, v86
	v_fma_f32 v87, v71, v87, v71
	v_mul_f32_e32 v84, 0x3f4c422a, v84
	v_mul_f32_e32 v85, 0x3f4c422a, v85
	v_mul_f32_e32 v86, 0xc038aa3b, v86
	v_mul_f32_e32 v87, 0x3f4c422a, v87
	v_mul_f32_e32 v84, 0xc038aa3b, v84
	v_mul_f32_e32 v85, 0xc038aa3b, v85
	v_exp_f32_e32 v86, v86
	v_mul_f32_e32 v87, 0xc038aa3b, v87
	v_exp_f32_e32 v84, v84
	v_exp_f32_e32 v85, v85
	v_exp_f32_e32 v87, v87
	v_add_f32_e32 v86, 1.0, v86
	v_add_f32_e32 v84, 1.0, v84
	v_add_f32_e32 v85, 1.0, v85
	v_rcp_f32_e32 v89, v86
	v_add_f32_e32 v86, 1.0, v87
	v_rcp_f32_e32 v84, v84
	v_rcp_f32_e32 v85, v85
	v_rcp_f32_e32 v87, v86
	v_pk_mul_f32 v[64:65], v[64:65], v[88:89] op_sel_hi:[1,0]
	v_pk_mul_f32 v[66:67], v[66:67], v[88:89] op_sel_hi:[1,0]
	v_mul_f32_e32 v84, v68, v84
	v_mul_f32_e32 v86, v69, v85
	v_mul_f32_e32 v68, v70, v89
	v_mul_f32_e32 v70, v71, v87
	v_mul_f32_e32 v69, 0x3d372713, v64
	v_mul_f32_e32 v71, 0x3d372713, v65
	v_mul_f32_e32 v85, 0x3d372713, v66
	v_mul_f32_e32 v87, 0x3d372713, v67
	v_mul_f32_e32 v69, v64, v69
	v_mul_f32_e32 v71, v65, v71
	v_mul_f32_e32 v85, v66, v85
	v_mul_f32_e32 v87, v67, v87
	v_fma_f32 v69, v64, v69, v64
	v_fma_f32 v71, v65, v71, v65
	v_fma_f32 v85, v66, v85, v66
	v_fma_f32 v87, v67, v87, v67
	v_mul_f32_e32 v69, 0x3f4c422a, v69
	v_mul_f32_e32 v71, 0x3f4c422a, v71
	v_mul_f32_e32 v85, 0x3f4c422a, v85
	v_mul_f32_e32 v87, 0x3f4c422a, v87
	v_mul_f32_e32 v69, 0xc038aa3b, v69
	v_mul_f32_e32 v71, 0xc038aa3b, v71
	v_mul_f32_e32 v85, 0xc038aa3b, v85
	v_mul_f32_e32 v87, 0xc038aa3b, v87
	v_exp_f32_e32 v69, v69
	v_exp_f32_e32 v71, v71
	v_exp_f32_e32 v85, v85
	v_exp_f32_e32 v87, v87
	v_add_f32_e32 v69, 1.0, v69
	v_add_f32_e32 v71, 1.0, v71
	v_add_f32_e32 v85, 1.0, v85
	v_add_f32_e32 v87, 1.0, v87
	v_rcp_f32_e32 v69, v69
	v_rcp_f32_e32 v71, v71
	v_rcp_f32_e32 v85, v85
	v_rcp_f32_e32 v87, v87
	v_cvt_pk_bf16_f32 v232, v84, v86
	v_cvt_pk_bf16_f32 v233, v68, v70
	v_mul_f32_e32 v88, v64, v69
	v_mul_f32_e32 v90, v65, v71
	v_mul_f32_e32 v64, v66, v85
	v_mul_f32_e32 v66, v67, v87
	s_and_b64 vcc, exec, s[6:7]
	v_cvt_pk_bf16_f32 v234, v88, v90
	v_cvt_pk_bf16_f32 v235, v64, v66
	s_nop 1
	v_permlane16_swap_b32_e32 v232, v234
	v_permlane16_swap_b32_e32 v233, v235
	v_lshl_add_u64 v[236:237], v[92:93], 0, v[238:239]
	global_store_dwordx4 v[236:237], v[232:235], off offset:256
	s_nop 1
	s_cbranch_vccnz .LBB0_250
	v_pk_mul_f32 v[94:95], v[76:77], v[76:77]
	v_pk_add_f32 v[100:101], v[72:73], v[76:77]
	v_pk_mul_f32 v[76:77], v[72:73], v[76:77]
	v_pk_mul_f32 v[92:93], v[72:73], v[72:73]
	v_pk_mul_f32 v[98:99], v[82:83], v[82:83]
	v_mov_b32_e32 v101, v77
	v_pk_add_f32 v[76:77], v[74:75], v[82:83]
	v_pk_mul_f32 v[82:83], v[74:75], v[82:83]
	v_pk_mul_f32 v[96:97], v[74:75], v[74:75]
	v_mul_f32_e32 v82, v78, v78
	v_pk_mov_b32 v[72:73], v[72:73], v[92:93] op_sel:[1,0]
	v_pk_mov_b32 v[74:75], v[74:75], v[94:95] op_sel:[1,0]
	v_mov_b32_e32 v77, v83
	v_pk_fma_f32 v[82:83], v[78:79], v[78:79], v[82:83] op_sel_hi:[1,1,0]
	v_pk_add_f32 v[72:73], v[72:73], v[74:75]
	v_mov_b32_e32 v74, v78
	v_mov_b32_e32 v75, v96
	v_pk_mov_b32 v[78:79], v[78:79], v[98:99] op_sel:[1,0]
	v_mul_f32_e32 v85, v84, v84
	v_mul_f32_e32 v87, v86, v86
	v_mul_f32_e32 v69, v68, v68
	v_mul_f32_e32 v71, v70, v70
	v_pk_add_f32 v[76:77], v[100:101], v[76:77]
	v_mov_b32_e32 v82, v133
	v_pk_add_f32 v[74:75], v[74:75], v[78:79]
	v_mul_f32_e32 v89, v88, v88
	v_mul_f32_e32 v91, v90, v90
	v_mul_f32_e32 v65, v64, v64
	v_mul_f32_e32 v67, v66, v66
	v_pk_add_f32 v[76:77], v[76:77], v[82:83]
	v_pk_add_f32 v[72:73], v[72:73], v[74:75]
	v_pk_add_f32 v[74:75], v[84:85], v[86:87]
	v_pk_add_f32 v[68:69], v[68:69], v[70:71]
	v_pk_add_f32 v[72:73], v[72:73], v[76:77]
	v_pk_add_f32 v[68:69], v[74:75], v[68:69]
	v_pk_add_f32 v[70:71], v[88:89], v[90:91]
	v_pk_add_f32 v[64:65], v[64:65], v[66:67]
	v_pk_add_f32 v[68:69], v[68:69], v[72:73]
	v_pk_add_f32 v[64:65], v[70:71], v[64:65]
	s_nop 0
	v_pk_add_f32 v[64:65], v[64:65], v[68:69]
	ds_bpermute_b32 v66, v164, v64
	ds_bpermute_b32 v67, v164, v65
	s_waitcnt lgkmcnt(0)
	v_pk_add_f32 v[64:65], v[64:65], v[66:67]
	ds_bpermute_b32 v66, v165, v64
	ds_bpermute_b32 v67, v165, v65
	s_and_saveexec_b64 s[30:31], s[2:3]
	s_cbranch_execz .LBB0_249
	s_lshl_b32 s9, s14, 2
	s_add_i32 s9, s9, -16
	v_mov_b32_e32 v132, s9
	v_lshl_add_u64 v[68:69], v[80:81], 4, v[132:133]
	v_or_b32_e32 v68, s59, v68
	v_lshl_add_u64 v[68:69], v[68:69], 3, s[18:19]
	s_waitcnt lgkmcnt(0)
	v_pk_add_f32 v[64:65], v[64:65], v[66:67]
	global_store_dwordx2 v[68:69], v[64:65], off

.LBB0_250:
	v_add_f32_e32 v64, v182, v183
	v_fmamk_f32 v64, v64, 0x3a800000, v175
	v_rsq_f32_e32 v70, v64
	v_lshlrev_b64 v[64:65], 11, v[150:151]
	v_lshl_add_u64 v[74:75], v[146:147], 0, v[64:65]
	s_and_b64 vcc, exec, s[6:7]
	v_pk_mul_f32 v[62:63], v[62:63], v[70:71] op_sel_hi:[1,0]
	v_pk_mul_f32 v[60:61], v[60:61], v[70:71] op_sel_hi:[1,0]
	s_waitcnt lgkmcnt(1)
	v_mul_f32_e32 v66, 0x3d372713, v62
	v_mul_f32_e32 v66, v62, v66
	v_fma_f32 v66, v62, v66, v62
	v_mul_f32_e32 v65, 0x3d372713, v61
	v_mul_f32_e32 v66, 0x3f4c422a, v66
	v_mul_f32_e32 v65, v61, v65
	v_mul_f32_e32 v66, 0xc038aa3b, v66
	v_pk_mul_f32 v[76:77], v[56:57], v[70:71] op_sel_hi:[1,0]
	v_fma_f32 v65, v61, v65, v61
	s_waitcnt lgkmcnt(0)
	v_exp_f32_e32 v67, v66
	v_mul_f32_e32 v66, 0x3d372713, v63
	v_mul_f32_e32 v56, 0x3d372713, v76
	v_mul_f32_e32 v65, 0x3f4c422a, v65
	v_mul_f32_e32 v66, v63, v66
	v_mul_f32_e32 v56, v76, v56
	v_mul_f32_e32 v57, 0x3d372713, v77
	v_mul_f32_e32 v65, 0xc038aa3b, v65
	v_fma_f32 v66, v63, v66, v63
	v_fma_f32 v56, v76, v56, v76
	v_mul_f32_e32 v57, v77, v57
	v_exp_f32_e32 v65, v65
	v_mul_f32_e32 v66, 0x3f4c422a, v66
	v_mul_f32_e32 v56, 0x3f4c422a, v56
	v_fma_f32 v57, v77, v57, v77
	v_mul_f32_e32 v66, 0xc038aa3b, v66
	v_mul_f32_e32 v56, 0xc038aa3b, v56
	v_mul_f32_e32 v57, 0x3f4c422a, v57
	v_exp_f32_e32 v69, v66
	v_exp_f32_e32 v56, v56
	v_mul_f32_e32 v57, 0xc038aa3b, v57
	v_exp_f32_e32 v57, v57
	v_add_f32_e32 v65, 1.0, v65
	v_rcp_f32_e32 v66, v65
	v_add_f32_e32 v65, 1.0, v67
	v_rcp_f32_e32 v68, v65
	v_add_f32_e32 v65, 1.0, v69
	v_add_f32_e32 v56, 1.0, v56
	v_rcp_f32_e32 v72, v65
	v_rcp_f32_e32 v65, v56
	v_add_f32_e32 v56, 1.0, v57
	v_rcp_f32_e32 v69, v56
	v_mul_f32_e32 v64, 0x3d372713, v60
	v_mul_f32_e32 v64, v60, v64
	v_pk_mul_f32 v[78:79], v[58:59], v[70:71] op_sel_hi:[1,0]
	v_mov_b32_e32 v57, v76
	v_pk_mov_b32 v[58:59], v[60:61], v[76:77] op_sel:[1,0]
	v_mov_b32_e32 v67, v65
	v_mov_b32_e32 v76, v62
	v_fma_f32 v64, v60, v64, v60
	v_mov_b32_e32 v56, v60
	v_pk_mul_f32 v[60:61], v[58:59], v[66:67]
	v_pk_mul_f32 v[58:59], v[76:77], v[68:69]
	v_mov_b32_e32 v76, v63
	v_mul_f32_e32 v62, 0x3d372713, v78
	v_mul_f32_e32 v63, 0x3d372713, v79
	v_mul_f32_e32 v62, v78, v62
	v_mul_f32_e32 v63, v79, v63
	v_mul_f32_e32 v64, 0x3f4c422a, v64
	v_fma_f32 v62, v78, v62, v78
	v_fma_f32 v63, v79, v63, v79
	v_mul_f32_e32 v64, 0xc038aa3b, v64
	v_mul_f32_e32 v62, 0x3f4c422a, v62
	v_mul_f32_e32 v63, 0x3f4c422a, v63
	v_exp_f32_e32 v64, v64
	v_mul_f32_e32 v62, 0xc038aa3b, v62
	v_mul_f32_e32 v63, 0xc038aa3b, v63
	v_exp_f32_e32 v62, v62
	v_exp_f32_e32 v63, v63
	v_add_f32_e32 v64, 1.0, v64
	v_rcp_f32_e32 v64, v64
	v_add_f32_e32 v62, 1.0, v62
	v_add_f32_e32 v63, 1.0, v63
	v_rcp_f32_e32 v62, v62
	v_rcp_f32_e32 v63, v63
	v_mov_b32_e32 v73, v69
	v_pk_mul_f32 v[56:57], v[56:57], v[64:65]
	v_pk_mul_f32 v[64:65], v[76:77], v[72:73]
	v_cvt_pk_bf16_f32 v232, v56, v60
	v_pk_mul_f32 v[54:55], v[54:55], v[70:71] op_sel_hi:[1,0]
	v_cvt_pk_bf16_f32 v233, v58, v64
	v_pk_mul_f32 v[62:63], v[78:79], v[62:63]
	v_cvt_pk_bf16_f32 v234, v57, v59
	v_pk_mul_f32 v[52:53], v[52:53], v[70:71] op_sel_hi:[1,0]
	v_cvt_pk_bf16_f32 v235, v62, v63
	v_mul_f32_e32 v68, 0x3d372713, v54
	s_nop 1
	v_permlane16_swap_b32_e32 v232, v234
	v_permlane16_swap_b32_e32 v233, v235
	v_lshl_add_u64 v[236:237], v[74:75], 0, v[238:239]
	global_store_dwordx4 v[236:237], v[232:235], off
	s_nop 1
	v_mul_f32_e32 v66, 0x3d372713, v52
	v_mul_f32_e32 v67, 0x3d372713, v53
	v_mul_f32_e32 v68, v54, v68
	v_mul_f32_e32 v69, 0x3d372713, v55
	v_mul_f32_e32 v66, v52, v66
	v_mul_f32_e32 v67, v53, v67
	v_fma_f32 v68, v54, v68, v54
	v_mul_f32_e32 v69, v55, v69
	v_fma_f32 v66, v52, v66, v52
	v_fma_f32 v67, v53, v67, v53
	v_mul_f32_e32 v68, 0x3f4c422a, v68
	v_fma_f32 v69, v55, v69, v55
	v_mul_f32_e32 v66, 0x3f4c422a, v66
	v_mul_f32_e32 v67, 0x3f4c422a, v67
	v_mul_f32_e32 v68, 0xc038aa3b, v68
	v_mul_f32_e32 v69, 0x3f4c422a, v69
	v_mul_f32_e32 v66, 0xc038aa3b, v66
	v_mul_f32_e32 v67, 0xc038aa3b, v67
	v_exp_f32_e32 v68, v68
	v_mul_f32_e32 v69, 0xc038aa3b, v69
	v_exp_f32_e32 v66, v66
	v_exp_f32_e32 v67, v67
	v_exp_f32_e32 v69, v69
	v_add_f32_e32 v68, 1.0, v68
	v_add_f32_e32 v66, 1.0, v66
	v_add_f32_e32 v67, 1.0, v67
	v_rcp_f32_e32 v71, v68
	v_add_f32_e32 v68, 1.0, v69
	v_rcp_f32_e32 v66, v66
	v_rcp_f32_e32 v67, v67
	v_rcp_f32_e32 v69, v68
	v_pk_mul_f32 v[48:49], v[48:49], v[70:71] op_sel_hi:[1,0]
	v_pk_mul_f32 v[50:51], v[50:51], v[70:71] op_sel_hi:[1,0]
	v_mul_f32_e32 v66, v52, v66
	v_mul_f32_e32 v68, v53, v67
	v_mul_f32_e32 v52, v54, v71
	v_mul_f32_e32 v54, v55, v69
	v_mul_f32_e32 v53, 0x3d372713, v48
	v_mul_f32_e32 v55, 0x3d372713, v49
	v_mul_f32_e32 v67, 0x3d372713, v50
	v_mul_f32_e32 v69, 0x3d372713, v51
	v_mul_f32_e32 v53, v48, v53
	v_mul_f32_e32 v55, v49, v55
	v_mul_f32_e32 v67, v50, v67
	v_mul_f32_e32 v69, v51, v69
	v_fma_f32 v53, v48, v53, v48
	v_fma_f32 v55, v49, v55, v49
	v_fma_f32 v67, v50, v67, v50
	v_fma_f32 v69, v51, v69, v51
	v_mul_f32_e32 v53, 0x3f4c422a, v53
	v_mul_f32_e32 v55, 0x3f4c422a, v55
	v_mul_f32_e32 v67, 0x3f4c422a, v67
	v_mul_f32_e32 v69, 0x3f4c422a, v69
	v_mul_f32_e32 v53, 0xc038aa3b, v53
	v_mul_f32_e32 v55, 0xc038aa3b, v55
	v_mul_f32_e32 v67, 0xc038aa3b, v67
	v_mul_f32_e32 v69, 0xc038aa3b, v69
	v_exp_f32_e32 v53, v53
	v_exp_f32_e32 v55, v55
	v_exp_f32_e32 v67, v67
	v_exp_f32_e32 v69, v69
	v_add_f32_e32 v53, 1.0, v53
	v_add_f32_e32 v55, 1.0, v55
	v_add_f32_e32 v67, 1.0, v67
	v_add_f32_e32 v69, 1.0, v69
	v_rcp_f32_e32 v53, v53
	v_rcp_f32_e32 v55, v55
	v_rcp_f32_e32 v67, v67
	v_rcp_f32_e32 v69, v69
	v_cvt_pk_bf16_f32 v232, v66, v68
	v_cvt_pk_bf16_f32 v233, v52, v54
	v_mul_f32_e32 v70, v48, v53
	v_mul_f32_e32 v72, v49, v55
	v_mul_f32_e32 v48, v50, v67
	v_mul_f32_e32 v50, v51, v69
	v_cvt_pk_bf16_f32 v234, v70, v72
	v_cvt_pk_bf16_f32 v235, v48, v50
	s_nop 1
	v_permlane16_swap_b32_e32 v232, v234
	v_permlane16_swap_b32_e32 v233, v235
	v_lshl_add_u64 v[236:237], v[74:75], 0, v[238:239]
	global_store_dwordx4 v[236:237], v[232:235], off offset:256
	s_nop 1
	s_cbranch_vccnz .LBB0_254
	v_pk_mul_f32 v[76:77], v[60:61], v[60:61]
	v_pk_add_f32 v[82:83], v[56:57], v[60:61]
	v_pk_mul_f32 v[60:61], v[56:57], v[60:61]
	v_pk_mul_f32 v[74:75], v[56:57], v[56:57]
	v_pk_mul_f32 v[80:81], v[64:65], v[64:65]
	v_mov_b32_e32 v83, v61
	v_pk_add_f32 v[60:61], v[58:59], v[64:65]
	v_pk_mul_f32 v[64:65], v[58:59], v[64:65]
	v_pk_mul_f32 v[78:79], v[58:59], v[58:59]
	v_mul_f32_e32 v64, v62, v62
	v_pk_mov_b32 v[56:57], v[56:57], v[74:75] op_sel:[1,0]
	v_pk_mov_b32 v[58:59], v[58:59], v[76:77] op_sel:[1,0]
	v_mov_b32_e32 v61, v65
	v_pk_fma_f32 v[64:65], v[62:63], v[62:63], v[64:65] op_sel_hi:[1,1,0]
	v_pk_add_f32 v[56:57], v[56:57], v[58:59]
	v_mov_b32_e32 v58, v62
	v_mov_b32_e32 v59, v78
	v_pk_mov_b32 v[62:63], v[62:63], v[80:81] op_sel:[1,0]
	v_mul_f32_e32 v67, v66, v66
	v_mul_f32_e32 v69, v68, v68
	v_mul_f32_e32 v53, v52, v52
	v_mul_f32_e32 v55, v54, v54
	v_pk_add_f32 v[60:61], v[82:83], v[60:61]
	v_mov_b32_e32 v64, v133
	v_pk_add_f32 v[58:59], v[58:59], v[62:63]
	v_mul_f32_e32 v71, v70, v70
	v_mul_f32_e32 v73, v72, v72
	v_mul_f32_e32 v49, v48, v48
	v_mul_f32_e32 v51, v50, v50
	v_pk_add_f32 v[60:61], v[60:61], v[64:65]
	v_pk_add_f32 v[56:57], v[56:57], v[58:59]
	v_pk_add_f32 v[58:59], v[66:67], v[68:69]
	v_pk_add_f32 v[52:53], v[52:53], v[54:55]
	v_pk_add_f32 v[56:57], v[56:57], v[60:61]
	v_pk_add_f32 v[52:53], v[58:59], v[52:53]
	v_pk_add_f32 v[54:55], v[70:71], v[72:73]
	v_pk_add_f32 v[48:49], v[48:49], v[50:51]
	v_pk_add_f32 v[52:53], v[52:53], v[56:57]
	v_pk_add_f32 v[48:49], v[54:55], v[48:49]
	s_nop 0
	v_pk_add_f32 v[48:49], v[48:49], v[52:53]
	ds_bpermute_b32 v50, v164, v48
	ds_bpermute_b32 v51, v164, v49
	s_waitcnt lgkmcnt(0)
	v_pk_add_f32 v[48:49], v[48:49], v[50:51]
	ds_bpermute_b32 v50, v165, v48
	ds_bpermute_b32 v51, v165, v49
	s_and_saveexec_b64 s[30:31], s[2:3]
	s_cbranch_execz .LBB0_253
	s_lshl_b32 s9, s14, 2
	s_add_i32 s9, s9, -16
	v_mov_b32_e32 v132, s9
	v_lshl_add_u64 v[52:53], v[150:151], 4, v[132:133]
	v_or_b32_e32 v52, s59, v52
	v_lshl_add_u64 v[52:53], v[52:53], 3, s[18:19]
	s_waitcnt lgkmcnt(0)
	v_pk_add_f32 v[48:49], v[48:49], v[50:51]
	global_store_dwordx2 v[52:53], v[48:49], off

.LBB0_254:
	v_add_f32_e32 v48, v180, v181
	v_fmamk_f32 v48, v48, 0x3a800000, v175
	v_rsq_f32_e32 v54, v48
	v_lshlrev_b64 v[48:49], 11, v[148:149]
	v_lshl_add_u64 v[58:59], v[146:147], 0, v[48:49]
	s_and_b64 vcc, exec, s[6:7]
	v_pk_mul_f32 v[46:47], v[46:47], v[54:55] op_sel_hi:[1,0]
	v_pk_mul_f32 v[44:45], v[44:45], v[54:55] op_sel_hi:[1,0]
	s_waitcnt lgkmcnt(1)
	v_mul_f32_e32 v50, 0x3d372713, v46
	v_mul_f32_e32 v50, v46, v50
	v_fma_f32 v50, v46, v50, v46
	v_mul_f32_e32 v49, 0x3d372713, v45
	v_mul_f32_e32 v50, 0x3f4c422a, v50
	v_mul_f32_e32 v49, v45, v49
	v_mul_f32_e32 v50, 0xc038aa3b, v50
	v_pk_mul_f32 v[60:61], v[40:41], v[54:55] op_sel_hi:[1,0]
	v_fma_f32 v49, v45, v49, v45
	s_waitcnt lgkmcnt(0)
	v_exp_f32_e32 v51, v50
	v_mul_f32_e32 v50, 0x3d372713, v47
	v_mul_f32_e32 v40, 0x3d372713, v60
	v_mul_f32_e32 v49, 0x3f4c422a, v49
	v_mul_f32_e32 v50, v47, v50
	v_mul_f32_e32 v40, v60, v40
	v_mul_f32_e32 v41, 0x3d372713, v61
	v_mul_f32_e32 v49, 0xc038aa3b, v49
	v_fma_f32 v50, v47, v50, v47
	v_fma_f32 v40, v60, v40, v60
	v_mul_f32_e32 v41, v61, v41
	v_exp_f32_e32 v49, v49
	v_mul_f32_e32 v50, 0x3f4c422a, v50
	v_mul_f32_e32 v40, 0x3f4c422a, v40
	v_fma_f32 v41, v61, v41, v61
	v_mul_f32_e32 v50, 0xc038aa3b, v50
	v_mul_f32_e32 v40, 0xc038aa3b, v40
	v_mul_f32_e32 v41, 0x3f4c422a, v41
	v_exp_f32_e32 v53, v50
	v_exp_f32_e32 v40, v40
	v_mul_f32_e32 v41, 0xc038aa3b, v41
	v_exp_f32_e32 v41, v41
	v_add_f32_e32 v49, 1.0, v49
	v_rcp_f32_e32 v50, v49
	v_add_f32_e32 v49, 1.0, v51
	v_rcp_f32_e32 v52, v49
	v_add_f32_e32 v49, 1.0, v53
	v_add_f32_e32 v40, 1.0, v40
	v_rcp_f32_e32 v56, v49
	v_rcp_f32_e32 v49, v40
	v_add_f32_e32 v40, 1.0, v41
	v_rcp_f32_e32 v53, v40
	v_mul_f32_e32 v48, 0x3d372713, v44
	v_mul_f32_e32 v48, v44, v48
	v_pk_mul_f32 v[62:63], v[42:43], v[54:55] op_sel_hi:[1,0]
	v_mov_b32_e32 v41, v60
	v_pk_mov_b32 v[42:43], v[44:45], v[60:61] op_sel:[1,0]
	v_mov_b32_e32 v51, v49
	v_mov_b32_e32 v60, v46
	v_fma_f32 v48, v44, v48, v44
	v_mov_b32_e32 v40, v44
	v_pk_mul_f32 v[44:45], v[42:43], v[50:51]
	v_pk_mul_f32 v[42:43], v[60:61], v[52:53]
	v_mov_b32_e32 v60, v47
	v_mul_f32_e32 v46, 0x3d372713, v62
	v_mul_f32_e32 v47, 0x3d372713, v63
	v_mul_f32_e32 v46, v62, v46
	v_mul_f32_e32 v47, v63, v47
	v_mul_f32_e32 v48, 0x3f4c422a, v48
	v_fma_f32 v46, v62, v46, v62
	v_fma_f32 v47, v63, v47, v63
	v_mul_f32_e32 v48, 0xc038aa3b, v48
	v_mul_f32_e32 v46, 0x3f4c422a, v46
	v_mul_f32_e32 v47, 0x3f4c422a, v47
	v_exp_f32_e32 v48, v48
	v_mul_f32_e32 v46, 0xc038aa3b, v46
	v_mul_f32_e32 v47, 0xc038aa3b, v47
	v_exp_f32_e32 v46, v46
	v_exp_f32_e32 v47, v47
	v_add_f32_e32 v48, 1.0, v48
	v_rcp_f32_e32 v48, v48
	v_add_f32_e32 v46, 1.0, v46
	v_add_f32_e32 v47, 1.0, v47
	v_rcp_f32_e32 v46, v46
	v_rcp_f32_e32 v47, v47
	v_mov_b32_e32 v57, v53
	v_pk_mul_f32 v[40:41], v[40:41], v[48:49]
	v_pk_mul_f32 v[48:49], v[60:61], v[56:57]
	v_cvt_pk_bf16_f32 v232, v40, v44
	v_pk_mul_f32 v[38:39], v[38:39], v[54:55] op_sel_hi:[1,0]
	v_cvt_pk_bf16_f32 v233, v42, v48
	v_pk_mul_f32 v[46:47], v[62:63], v[46:47]
	v_cvt_pk_bf16_f32 v234, v41, v43
	v_pk_mul_f32 v[36:37], v[36:37], v[54:55] op_sel_hi:[1,0]
	v_cvt_pk_bf16_f32 v235, v46, v47
	v_mul_f32_e32 v52, 0x3d372713, v38
	s_nop 1
	v_permlane16_swap_b32_e32 v232, v234
	v_permlane16_swap_b32_e32 v233, v235
	v_lshl_add_u64 v[236:237], v[58:59], 0, v[238:239]
	global_store_dwordx4 v[236:237], v[232:235], off
	s_nop 1
	v_mul_f32_e32 v50, 0x3d372713, v36
	v_mul_f32_e32 v51, 0x3d372713, v37
	v_mul_f32_e32 v52, v38, v52
	v_mul_f32_e32 v53, 0x3d372713, v39
	v_mul_f32_e32 v50, v36, v50
	v_mul_f32_e32 v51, v37, v51
	v_fma_f32 v52, v38, v52, v38
	v_mul_f32_e32 v53, v39, v53
	v_fma_f32 v50, v36, v50, v36
	v_fma_f32 v51, v37, v51, v37
	v_mul_f32_e32 v52, 0x3f4c422a, v52
	v_fma_f32 v53, v39, v53, v39
	v_mul_f32_e32 v50, 0x3f4c422a, v50
	v_mul_f32_e32 v51, 0x3f4c422a, v51
	v_mul_f32_e32 v52, 0xc038aa3b, v52
	v_mul_f32_e32 v53, 0x3f4c422a, v53
	v_mul_f32_e32 v50, 0xc038aa3b, v50
	v_mul_f32_e32 v51, 0xc038aa3b, v51
	v_exp_f32_e32 v52, v52
	v_mul_f32_e32 v53, 0xc038aa3b, v53
	v_exp_f32_e32 v50, v50
	v_exp_f32_e32 v51, v51
	v_exp_f32_e32 v53, v53
	v_add_f32_e32 v52, 1.0, v52
	v_add_f32_e32 v50, 1.0, v50
	v_add_f32_e32 v51, 1.0, v51
	v_rcp_f32_e32 v55, v52
	v_add_f32_e32 v52, 1.0, v53
	v_rcp_f32_e32 v50, v50
	v_rcp_f32_e32 v51, v51
	v_rcp_f32_e32 v53, v52
	v_pk_mul_f32 v[32:33], v[32:33], v[54:55] op_sel_hi:[1,0]
	v_pk_mul_f32 v[34:35], v[34:35], v[54:55] op_sel_hi:[1,0]
	v_mul_f32_e32 v50, v36, v50
	v_mul_f32_e32 v52, v37, v51
	v_mul_f32_e32 v36, v38, v55
	v_mul_f32_e32 v38, v39, v53
	v_mul_f32_e32 v37, 0x3d372713, v32
	v_mul_f32_e32 v39, 0x3d372713, v33
	v_mul_f32_e32 v51, 0x3d372713, v34
	v_mul_f32_e32 v53, 0x3d372713, v35
	v_mul_f32_e32 v37, v32, v37
	v_mul_f32_e32 v39, v33, v39
	v_mul_f32_e32 v51, v34, v51
	v_mul_f32_e32 v53, v35, v53
	v_fma_f32 v37, v32, v37, v32
	v_fma_f32 v39, v33, v39, v33
	v_fma_f32 v51, v34, v51, v34
	v_fma_f32 v53, v35, v53, v35
	v_mul_f32_e32 v37, 0x3f4c422a, v37
	v_mul_f32_e32 v39, 0x3f4c422a, v39
	v_mul_f32_e32 v51, 0x3f4c422a, v51
	v_mul_f32_e32 v53, 0x3f4c422a, v53
	v_mul_f32_e32 v37, 0xc038aa3b, v37
	v_mul_f32_e32 v39, 0xc038aa3b, v39
	v_mul_f32_e32 v51, 0xc038aa3b, v51
	v_mul_f32_e32 v53, 0xc038aa3b, v53
	v_exp_f32_e32 v37, v37
	v_exp_f32_e32 v39, v39
	v_exp_f32_e32 v51, v51
	v_exp_f32_e32 v53, v53
	v_add_f32_e32 v37, 1.0, v37
	v_add_f32_e32 v39, 1.0, v39
	v_add_f32_e32 v51, 1.0, v51
	v_add_f32_e32 v53, 1.0, v53
	v_rcp_f32_e32 v37, v37
	v_rcp_f32_e32 v39, v39
	v_rcp_f32_e32 v51, v51
	v_rcp_f32_e32 v53, v53
	v_cvt_pk_bf16_f32 v232, v50, v52
	v_cvt_pk_bf16_f32 v233, v36, v38
	v_mul_f32_e32 v54, v32, v37
	v_mul_f32_e32 v56, v33, v39
	v_mul_f32_e32 v32, v34, v51
	v_mul_f32_e32 v34, v35, v53
	v_cvt_pk_bf16_f32 v234, v54, v56
	v_cvt_pk_bf16_f32 v235, v32, v34
	s_nop 1
	v_permlane16_swap_b32_e32 v232, v234
	v_permlane16_swap_b32_e32 v233, v235
	v_lshl_add_u64 v[236:237], v[58:59], 0, v[238:239]
	global_store_dwordx4 v[236:237], v[232:235], off offset:256
	s_nop 1
	s_cbranch_vccnz .LBB0_258
	v_pk_mul_f32 v[60:61], v[44:45], v[44:45]
	v_pk_add_f32 v[66:67], v[40:41], v[44:45]
	v_pk_mul_f32 v[44:45], v[40:41], v[44:45]
	v_pk_mul_f32 v[58:59], v[40:41], v[40:41]
	v_pk_mul_f32 v[64:65], v[48:49], v[48:49]
	v_mov_b32_e32 v67, v45
	v_pk_add_f32 v[44:45], v[42:43], v[48:49]
	v_pk_mul_f32 v[48:49], v[42:43], v[48:49]
	v_pk_mul_f32 v[62:63], v[42:43], v[42:43]
	v_mul_f32_e32 v48, v46, v46
	v_pk_mov_b32 v[40:41], v[40:41], v[58:59] op_sel:[1,0]
	v_pk_mov_b32 v[42:43], v[42:43], v[60:61] op_sel:[1,0]
	v_mov_b32_e32 v45, v49
	v_pk_fma_f32 v[48:49], v[46:47], v[46:47], v[48:49] op_sel_hi:[1,1,0]
	v_pk_add_f32 v[40:41], v[40:41], v[42:43]
	v_mov_b32_e32 v42, v46
	v_mov_b32_e32 v43, v62
	v_pk_mov_b32 v[46:47], v[46:47], v[64:65] op_sel:[1,0]
	v_mul_f32_e32 v51, v50, v50
	v_mul_f32_e32 v53, v52, v52
	v_mul_f32_e32 v37, v36, v36
	v_mul_f32_e32 v39, v38, v38
	v_pk_add_f32 v[44:45], v[66:67], v[44:45]
	v_mov_b32_e32 v48, v133
	v_pk_add_f32 v[42:43], v[42:43], v[46:47]
	v_mul_f32_e32 v55, v54, v54
	v_mul_f32_e32 v57, v56, v56
	v_mul_f32_e32 v33, v32, v32
	v_mul_f32_e32 v35, v34, v34
	v_pk_add_f32 v[44:45], v[44:45], v[48:49]
	v_pk_add_f32 v[40:41], v[40:41], v[42:43]
	v_pk_add_f32 v[42:43], v[50:51], v[52:53]
	v_pk_add_f32 v[36:37], v[36:37], v[38:39]
	v_pk_add_f32 v[40:41], v[40:41], v[44:45]
	v_pk_add_f32 v[36:37], v[42:43], v[36:37]
	v_pk_add_f32 v[38:39], v[54:55], v[56:57]
	v_pk_add_f32 v[32:33], v[32:33], v[34:35]
	v_pk_add_f32 v[36:37], v[36:37], v[40:41]
	v_pk_add_f32 v[32:33], v[38:39], v[32:33]
	s_nop 0
	v_pk_add_f32 v[32:33], v[32:33], v[36:37]
	ds_bpermute_b32 v34, v164, v32
	ds_bpermute_b32 v35, v164, v33
	s_waitcnt lgkmcnt(0)
	v_pk_add_f32 v[32:33], v[32:33], v[34:35]
	ds_bpermute_b32 v34, v165, v32
	ds_bpermute_b32 v35, v165, v33
	s_and_saveexec_b64 s[30:31], s[2:3]
	s_cbranch_execz .LBB0_257
	s_lshl_b32 s9, s14, 2
	s_add_i32 s9, s9, -16
	v_mov_b32_e32 v132, s9
	v_lshl_add_u64 v[36:37], v[148:149], 4, v[132:133]
	v_or_b32_e32 v36, s59, v36
	v_lshl_add_u64 v[36:37], v[36:37], 3, s[18:19]
	s_waitcnt lgkmcnt(0)
	v_pk_add_f32 v[32:33], v[32:33], v[34:35]
	global_store_dwordx2 v[36:37], v[32:33], off

.LBB0_258:
	v_add_f32_e32 v32, v178, v179
	v_fmamk_f32 v32, v32, 0x3a800000, v175
	v_rsq_f32_e32 v38, v32
	v_lshlrev_b64 v[32:33], 11, v[144:145]
	v_lshl_add_u64 v[42:43], v[146:147], 0, v[32:33]
	s_and_b64 vcc, exec, s[6:7]
	v_pk_mul_f32 v[30:31], v[30:31], v[38:39] op_sel_hi:[1,0]
	v_pk_mul_f32 v[28:29], v[28:29], v[38:39] op_sel_hi:[1,0]
	s_waitcnt lgkmcnt(1)
	v_mul_f32_e32 v34, 0x3d372713, v30
	v_mul_f32_e32 v34, v30, v34
	v_fma_f32 v34, v30, v34, v30
	v_mul_f32_e32 v33, 0x3d372713, v29
	v_mul_f32_e32 v34, 0x3f4c422a, v34
	v_mul_f32_e32 v33, v29, v33
	v_mul_f32_e32 v34, 0xc038aa3b, v34
	v_pk_mul_f32 v[44:45], v[24:25], v[38:39] op_sel_hi:[1,0]
	v_fma_f32 v33, v29, v33, v29
	s_waitcnt lgkmcnt(0)
	v_exp_f32_e32 v35, v34
	v_mul_f32_e32 v34, 0x3d372713, v31
	v_mul_f32_e32 v24, 0x3d372713, v44
	v_mul_f32_e32 v33, 0x3f4c422a, v33
	v_mul_f32_e32 v34, v31, v34
	v_mul_f32_e32 v24, v44, v24
	v_mul_f32_e32 v25, 0x3d372713, v45
	v_mul_f32_e32 v33, 0xc038aa3b, v33
	v_fma_f32 v34, v31, v34, v31
	v_fma_f32 v24, v44, v24, v44
	v_mul_f32_e32 v25, v45, v25
	v_exp_f32_e32 v33, v33
	v_mul_f32_e32 v34, 0x3f4c422a, v34
	v_mul_f32_e32 v24, 0x3f4c422a, v24
	v_fma_f32 v25, v45, v25, v45
	v_mul_f32_e32 v34, 0xc038aa3b, v34
	v_mul_f32_e32 v24, 0xc038aa3b, v24
	v_mul_f32_e32 v25, 0x3f4c422a, v25
	v_exp_f32_e32 v37, v34
	v_exp_f32_e32 v24, v24
	v_mul_f32_e32 v25, 0xc038aa3b, v25
	v_exp_f32_e32 v25, v25
	v_add_f32_e32 v33, 1.0, v33
	v_rcp_f32_e32 v34, v33
	v_add_f32_e32 v33, 1.0, v35
	v_rcp_f32_e32 v36, v33
	v_add_f32_e32 v33, 1.0, v37
	v_add_f32_e32 v24, 1.0, v24
	v_rcp_f32_e32 v40, v33
	v_rcp_f32_e32 v33, v24
	v_add_f32_e32 v24, 1.0, v25
	v_rcp_f32_e32 v37, v24
	v_mul_f32_e32 v32, 0x3d372713, v28
	v_mul_f32_e32 v32, v28, v32
	v_pk_mul_f32 v[46:47], v[26:27], v[38:39] op_sel_hi:[1,0]
	v_mov_b32_e32 v25, v44
	v_pk_mov_b32 v[26:27], v[28:29], v[44:45] op_sel:[1,0]
	v_mov_b32_e32 v35, v33
	v_mov_b32_e32 v44, v30
	v_fma_f32 v32, v28, v32, v28
	v_mov_b32_e32 v24, v28
	v_pk_mul_f32 v[28:29], v[26:27], v[34:35]
	v_pk_mul_f32 v[26:27], v[44:45], v[36:37]
	v_mov_b32_e32 v44, v31
	v_mul_f32_e32 v30, 0x3d372713, v46
	v_mul_f32_e32 v31, 0x3d372713, v47
	v_mul_f32_e32 v30, v46, v30
	v_mul_f32_e32 v31, v47, v31
	v_mul_f32_e32 v32, 0x3f4c422a, v32
	v_fma_f32 v30, v46, v30, v46
	v_fma_f32 v31, v47, v31, v47
	v_mul_f32_e32 v32, 0xc038aa3b, v32
	v_mul_f32_e32 v30, 0x3f4c422a, v30
	v_mul_f32_e32 v31, 0x3f4c422a, v31
	v_exp_f32_e32 v32, v32
	v_mul_f32_e32 v30, 0xc038aa3b, v30
	v_mul_f32_e32 v31, 0xc038aa3b, v31
	v_exp_f32_e32 v30, v30
	v_exp_f32_e32 v31, v31
	v_add_f32_e32 v32, 1.0, v32
	v_rcp_f32_e32 v32, v32
	v_add_f32_e32 v30, 1.0, v30
	v_add_f32_e32 v31, 1.0, v31
	v_rcp_f32_e32 v30, v30
	v_rcp_f32_e32 v31, v31
	v_mov_b32_e32 v41, v37
	v_pk_mul_f32 v[24:25], v[24:25], v[32:33]
	v_pk_mul_f32 v[32:33], v[44:45], v[40:41]
	v_cvt_pk_bf16_f32 v232, v24, v28
	v_pk_mul_f32 v[22:23], v[22:23], v[38:39] op_sel_hi:[1,0]
	v_cvt_pk_bf16_f32 v233, v26, v32
	v_pk_mul_f32 v[30:31], v[46:47], v[30:31]
	v_cvt_pk_bf16_f32 v234, v25, v27
	v_pk_mul_f32 v[20:21], v[20:21], v[38:39] op_sel_hi:[1,0]
	v_cvt_pk_bf16_f32 v235, v30, v31
	v_mul_f32_e32 v36, 0x3d372713, v22
	s_nop 1
	v_permlane16_swap_b32_e32 v232, v234
	v_permlane16_swap_b32_e32 v233, v235
	v_lshl_add_u64 v[236:237], v[42:43], 0, v[238:239]
	global_store_dwordx4 v[236:237], v[232:235], off
	s_nop 1
	v_mul_f32_e32 v34, 0x3d372713, v20
	v_mul_f32_e32 v35, 0x3d372713, v21
	v_mul_f32_e32 v36, v22, v36
	v_mul_f32_e32 v37, 0x3d372713, v23
	v_mul_f32_e32 v34, v20, v34
	v_mul_f32_e32 v35, v21, v35
	v_fma_f32 v36, v22, v36, v22
	v_mul_f32_e32 v37, v23, v37
	v_fma_f32 v34, v20, v34, v20
	v_fma_f32 v35, v21, v35, v21
	v_mul_f32_e32 v36, 0x3f4c422a, v36
	v_fma_f32 v37, v23, v37, v23
	v_mul_f32_e32 v34, 0x3f4c422a, v34
	v_mul_f32_e32 v35, 0x3f4c422a, v35
	v_mul_f32_e32 v36, 0xc038aa3b, v36
	v_mul_f32_e32 v37, 0x3f4c422a, v37
	v_mul_f32_e32 v34, 0xc038aa3b, v34
	v_mul_f32_e32 v35, 0xc038aa3b, v35
	v_exp_f32_e32 v36, v36
	v_mul_f32_e32 v37, 0xc038aa3b, v37
	v_exp_f32_e32 v34, v34
	v_exp_f32_e32 v35, v35
	v_exp_f32_e32 v37, v37
	v_add_f32_e32 v36, 1.0, v36
	v_add_f32_e32 v34, 1.0, v34
	v_add_f32_e32 v35, 1.0, v35
	v_rcp_f32_e32 v39, v36
	v_add_f32_e32 v36, 1.0, v37
	v_rcp_f32_e32 v34, v34
	v_rcp_f32_e32 v35, v35
	v_rcp_f32_e32 v37, v36
	v_pk_mul_f32 v[16:17], v[16:17], v[38:39] op_sel_hi:[1,0]
	v_pk_mul_f32 v[18:19], v[18:19], v[38:39] op_sel_hi:[1,0]
	v_mul_f32_e32 v34, v20, v34
	v_mul_f32_e32 v36, v21, v35
	v_mul_f32_e32 v20, v22, v39
	v_mul_f32_e32 v22, v23, v37
	v_mul_f32_e32 v21, 0x3d372713, v16
	v_mul_f32_e32 v23, 0x3d372713, v17
	v_mul_f32_e32 v35, 0x3d372713, v18
	v_mul_f32_e32 v37, 0x3d372713, v19
	v_mul_f32_e32 v21, v16, v21
	v_mul_f32_e32 v23, v17, v23
	v_mul_f32_e32 v35, v18, v35
	v_mul_f32_e32 v37, v19, v37
	v_fma_f32 v21, v16, v21, v16
	v_fma_f32 v23, v17, v23, v17
	v_fma_f32 v35, v18, v35, v18
	v_fma_f32 v37, v19, v37, v19
	v_mul_f32_e32 v21, 0x3f4c422a, v21
	v_mul_f32_e32 v23, 0x3f4c422a, v23
	v_mul_f32_e32 v35, 0x3f4c422a, v35
	v_mul_f32_e32 v37, 0x3f4c422a, v37
	v_mul_f32_e32 v21, 0xc038aa3b, v21
	v_mul_f32_e32 v23, 0xc038aa3b, v23
	v_mul_f32_e32 v35, 0xc038aa3b, v35
	v_mul_f32_e32 v37, 0xc038aa3b, v37
	v_exp_f32_e32 v21, v21
	v_exp_f32_e32 v23, v23
	v_exp_f32_e32 v35, v35
	v_exp_f32_e32 v37, v37
	v_add_f32_e32 v21, 1.0, v21
	v_add_f32_e32 v23, 1.0, v23
	v_add_f32_e32 v35, 1.0, v35
	v_add_f32_e32 v37, 1.0, v37
	v_rcp_f32_e32 v21, v21
	v_rcp_f32_e32 v23, v23
	v_rcp_f32_e32 v35, v35
	v_rcp_f32_e32 v37, v37
	v_cvt_pk_bf16_f32 v232, v34, v36
	v_cvt_pk_bf16_f32 v233, v20, v22
	v_mul_f32_e32 v38, v16, v21
	v_mul_f32_e32 v40, v17, v23
	v_mul_f32_e32 v16, v18, v35
	v_mul_f32_e32 v18, v19, v37
	v_cvt_pk_bf16_f32 v234, v38, v40
	v_cvt_pk_bf16_f32 v235, v16, v18
	s_nop 1
	v_permlane16_swap_b32_e32 v232, v234
	v_permlane16_swap_b32_e32 v233, v235
	v_lshl_add_u64 v[236:237], v[42:43], 0, v[238:239]
	global_store_dwordx4 v[236:237], v[232:235], off offset:256
	s_nop 1
	s_cbranch_vccnz .LBB0_262
	v_pk_mul_f32 v[44:45], v[28:29], v[28:29]
	v_pk_add_f32 v[50:51], v[24:25], v[28:29]
	v_pk_mul_f32 v[28:29], v[24:25], v[28:29]
	v_pk_mul_f32 v[42:43], v[24:25], v[24:25]
	v_pk_mul_f32 v[48:49], v[32:33], v[32:33]
	v_mov_b32_e32 v51, v29
	v_pk_add_f32 v[28:29], v[26:27], v[32:33]
	v_pk_mul_f32 v[32:33], v[26:27], v[32:33]
	v_pk_mul_f32 v[46:47], v[26:27], v[26:27]
	v_mul_f32_e32 v32, v30, v30
	v_pk_mov_b32 v[24:25], v[24:25], v[42:43] op_sel:[1,0]
	v_pk_mov_b32 v[26:27], v[26:27], v[44:45] op_sel:[1,0]
	v_mov_b32_e32 v29, v33
	v_pk_fma_f32 v[32:33], v[30:31], v[30:31], v[32:33] op_sel_hi:[1,1,0]
	v_pk_add_f32 v[24:25], v[24:25], v[26:27]
	v_mov_b32_e32 v26, v30
	v_mov_b32_e32 v27, v46
	v_pk_mov_b32 v[30:31], v[30:31], v[48:49] op_sel:[1,0]
	v_mul_f32_e32 v35, v34, v34
	v_mul_f32_e32 v37, v36, v36
	v_mul_f32_e32 v21, v20, v20
	v_mul_f32_e32 v23, v22, v22
	v_pk_add_f32 v[28:29], v[50:51], v[28:29]
	v_mov_b32_e32 v32, v133
	v_pk_add_f32 v[26:27], v[26:27], v[30:31]
	v_mul_f32_e32 v39, v38, v38
	v_mul_f32_e32 v41, v40, v40
	v_mul_f32_e32 v17, v16, v16
	v_mul_f32_e32 v19, v18, v18
	v_pk_add_f32 v[28:29], v[28:29], v[32:33]
	v_pk_add_f32 v[24:25], v[24:25], v[26:27]
	v_pk_add_f32 v[26:27], v[34:35], v[36:37]
	v_pk_add_f32 v[20:21], v[20:21], v[22:23]
	v_pk_add_f32 v[24:25], v[24:25], v[28:29]
	v_pk_add_f32 v[20:21], v[26:27], v[20:21]
	v_pk_add_f32 v[22:23], v[38:39], v[40:41]
	v_pk_add_f32 v[16:17], v[16:17], v[18:19]
	v_pk_add_f32 v[20:21], v[20:21], v[24:25]
	v_pk_add_f32 v[16:17], v[22:23], v[16:17]
	s_nop 0
	v_pk_add_f32 v[16:17], v[16:17], v[20:21]
	ds_bpermute_b32 v18, v164, v16
	ds_bpermute_b32 v19, v164, v17
	s_waitcnt lgkmcnt(0)
	v_pk_add_f32 v[16:17], v[16:17], v[18:19]
	ds_bpermute_b32 v18, v165, v16
	ds_bpermute_b32 v19, v165, v17
	s_and_saveexec_b64 s[30:31], s[2:3]
	s_cbranch_execz .LBB0_261
	s_lshl_b32 s9, s14, 2
	s_add_i32 s9, s9, -16
	v_mov_b32_e32 v132, s9
	v_lshl_add_u64 v[20:21], v[144:145], 4, v[132:133]
	v_or_b32_e32 v20, s59, v20
	v_lshl_add_u64 v[20:21], v[20:21], 3, s[18:19]
	s_waitcnt lgkmcnt(0)
	v_pk_add_f32 v[16:17], v[16:17], v[18:19]
	global_store_dwordx2 v[20:21], v[16:17], off

.LBB0_262:
	v_add_f32_e32 v16, v176, v177
	v_fmamk_f32 v16, v16, 0x3a800000, v175
	v_rsq_f32_e32 v22, v16
	v_lshlrev_b64 v[16:17], 11, v[142:143]
	v_lshl_add_u64 v[26:27], v[146:147], 0, v[16:17]
	s_and_b64 vcc, exec, s[6:7]
	v_pk_mul_f32 v[14:15], v[14:15], v[22:23] op_sel_hi:[1,0]
	v_pk_mul_f32 v[12:13], v[12:13], v[22:23] op_sel_hi:[1,0]
	s_waitcnt lgkmcnt(1)
	v_mul_f32_e32 v18, 0x3d372713, v14
	v_mul_f32_e32 v18, v14, v18
	v_fma_f32 v18, v14, v18, v14
	v_mul_f32_e32 v17, 0x3d372713, v13
	v_mul_f32_e32 v18, 0x3f4c422a, v18
	v_mul_f32_e32 v17, v13, v17
	v_mul_f32_e32 v18, 0xc038aa3b, v18
	v_pk_mul_f32 v[28:29], v[8:9], v[22:23] op_sel_hi:[1,0]
	v_fma_f32 v17, v13, v17, v13
	s_waitcnt lgkmcnt(0)
	v_exp_f32_e32 v19, v18
	v_mul_f32_e32 v18, 0x3d372713, v15
	v_mul_f32_e32 v8, 0x3d372713, v28
	v_mul_f32_e32 v17, 0x3f4c422a, v17
	v_mul_f32_e32 v18, v15, v18
	v_mul_f32_e32 v8, v28, v8
	v_mul_f32_e32 v9, 0x3d372713, v29
	v_mul_f32_e32 v17, 0xc038aa3b, v17
	v_fma_f32 v18, v15, v18, v15
	v_fma_f32 v8, v28, v8, v28
	v_mul_f32_e32 v9, v29, v9
	v_exp_f32_e32 v17, v17
	v_mul_f32_e32 v18, 0x3f4c422a, v18
	v_mul_f32_e32 v8, 0x3f4c422a, v8
	v_fma_f32 v9, v29, v9, v29
	v_mul_f32_e32 v18, 0xc038aa3b, v18
	v_mul_f32_e32 v8, 0xc038aa3b, v8
	v_mul_f32_e32 v9, 0x3f4c422a, v9
	v_exp_f32_e32 v21, v18
	v_exp_f32_e32 v8, v8
	v_mul_f32_e32 v9, 0xc038aa3b, v9
	v_exp_f32_e32 v9, v9
	v_add_f32_e32 v17, 1.0, v17
	v_rcp_f32_e32 v18, v17
	v_add_f32_e32 v17, 1.0, v19
	v_rcp_f32_e32 v20, v17
	v_add_f32_e32 v17, 1.0, v21
	v_add_f32_e32 v8, 1.0, v8
	v_rcp_f32_e32 v24, v17
	v_rcp_f32_e32 v17, v8
	v_add_f32_e32 v8, 1.0, v9
	v_rcp_f32_e32 v21, v8
	v_mul_f32_e32 v16, 0x3d372713, v12
	v_mul_f32_e32 v16, v12, v16
	v_pk_mul_f32 v[30:31], v[10:11], v[22:23] op_sel_hi:[1,0]
	v_mov_b32_e32 v9, v28
	v_pk_mov_b32 v[10:11], v[12:13], v[28:29] op_sel:[1,0]
	v_mov_b32_e32 v19, v17
	v_mov_b32_e32 v28, v14
	v_fma_f32 v16, v12, v16, v12
	v_mov_b32_e32 v8, v12
	v_pk_mul_f32 v[12:13], v[10:11], v[18:19]
	v_pk_mul_f32 v[10:11], v[28:29], v[20:21]
	v_mov_b32_e32 v28, v15
	v_mul_f32_e32 v14, 0x3d372713, v30
	v_mul_f32_e32 v15, 0x3d372713, v31
	v_mul_f32_e32 v14, v30, v14
	v_mul_f32_e32 v15, v31, v15
	v_mul_f32_e32 v16, 0x3f4c422a, v16
	v_fma_f32 v14, v30, v14, v30
	v_fma_f32 v15, v31, v15, v31
	v_mul_f32_e32 v16, 0xc038aa3b, v16
	v_mul_f32_e32 v14, 0x3f4c422a, v14
	v_mul_f32_e32 v15, 0x3f4c422a, v15
	v_exp_f32_e32 v16, v16
	v_mul_f32_e32 v14, 0xc038aa3b, v14
	v_mul_f32_e32 v15, 0xc038aa3b, v15
	v_exp_f32_e32 v14, v14
	v_exp_f32_e32 v15, v15
	v_add_f32_e32 v16, 1.0, v16
	v_rcp_f32_e32 v16, v16
	v_add_f32_e32 v14, 1.0, v14
	v_add_f32_e32 v15, 1.0, v15
	v_rcp_f32_e32 v14, v14
	v_rcp_f32_e32 v15, v15
	v_mov_b32_e32 v25, v21
	v_pk_mul_f32 v[8:9], v[8:9], v[16:17]
	v_pk_mul_f32 v[16:17], v[28:29], v[24:25]
	v_cvt_pk_bf16_f32 v232, v8, v12
	v_pk_mul_f32 v[6:7], v[6:7], v[22:23] op_sel_hi:[1,0]
	v_cvt_pk_bf16_f32 v233, v10, v16
	v_pk_mul_f32 v[14:15], v[30:31], v[14:15]
	v_cvt_pk_bf16_f32 v234, v9, v11
	v_pk_mul_f32 v[4:5], v[4:5], v[22:23] op_sel_hi:[1,0]
	v_cvt_pk_bf16_f32 v235, v14, v15
	v_mul_f32_e32 v20, 0x3d372713, v6
	s_nop 1
	v_permlane16_swap_b32_e32 v232, v234
	v_permlane16_swap_b32_e32 v233, v235
	v_lshl_add_u64 v[236:237], v[26:27], 0, v[238:239]
	global_store_dwordx4 v[236:237], v[232:235], off
	s_nop 1
	v_mul_f32_e32 v18, 0x3d372713, v4
	v_mul_f32_e32 v19, 0x3d372713, v5
	v_mul_f32_e32 v20, v6, v20
	v_mul_f32_e32 v21, 0x3d372713, v7
	v_mul_f32_e32 v18, v4, v18
	v_mul_f32_e32 v19, v5, v19
	v_fma_f32 v20, v6, v20, v6
	v_mul_f32_e32 v21, v7, v21
	v_fma_f32 v18, v4, v18, v4
	v_fma_f32 v19, v5, v19, v5
	v_mul_f32_e32 v20, 0x3f4c422a, v20
	v_fma_f32 v21, v7, v21, v7
	v_mul_f32_e32 v18, 0x3f4c422a, v18
	v_mul_f32_e32 v19, 0x3f4c422a, v19
	v_mul_f32_e32 v20, 0xc038aa3b, v20
	v_mul_f32_e32 v21, 0x3f4c422a, v21
	v_mul_f32_e32 v18, 0xc038aa3b, v18
	v_mul_f32_e32 v19, 0xc038aa3b, v19
	v_exp_f32_e32 v20, v20
	v_mul_f32_e32 v21, 0xc038aa3b, v21
	v_exp_f32_e32 v18, v18
	v_exp_f32_e32 v19, v19
	v_exp_f32_e32 v21, v21
	v_add_f32_e32 v20, 1.0, v20
	v_add_f32_e32 v18, 1.0, v18
	v_add_f32_e32 v19, 1.0, v19
	v_rcp_f32_e32 v23, v20
	v_add_f32_e32 v20, 1.0, v21
	v_rcp_f32_e32 v18, v18
	v_rcp_f32_e32 v19, v19
	v_rcp_f32_e32 v21, v20
	v_pk_mul_f32 v[0:1], v[0:1], v[22:23] op_sel_hi:[1,0]
	v_pk_mul_f32 v[2:3], v[2:3], v[22:23] op_sel_hi:[1,0]
	v_mul_f32_e32 v18, v4, v18
	v_mul_f32_e32 v20, v5, v19
	v_mul_f32_e32 v4, v6, v23
	v_mul_f32_e32 v6, v7, v21
	v_mul_f32_e32 v5, 0x3d372713, v0
	v_mul_f32_e32 v7, 0x3d372713, v1
	v_mul_f32_e32 v19, 0x3d372713, v2
	v_mul_f32_e32 v21, 0x3d372713, v3
	v_mul_f32_e32 v5, v0, v5
	v_mul_f32_e32 v7, v1, v7
	v_mul_f32_e32 v19, v2, v19
	v_mul_f32_e32 v21, v3, v21
	v_fma_f32 v5, v0, v5, v0
	v_fma_f32 v7, v1, v7, v1
	v_fma_f32 v19, v2, v19, v2
	v_fma_f32 v21, v3, v21, v3
	v_mul_f32_e32 v5, 0x3f4c422a, v5
	v_mul_f32_e32 v7, 0x3f4c422a, v7
	v_mul_f32_e32 v19, 0x3f4c422a, v19
	v_mul_f32_e32 v21, 0x3f4c422a, v21
	v_mul_f32_e32 v5, 0xc038aa3b, v5
	v_mul_f32_e32 v7, 0xc038aa3b, v7
	v_mul_f32_e32 v19, 0xc038aa3b, v19
	v_mul_f32_e32 v21, 0xc038aa3b, v21
	v_exp_f32_e32 v5, v5
	v_exp_f32_e32 v7, v7
	v_exp_f32_e32 v19, v19
	v_exp_f32_e32 v21, v21
	v_add_f32_e32 v5, 1.0, v5
	v_add_f32_e32 v7, 1.0, v7
	v_add_f32_e32 v19, 1.0, v19
	v_add_f32_e32 v21, 1.0, v21
	v_rcp_f32_e32 v5, v5
	v_rcp_f32_e32 v7, v7
	v_rcp_f32_e32 v19, v19
	v_rcp_f32_e32 v21, v21
	v_cvt_pk_bf16_f32 v232, v18, v20
	v_cvt_pk_bf16_f32 v233, v4, v6
	v_mul_f32_e32 v22, v0, v5
	v_mul_f32_e32 v24, v1, v7
	v_mul_f32_e32 v0, v2, v19
	v_mul_f32_e32 v2, v3, v21
	v_cvt_pk_bf16_f32 v234, v22, v24
	v_cvt_pk_bf16_f32 v235, v0, v2
	s_nop 1
	v_permlane16_swap_b32_e32 v232, v234
	v_permlane16_swap_b32_e32 v233, v235
	v_lshl_add_u64 v[236:237], v[26:27], 0, v[238:239]
	global_store_dwordx4 v[236:237], v[232:235], off offset:256
	s_nop 1
	s_cbranch_vccnz .LBB0_266
	v_pk_mul_f32 v[28:29], v[12:13], v[12:13]
	v_pk_add_f32 v[34:35], v[8:9], v[12:13]
	v_pk_mul_f32 v[12:13], v[8:9], v[12:13]
	v_pk_mul_f32 v[26:27], v[8:9], v[8:9]
	v_pk_mul_f32 v[32:33], v[16:17], v[16:17]
	v_mov_b32_e32 v35, v13
	v_pk_add_f32 v[12:13], v[10:11], v[16:17]
	v_pk_mul_f32 v[16:17], v[10:11], v[16:17]
	v_pk_mul_f32 v[30:31], v[10:11], v[10:11]
	v_mul_f32_e32 v16, v14, v14
	v_pk_mov_b32 v[8:9], v[8:9], v[26:27] op_sel:[1,0]
	v_pk_mov_b32 v[10:11], v[10:11], v[28:29] op_sel:[1,0]
	v_mov_b32_e32 v13, v17
	v_pk_fma_f32 v[16:17], v[14:15], v[14:15], v[16:17] op_sel_hi:[1,1,0]
	v_pk_add_f32 v[8:9], v[8:9], v[10:11]
	v_mov_b32_e32 v10, v14
	v_mov_b32_e32 v11, v30
	v_pk_mov_b32 v[14:15], v[14:15], v[32:33] op_sel:[1,0]
	v_mul_f32_e32 v19, v18, v18
	v_mul_f32_e32 v21, v20, v20
	v_mul_f32_e32 v5, v4, v4
	v_mul_f32_e32 v7, v6, v6
	v_pk_add_f32 v[12:13], v[34:35], v[12:13]
	v_mov_b32_e32 v16, v133
	v_pk_add_f32 v[10:11], v[10:11], v[14:15]
	v_mul_f32_e32 v23, v22, v22
	v_mul_f32_e32 v25, v24, v24
	v_mul_f32_e32 v1, v0, v0
	v_mul_f32_e32 v3, v2, v2
	v_pk_add_f32 v[12:13], v[12:13], v[16:17]
	v_pk_add_f32 v[8:9], v[8:9], v[10:11]
	v_pk_add_f32 v[10:11], v[18:19], v[20:21]
	v_pk_add_f32 v[4:5], v[4:5], v[6:7]
	v_pk_add_f32 v[8:9], v[8:9], v[12:13]
	v_pk_add_f32 v[4:5], v[10:11], v[4:5]
	v_pk_add_f32 v[6:7], v[22:23], v[24:25]
	v_pk_add_f32 v[0:1], v[0:1], v[2:3]
	v_pk_add_f32 v[4:5], v[4:5], v[8:9]
	v_pk_add_f32 v[0:1], v[6:7], v[0:1]
	s_nop 0
	v_pk_add_f32 v[0:1], v[0:1], v[4:5]
	ds_bpermute_b32 v2, v164, v0
	ds_bpermute_b32 v3, v164, v1
	s_waitcnt lgkmcnt(0)
	v_pk_add_f32 v[0:1], v[0:1], v[2:3]
	ds_bpermute_b32 v2, v165, v0
	ds_bpermute_b32 v3, v165, v1
	s_and_saveexec_b64 s[6:7], s[2:3]
	s_cbranch_execz .LBB0_265
	s_lshl_b32 s9, s14, 2
	s_add_i32 s9, s9, -16
	v_mov_b32_e32 v132, s9
	v_lshl_add_u64 v[4:5], v[142:143], 4, v[132:133]
	v_or_b32_e32 v4, s59, v4
	v_lshl_add_u64 v[4:5], v[4:5], 3, s[18:19]
	s_waitcnt lgkmcnt(0)
	v_pk_add_f32 v[0:1], v[0:1], v[2:3]
	global_store_dwordx2 v[4:5], v[0:1], off

.LBB0_707:
	ds_read_b128 v[48:51], v196
	ds_read_b128 v[52:55], v196 offset:1024
	ds_read_b128 v[56:59], v196 offset:2048
	ds_read_b128 v[60:63], v196 offset:3072
	ds_read_b128 v[162:165], v197
	ds_read_b128 v[166:169], v197 offset:1024
	ds_read_b128 v[170:173], v197 offset:2048
	ds_read_b128 v[174:177], v197 offset:3072
	s_add_u32 s6, s4, 0xfffc0080
	s_addc_u32 s7, s5, -1
	s_cmp_eq_u32 s56, 12
	s_cselect_b32 s9, s11, s7
	s_cselect_b32 s8, s27, s6
	s_cselect_b32 s7, s25, s55
	s_cselect_b32 s6, s53, s54
	v_lshl_add_u64 v[190:191], s[4:5], 0, v[154:155]
	s_add_i32 m0, s63, 0xc000
	ds_read_b128 v[178:181], v198
	ds_read_b128 v[182:185], v198 offset:1024
	ds_read_b128 v[186:189], v198 offset:2048
	ds_read_b128 v[200:203], v198 offset:3072
	ds_read_b128 v[204:207], v198 offset:4096
	ds_read_b128 v[208:211], v198 offset:5120
	ds_read_b128 v[216:219], v198 offset:6144
	ds_read_b128 v[220:223], v198 offset:7168
	global_load_lds_dwordx4 v[190:191], off
	v_lshl_add_u64 v[190:191], s[4:5], 0, v[156:157]
	s_add_i32 m0, s63, 0xe000
	s_nop 0
	global_load_lds_dwordx4 v[190:191], off
	s_waitcnt vmcnt(8)
	s_waitcnt lgkmcnt(0)
	s_barrier
	s_setprio 1
	s_waitcnt lgkmcnt(0)
	v_mfma_f32_16x16x32_bf16 v[140:143], v[48:51], v[178:181], v[140:143]
	v_mfma_f32_16x16x32_bf16 v[136:139], v[56:59], v[178:181], v[136:139]
	v_mfma_f32_16x16x32_bf16 v[124:127], v[48:51], v[186:189], v[124:127]
	v_mfma_f32_16x16x32_bf16 v[120:123], v[56:59], v[186:189], v[120:123]
	v_mfma_f32_16x16x32_bf16 v[108:111], v[48:51], v[204:207], v[108:111]
	v_mfma_f32_16x16x32_bf16 v[104:107], v[56:59], v[204:207], v[104:107]
	v_mfma_f32_16x16x32_bf16 v[92:95], v[48:51], v[216:219], v[92:95]
	v_mfma_f32_16x16x32_bf16 v[88:91], v[56:59], v[216:219], v[88:91]
	v_mfma_f32_16x16x32_bf16 v[140:143], v[52:55], v[182:185], v[140:143]
	v_mfma_f32_16x16x32_bf16 v[136:139], v[60:63], v[182:185], v[136:139]
	v_mfma_f32_16x16x32_bf16 v[124:127], v[52:55], v[200:203], v[124:127]
	v_mfma_f32_16x16x32_bf16 v[120:123], v[60:63], v[200:203], v[120:123]
	v_mfma_f32_16x16x32_bf16 v[108:111], v[52:55], v[208:211], v[108:111]
	v_mfma_f32_16x16x32_bf16 v[104:107], v[60:63], v[208:211], v[104:107]
	v_mfma_f32_16x16x32_bf16 v[92:95], v[52:55], v[220:223], v[92:95]
	v_mfma_f32_16x16x32_bf16 v[88:91], v[60:63], v[220:223], v[88:91]
	s_setprio 0
	s_setprio 1
	v_mfma_f32_16x16x32_bf16 v[132:135], v[162:165], v[178:181], v[132:135]
	v_mfma_f32_16x16x32_bf16 v[128:131], v[170:173], v[178:181], v[128:131]
	v_mfma_f32_16x16x32_bf16 v[116:119], v[162:165], v[186:189], v[116:119]
	v_mfma_f32_16x16x32_bf16 v[112:115], v[170:173], v[186:189], v[112:115]
	v_mfma_f32_16x16x32_bf16 v[100:103], v[162:165], v[204:207], v[100:103]
	v_mfma_f32_16x16x32_bf16 v[96:99], v[170:173], v[204:207], v[96:99]
	v_mfma_f32_16x16x32_bf16 v[84:87], v[162:165], v[216:219], v[84:87]
	v_mfma_f32_16x16x32_bf16 v[80:83], v[170:173], v[216:219], v[80:83]
	v_mfma_f32_16x16x32_bf16 v[132:135], v[166:169], v[182:185], v[132:135]
	v_mfma_f32_16x16x32_bf16 v[128:131], v[174:177], v[182:185], v[128:131]
	v_mfma_f32_16x16x32_bf16 v[116:119], v[166:169], v[200:203], v[116:119]
	v_mfma_f32_16x16x32_bf16 v[112:115], v[174:177], v[200:203], v[112:115]
	v_mfma_f32_16x16x32_bf16 v[100:103], v[166:169], v[208:211], v[100:103]
	v_mfma_f32_16x16x32_bf16 v[96:99], v[174:177], v[208:211], v[96:99]
	v_mfma_f32_16x16x32_bf16 v[84:87], v[166:169], v[220:223], v[84:87]
	v_mfma_f32_16x16x32_bf16 v[80:83], v[174:177], v[220:223], v[80:83]
	s_setprio 0
	s_barrier
	s_add_i32 s57, s87, s62
	v_lshl_add_u64 v[190:191], s[6:7], 0, v[144:145]
	s_mov_b32 m0, s57
	ds_read_b128 v[178:181], v198 offset:16384
	ds_read_b128 v[182:185], v198 offset:17408
	ds_read_b128 v[186:189], v198 offset:18432
	ds_read_b128 v[200:203], v198 offset:19456
	ds_read_b128 v[204:207], v198 offset:20480
	ds_read_b128 v[208:211], v198 offset:21504
	ds_read_b128 v[216:219], v198 offset:22528
	ds_read_b128 v[220:223], v198 offset:23552
	global_load_lds_dwordx4 v[190:191], off
	s_add_i32 m0, s57, 0x2000
	s_add_u32 s58, s6, 0x40000
	v_lshl_add_u64 v[212:213], s[6:7], 0, v[146:147]
	s_addc_u32 s59, s7, 0
	s_add_i32 s57, s88, s62
	global_load_lds_dwordx4 v[212:213], off
	v_lshl_add_u64 v[224:225], s[58:59], 0, v[144:145]
	s_mov_b32 m0, s57
	v_lshl_add_u64 v[226:227], s[8:9], 0, v[146:147]
	global_load_lds_dwordx4 v[224:225], off
	v_lshl_add_u64 v[224:225], s[58:59], 0, v[146:147]
	s_add_i32 m0, s57, 0x2000
	s_nop 0
	global_load_lds_dwordx4 v[224:225], off
	v_lshl_add_u64 v[224:225], s[8:9], 0, v[144:145]
	s_mov_b32 m0, s63
	s_nop 0
	global_load_lds_dwordx4 v[224:225], off
	s_mov_b32 m0, s64
	s_nop 0
	global_load_lds_dwordx4 v[226:227], off
	s_waitcnt vmcnt(8)
	s_waitcnt lgkmcnt(0)
	s_barrier
	s_setprio 1
	s_waitcnt lgkmcnt(0)
	v_mfma_f32_16x16x32_bf16 v[76:79], v[48:51], v[178:181], v[76:79]
	v_mfma_f32_16x16x32_bf16 v[72:75], v[56:59], v[178:181], v[72:75]
	v_mfma_f32_16x16x32_bf16 v[44:47], v[48:51], v[186:189], v[44:47]
	v_mfma_f32_16x16x32_bf16 v[40:43], v[56:59], v[186:189], v[40:43]
	v_mfma_f32_16x16x32_bf16 v[28:31], v[48:51], v[204:207], v[28:31]
	v_mfma_f32_16x16x32_bf16 v[24:27], v[56:59], v[204:207], v[24:27]
	v_mfma_f32_16x16x32_bf16 v[12:15], v[48:51], v[216:219], v[12:15]
	v_mfma_f32_16x16x32_bf16 v[8:11], v[56:59], v[216:219], v[8:11]
	v_mfma_f32_16x16x32_bf16 v[76:79], v[52:55], v[182:185], v[76:79]
	v_mfma_f32_16x16x32_bf16 v[72:75], v[60:63], v[182:185], v[72:75]
	v_mfma_f32_16x16x32_bf16 v[44:47], v[52:55], v[200:203], v[44:47]
	v_mfma_f32_16x16x32_bf16 v[40:43], v[60:63], v[200:203], v[40:43]
	v_mfma_f32_16x16x32_bf16 v[28:31], v[52:55], v[208:211], v[28:31]
	v_mfma_f32_16x16x32_bf16 v[24:27], v[60:63], v[208:211], v[24:27]
	v_mfma_f32_16x16x32_bf16 v[12:15], v[52:55], v[220:223], v[12:15]
	v_mfma_f32_16x16x32_bf16 v[8:11], v[60:63], v[220:223], v[8:11]
	s_setprio 0
	s_setprio 1
	v_mfma_f32_16x16x32_bf16 v[36:39], v[162:165], v[186:189], v[36:39]
	v_mfma_f32_16x16x32_bf16 v[32:35], v[170:173], v[186:189], v[32:35]
	v_mfma_f32_16x16x32_bf16 v[20:23], v[162:165], v[204:207], v[20:23]
	v_mfma_f32_16x16x32_bf16 v[16:19], v[170:173], v[204:207], v[16:19]
	v_mfma_f32_16x16x32_bf16 v[4:7], v[162:165], v[216:219], v[4:7]
	v_mfma_f32_16x16x32_bf16 v[0:3], v[170:173], v[216:219], v[0:3]
	v_mfma_f32_16x16x32_bf16 v[48:51], v[162:165], v[178:181], v[68:71]
	v_mfma_f32_16x16x32_bf16 v[52:55], v[170:173], v[178:181], v[64:67]
	v_mfma_f32_16x16x32_bf16 v[36:39], v[166:169], v[200:203], v[36:39]
	v_mfma_f32_16x16x32_bf16 v[32:35], v[174:177], v[200:203], v[32:35]
	v_mfma_f32_16x16x32_bf16 v[20:23], v[166:169], v[208:211], v[20:23]
	v_mfma_f32_16x16x32_bf16 v[16:19], v[174:177], v[208:211], v[16:19]
	v_mfma_f32_16x16x32_bf16 v[4:7], v[166:169], v[220:223], v[4:7]
	v_mfma_f32_16x16x32_bf16 v[0:3], v[174:177], v[220:223], v[0:3]
	v_mfma_f32_16x16x32_bf16 v[48:51], v[166:169], v[182:185], v[48:51]
	v_mfma_f32_16x16x32_bf16 v[52:55], v[174:177], v[182:185], v[52:55]
	s_setprio 0
	s_barrier
	s_add_i32 s57, 0, 0x18000
	s_add_i32 s58, 0, 0x1c000
	v_add_u32_e32 v68, s57, v193
	v_add_u32_e32 v174, s58, v193
	ds_read_b128 v[56:59], v68
	ds_read_b128 v[60:63], v68 offset:1024
	ds_read_b128 v[64:67], v68 offset:2048
	ds_read_b128 v[68:71], v68 offset:3072
	ds_read_b128 v[162:165], v174
	ds_read_b128 v[166:169], v174 offset:1024
	ds_read_b128 v[170:173], v174 offset:2048
	ds_read_b128 v[174:177], v174 offset:3072
	s_add_u32 s8, s8, 0x40000
	s_addc_u32 s9, s9, 0
	s_mov_b32 m0, s65
	v_lshl_add_u64 v[228:229], s[8:9], 0, v[144:145]
	ds_read_b128 v[178:181], v198 offset:32768
	ds_read_b128 v[182:185], v198 offset:33792
	ds_read_b128 v[186:189], v198 offset:34816
	ds_read_b128 v[200:203], v198 offset:35840
	ds_read_b128 v[204:207], v198 offset:36864
	ds_read_b128 v[208:211], v198 offset:37888
	ds_read_b128 v[216:219], v198 offset:38912
	ds_read_b128 v[220:223], v198 offset:39936
	global_load_lds_dwordx4 v[228:229], off
	v_lshl_add_u64 v[228:229], s[8:9], 0, v[146:147]
	s_mov_b32 m0, s66
	s_nop 0
	global_load_lds_dwordx4 v[228:229], off
	s_waitcnt vmcnt(8)
	s_waitcnt lgkmcnt(0)
	s_barrier
	s_setprio 1
	s_waitcnt lgkmcnt(0)
	v_mfma_f32_16x16x32_bf16 v[140:143], v[56:59], v[178:181], v[140:143]
	v_mfma_f32_16x16x32_bf16 v[136:139], v[64:67], v[178:181], v[136:139]
	v_mfma_f32_16x16x32_bf16 v[124:127], v[56:59], v[186:189], v[124:127]
	v_mfma_f32_16x16x32_bf16 v[120:123], v[64:67], v[186:189], v[120:123]
	v_mfma_f32_16x16x32_bf16 v[108:111], v[56:59], v[204:207], v[108:111]
	v_mfma_f32_16x16x32_bf16 v[104:107], v[64:67], v[204:207], v[104:107]
	v_mfma_f32_16x16x32_bf16 v[92:95], v[56:59], v[216:219], v[92:95]
	v_mfma_f32_16x16x32_bf16 v[88:91], v[64:67], v[216:219], v[88:91]
	v_mfma_f32_16x16x32_bf16 v[140:143], v[60:63], v[182:185], v[140:143]
	v_mfma_f32_16x16x32_bf16 v[136:139], v[68:71], v[182:185], v[136:139]
	v_mfma_f32_16x16x32_bf16 v[124:127], v[60:63], v[200:203], v[124:127]
	v_mfma_f32_16x16x32_bf16 v[120:123], v[68:71], v[200:203], v[120:123]
	v_mfma_f32_16x16x32_bf16 v[108:111], v[60:63], v[208:211], v[108:111]
	v_mfma_f32_16x16x32_bf16 v[104:107], v[68:71], v[208:211], v[104:107]
	v_mfma_f32_16x16x32_bf16 v[92:95], v[60:63], v[220:223], v[92:95]
	v_mfma_f32_16x16x32_bf16 v[88:91], v[68:71], v[220:223], v[88:91]
	s_setprio 0
	s_setprio 1
	v_mfma_f32_16x16x32_bf16 v[132:135], v[162:165], v[178:181], v[132:135]
	v_mfma_f32_16x16x32_bf16 v[128:131], v[170:173], v[178:181], v[128:131]
	v_mfma_f32_16x16x32_bf16 v[116:119], v[162:165], v[186:189], v[116:119]
	v_mfma_f32_16x16x32_bf16 v[112:115], v[170:173], v[186:189], v[112:115]
	v_mfma_f32_16x16x32_bf16 v[100:103], v[162:165], v[204:207], v[100:103]
	v_mfma_f32_16x16x32_bf16 v[96:99], v[170:173], v[204:207], v[96:99]
	v_mfma_f32_16x16x32_bf16 v[84:87], v[162:165], v[216:219], v[84:87]
	v_mfma_f32_16x16x32_bf16 v[80:83], v[170:173], v[216:219], v[80:83]
	v_mfma_f32_16x16x32_bf16 v[132:135], v[166:169], v[182:185], v[132:135]
	v_mfma_f32_16x16x32_bf16 v[128:131], v[174:177], v[182:185], v[128:131]
	v_mfma_f32_16x16x32_bf16 v[116:119], v[166:169], v[200:203], v[116:119]
	v_mfma_f32_16x16x32_bf16 v[112:115], v[174:177], v[200:203], v[112:115]
	v_mfma_f32_16x16x32_bf16 v[100:103], v[166:169], v[208:211], v[100:103]
	v_mfma_f32_16x16x32_bf16 v[96:99], v[174:177], v[208:211], v[96:99]
	v_mfma_f32_16x16x32_bf16 v[84:87], v[166:169], v[220:223], v[84:87]
	v_mfma_f32_16x16x32_bf16 v[80:83], v[174:177], v[220:223], v[80:83]
	s_setprio 0
	s_barrier
	s_add_i32 s8, s57, s62
	v_lshl_add_u64 v[190:191], v[190:191], 0, s[20:21]
	s_mov_b32 m0, s8
	ds_read_b128 v[178:181], v198 offset:49152
	ds_read_b128 v[182:185], v198 offset:50176
	ds_read_b128 v[186:189], v198 offset:51200
	ds_read_b128 v[200:203], v198 offset:52224
	ds_read_b128 v[204:207], v198 offset:53248
	ds_read_b128 v[208:211], v198 offset:54272
	ds_read_b128 v[216:219], v198 offset:55296
	ds_read_b128 v[220:223], v198 offset:56320
	global_load_lds_dwordx4 v[190:191], off
	s_add_i32 m0, s8, 0x2000
	s_add_u32 s6, s6, 0x40080
	v_lshl_add_u64 v[190:191], v[212:213], 0, s[20:21]
	s_addc_u32 s7, s7, 0
	s_add_i32 s8, s58, s62
	global_load_lds_dwordx4 v[190:191], off
	v_lshl_add_u64 v[190:191], s[6:7], 0, v[144:145]
	s_mov_b32 m0, s8
	s_nop 0
	global_load_lds_dwordx4 v[190:191], off
	v_lshl_add_u64 v[190:191], s[6:7], 0, v[146:147]
	s_add_i32 m0, s8, 0x2000
	s_nop 0
	global_load_lds_dwordx4 v[190:191], off
	v_lshl_add_u64 v[190:191], v[224:225], 0, s[20:21]
	s_mov_b32 m0, s81
	s_nop 0
	global_load_lds_dwordx4 v[190:191], off
	v_lshl_add_u64 v[190:191], v[226:227], 0, s[20:21]
	s_mov_b32 m0, s82
	s_nop 0
	global_load_lds_dwordx4 v[190:191], off
	s_waitcnt vmcnt(8)
	s_waitcnt lgkmcnt(0)
	s_barrier
	s_setprio 1
	s_waitcnt lgkmcnt(0)
	v_mfma_f32_16x16x32_bf16 v[76:79], v[56:59], v[178:181], v[76:79]
	v_mfma_f32_16x16x32_bf16 v[72:75], v[64:67], v[178:181], v[72:75]
	v_mfma_f32_16x16x32_bf16 v[44:47], v[56:59], v[186:189], v[44:47]
	v_mfma_f32_16x16x32_bf16 v[40:43], v[64:67], v[186:189], v[40:43]
	v_mfma_f32_16x16x32_bf16 v[28:31], v[56:59], v[204:207], v[28:31]
	v_mfma_f32_16x16x32_bf16 v[24:27], v[64:67], v[204:207], v[24:27]
	v_mfma_f32_16x16x32_bf16 v[12:15], v[56:59], v[216:219], v[12:15]
	v_mfma_f32_16x16x32_bf16 v[8:11], v[64:67], v[216:219], v[8:11]
	v_mfma_f32_16x16x32_bf16 v[76:79], v[60:63], v[182:185], v[76:79]
	v_mfma_f32_16x16x32_bf16 v[72:75], v[68:71], v[182:185], v[72:75]
	v_mfma_f32_16x16x32_bf16 v[44:47], v[60:63], v[200:203], v[44:47]
	v_mfma_f32_16x16x32_bf16 v[40:43], v[68:71], v[200:203], v[40:43]
	v_mfma_f32_16x16x32_bf16 v[28:31], v[60:63], v[208:211], v[28:31]
	v_mfma_f32_16x16x32_bf16 v[24:27], v[68:71], v[208:211], v[24:27]
	v_mfma_f32_16x16x32_bf16 v[12:15], v[60:63], v[220:223], v[12:15]
	v_mfma_f32_16x16x32_bf16 v[8:11], v[68:71], v[220:223], v[8:11]
	s_setprio 0
	s_setprio 1
	v_mfma_f32_16x16x32_bf16 v[48:51], v[162:165], v[178:181], v[48:51]
	v_mfma_f32_16x16x32_bf16 v[68:71], v[166:169], v[182:185], v[48:51]
	v_mfma_f32_16x16x32_bf16 v[48:51], v[170:173], v[178:181], v[52:55]
	v_mfma_f32_16x16x32_bf16 v[36:39], v[162:165], v[186:189], v[36:39]
	v_mfma_f32_16x16x32_bf16 v[32:35], v[170:173], v[186:189], v[32:35]
	v_mfma_f32_16x16x32_bf16 v[20:23], v[162:165], v[204:207], v[20:23]
	v_mfma_f32_16x16x32_bf16 v[16:19], v[170:173], v[204:207], v[16:19]
	v_mfma_f32_16x16x32_bf16 v[4:7], v[162:165], v[216:219], v[4:7]
	v_mfma_f32_16x16x32_bf16 v[0:3], v[170:173], v[216:219], v[0:3]
	v_mfma_f32_16x16x32_bf16 v[64:67], v[174:177], v[182:185], v[48:51]
	v_mfma_f32_16x16x32_bf16 v[36:39], v[166:169], v[200:203], v[36:39]
	v_mfma_f32_16x16x32_bf16 v[32:35], v[174:177], v[200:203], v[32:35]
	v_mfma_f32_16x16x32_bf16 v[20:23], v[166:169], v[208:211], v[20:23]
	v_mfma_f32_16x16x32_bf16 v[16:19], v[174:177], v[208:211], v[16:19]
	v_mfma_f32_16x16x32_bf16 v[4:7], v[166:169], v[220:223], v[4:7]
	v_mfma_f32_16x16x32_bf16 v[0:3], v[174:177], v[220:223], v[0:3]
	s_setprio 0
	s_barrier
	s_add_i32 s56, s56, 2
	s_add_u32 s4, s4, 0x100
	s_addc_u32 s5, s5, 0
	s_add_u32 s54, s54, 0x100
	s_addc_u32 s55, s55, 0
	s_cmp_gt_u32 s56, 13
	s_cbranch_scc0 .LBB0_707
	v_mbcnt_lo_u32_b32 v238, -1, 0
	v_mbcnt_hi_u32_b32 v238, -1, v238
	v_bfe_u32 v238, v238, 4, 1
	v_mul_u32_u24_e32 v238, 24, v238
	v_mov_b32_e32 v239, 0
	s_and_b64 vcc, exec, s[22:23]
	s_cbranch_vccz .LBB0_710
	s_barrier

.LBB0_720:
	s_lshl_b32 s8, s10, 2
	s_and_b32 s8, s8, 12
	v_add_u32_e32 v128, 0xffff8000, v162
	v_cmp_gt_i32_e32 vcc, s83, v162
	v_mov_b32_e32 v130, s71
	v_mov_b32_e32 v131, s69
	s_or_b32 s8, s8, s80
	v_cndmask_b32_e32 v129, 0, v163, vcc
	v_cndmask_b32_e32 v128, v128, v162, vcc
	v_cndmask_b32_e32 v131, v130, v131, vcc
	v_mov_b32_e32 v130, s70
	v_mov_b32_e32 v132, s68
	v_lshl_or_b32 v134, s8, 6, v150
	v_cndmask_b32_e32 v130, v130, v132, vcc
	v_lshlrev_b64 v[128:129], 12, v[128:129]
	s_cmp_eq_u32 s11, 1
	v_lshl_add_u64 v[130:131], v[130:131], 0, v[128:129]
	v_lshlrev_b32_e32 v132, 2, v134
	v_mov_b32_e32 v133, v149
	v_lshl_add_u64 v[130:131], v[130:131], 0, v[132:133]
	s_cselect_b64 s[8:9], -1, 0
	v_cndmask_b32_e64 v183, 0, v130, s[8:9]
	v_cndmask_b32_e64 v188, 0, v131, s[8:9]
	v_mov_b32_e32 v130, s77
	v_mov_b32_e32 v131, s74
	s_and_b64 s[52:53], s[8:9], exec
	v_cndmask_b32_e32 v131, v130, v131, vcc
	v_mov_b32_e32 v130, s76
	v_mov_b32_e32 v189, s73
	s_cselect_b32 s10, s58, s56
	s_cselect_b32 s25, s59, s57
	s_and_b64 s[52:53], s[4:5], exec
	v_cndmask_b32_e32 v130, v130, v189, vcc
	s_cselect_b32 s53, s55, s25
	s_cselect_b32 s52, s54, s10
	s_cmp_eq_u32 s11, 2
	v_lshl_add_u64 v[128:129], v[130:131], 0, v[128:129]
	v_lshlrev_b32_e32 v134, 1, v134
	v_mov_b32_e32 v135, v149
	v_lshl_add_u64 v[128:129], v[128:129], 0, v[132:133]
	s_cselect_b64 s[10:11], -1, 0
	v_lshl_add_u64 v[134:135], s[52:53], 0, v[134:135]
	v_cndmask_b32_e64 v189, v188, v129, s[10:11]
	v_cndmask_b32_e64 v188, v183, v128, s[10:11]
	v_lshlrev_b64 v[128:129], 11, v[162:163]
	v_lshl_add_u64 v[190:191], v[134:135], 0, v[128:129]
	v_pk_mul_f32 v[128:129], v[184:185], v[182:183] op_sel_hi:[1,0]
	v_pk_mul_f32 v[184:185], v[186:187], v[182:183] op_sel_hi:[1,0]
	v_cmp_ne_u64_e32 vcc, 0, v[188:189]
	v_pk_mul_f32 v[130:131], v[62:63], v[128:129]
	v_pk_mul_f32 v[128:129], v[60:61], v[184:185]
	s_nop 0
	v_cvt_pk_bf16_f32 v232, v128, v129
	v_cvt_pk_bf16_f32 v233, v130, v131
	s_and_saveexec_b64 s[52:53], vcc
	s_cbranch_execz .LBB0_722
	global_store_dwordx4 v[188:189], v[128:131], off nt
.LBB0_722:
	s_or_b64 exec, exec, s[52:53]
	v_mov_b32_e32 v183, v182
	v_mov_b32_e32 v184, v182
	v_mov_b32_e32 v185, v182
	v_pk_mul_f32 v[128:129], v[178:179], v[184:185]
	v_pk_mul_f32 v[178:179], v[180:181], v[182:183]
	v_pk_mul_f32 v[130:131], v[54:55], v[128:129]
	v_pk_mul_f32 v[128:129], v[52:53], v[178:179]
	s_nop 0
	v_cvt_pk_bf16_f32 v234, v128, v129
	v_cvt_pk_bf16_f32 v235, v130, v131
	s_nop 1
	v_permlane16_swap_b32_e32 v232, v234
	v_permlane16_swap_b32_e32 v233, v235
	v_lshl_add_u64 v[236:237], v[190:191], 0, v[238:239]
	flat_store_dwordx4 v[236:237], v[232:235]
	s_nop 1
	s_and_saveexec_b64 s[52:53], vcc
	s_cbranch_execz .LBB0_724
	global_store_dwordx4 v[188:189], v[128:131], off offset:64 nt
.LBB0_724:
	s_or_b64 exec, exec, s[52:53]
	s_nop 0
	v_pk_mul_f32 v[128:129], v[140:141], v[184:185]
	v_pk_mul_f32 v[140:141], v[142:143], v[182:183]
	v_pk_mul_f32 v[130:131], v[58:59], v[128:129]
	v_pk_mul_f32 v[128:129], v[56:57], v[140:141]
	s_nop 0
	v_cvt_pk_bf16_f32 v232, v128, v129
	v_cvt_pk_bf16_f32 v233, v130, v131
	s_and_saveexec_b64 s[52:53], vcc
	s_cbranch_execz .LBB0_726
	global_store_dwordx4 v[188:189], v[128:131], off offset:128 nt
.LBB0_726:
	s_or_b64 exec, exec, s[52:53]
	s_nop 0
	v_mov_b32_e32 v128, v182
	v_mov_b32_e32 v129, v182
	v_pk_mul_f32 v[128:129], v[136:137], v[128:129]
	v_pk_mul_f32 v[136:137], v[138:139], v[182:183]
	v_pk_mul_f32 v[130:131], v[50:51], v[128:129]
	v_pk_mul_f32 v[128:129], v[48:49], v[136:137]
	s_nop 0
	v_cvt_pk_bf16_f32 v234, v128, v129
	v_cvt_pk_bf16_f32 v235, v130, v131
	s_nop 1
	v_permlane16_swap_b32_e32 v232, v234
	v_permlane16_swap_b32_e32 v233, v235
	v_lshl_add_u64 v[236:237], v[190:191], 0, v[238:239]
	flat_store_dwordx4 v[236:237], v[232:235] offset:64
	s_nop 1
	s_and_saveexec_b64 s[52:53], vcc
	s_cbranch_execz .LBB0_728
	global_store_dwordx4 v[188:189], v[128:131], off offset:192 nt

.LBB0_730:
	v_add_u32_e32 v112, 0xffff8010, v162
	v_cmp_gt_i32_e32 vcc, s83, v176
	v_mov_b32_e32 v114, s71
	v_mov_b32_e32 v115, s69
	v_cndmask_b32_e32 v113, 0, v177, vcc
	v_cndmask_b32_e32 v112, v112, v176, vcc
	v_cndmask_b32_e32 v115, v114, v115, vcc
	v_mov_b32_e32 v114, s70
	v_mov_b32_e32 v129, s68
	v_cndmask_b32_e32 v114, v114, v129, vcc
	v_lshlrev_b64 v[112:113], 12, v[112:113]
	v_lshl_add_u64 v[114:115], v[114:115], 0, v[112:113]
	v_mov_b32_e32 v133, v149
	v_lshl_add_u64 v[114:115], v[114:115], 0, v[132:133]
	v_cndmask_b32_e64 v129, 0, v114, s[8:9]
	v_cndmask_b32_e64 v130, 0, v115, s[8:9]
	v_mov_b32_e32 v114, s77
	v_mov_b32_e32 v115, s74
	v_cndmask_b32_e32 v115, v114, v115, vcc
	v_mov_b32_e32 v114, s76
	v_mov_b32_e32 v131, s73
	v_cndmask_b32_e32 v114, v114, v131, vcc
	v_lshl_add_u64 v[112:113], v[114:115], 0, v[112:113]
	v_lshl_add_u64 v[112:113], v[112:113], 0, v[132:133]
	v_cndmask_b32_e64 v131, v130, v113, s[10:11]
	v_cndmask_b32_e64 v130, v129, v112, s[10:11]
	v_lshlrev_b64 v[112:113], 11, v[176:177]
	v_lshl_add_u64 v[140:141], v[134:135], 0, v[112:113]
	v_pk_mul_f32 v[112:113], v[136:137], v[128:129] op_sel_hi:[1,0]
	v_pk_mul_f32 v[136:137], v[138:139], v[128:129] op_sel_hi:[1,0]
	v_cmp_ne_u64_e32 vcc, 0, v[130:131]
	v_pk_mul_f32 v[114:115], v[62:63], v[112:113]
	v_pk_mul_f32 v[112:113], v[60:61], v[136:137]
	s_nop 0
	v_cvt_pk_bf16_f32 v232, v112, v113
	v_cvt_pk_bf16_f32 v233, v114, v115
	s_and_saveexec_b64 s[52:53], vcc
	s_cbranch_execz .LBB0_732
	global_store_dwordx4 v[130:131], v[112:115], off nt
.LBB0_732:
	s_or_b64 exec, exec, s[52:53]
	v_mov_b32_e32 v129, v128
	v_mov_b32_e32 v136, v128
	v_mov_b32_e32 v137, v128
	v_pk_mul_f32 v[112:113], v[124:125], v[136:137]
	v_pk_mul_f32 v[124:125], v[126:127], v[128:129]
	v_pk_mul_f32 v[114:115], v[54:55], v[112:113]
	v_pk_mul_f32 v[112:113], v[52:53], v[124:125]
	s_nop 0
	v_cvt_pk_bf16_f32 v234, v112, v113
	v_cvt_pk_bf16_f32 v235, v114, v115
	s_nop 1
	v_permlane16_swap_b32_e32 v232, v234
	v_permlane16_swap_b32_e32 v233, v235
	v_lshl_add_u64 v[236:237], v[140:141], 0, v[238:239]
	flat_store_dwordx4 v[236:237], v[232:235]
	s_nop 1
	s_and_saveexec_b64 s[52:53], vcc
	s_cbranch_execz .LBB0_734
	global_store_dwordx4 v[130:131], v[112:115], off offset:64 nt
.LBB0_734:
	s_or_b64 exec, exec, s[52:53]
	s_nop 0
	v_pk_mul_f32 v[112:113], v[120:121], v[136:137]
	v_pk_mul_f32 v[120:121], v[122:123], v[128:129]
	v_pk_mul_f32 v[114:115], v[58:59], v[112:113]
	v_pk_mul_f32 v[112:113], v[56:57], v[120:121]
	s_nop 0
	v_cvt_pk_bf16_f32 v232, v112, v113
	v_cvt_pk_bf16_f32 v233, v114, v115
	s_and_saveexec_b64 s[52:53], vcc
	s_cbranch_execz .LBB0_736
	global_store_dwordx4 v[130:131], v[112:115], off offset:128 nt
.LBB0_736:
	s_or_b64 exec, exec, s[52:53]
	s_nop 0
	v_mov_b32_e32 v112, v128
	v_mov_b32_e32 v113, v128
	v_pk_mul_f32 v[112:113], v[116:117], v[112:113]
	v_pk_mul_f32 v[116:117], v[118:119], v[128:129]
	v_pk_mul_f32 v[114:115], v[50:51], v[112:113]
	v_pk_mul_f32 v[112:113], v[48:49], v[116:117]
	s_nop 0
	v_cvt_pk_bf16_f32 v234, v112, v113
	v_cvt_pk_bf16_f32 v235, v114, v115
	s_nop 1
	v_permlane16_swap_b32_e32 v232, v234
	v_permlane16_swap_b32_e32 v233, v235
	v_lshl_add_u64 v[236:237], v[140:141], 0, v[238:239]
	flat_store_dwordx4 v[236:237], v[232:235] offset:64
	s_nop 1
	s_and_saveexec_b64 s[52:53], vcc
	s_cbranch_execz .LBB0_738
	global_store_dwordx4 v[130:131], v[112:115], off offset:192 nt

.LBB0_740:
	v_add_u32_e32 v96, 0xffff8020, v162
	v_cmp_gt_i32_e32 vcc, s83, v174
	v_mov_b32_e32 v98, s71
	v_mov_b32_e32 v99, s69
	v_cndmask_b32_e32 v97, 0, v175, vcc
	v_cndmask_b32_e32 v96, v96, v174, vcc
	v_cndmask_b32_e32 v99, v98, v99, vcc
	v_mov_b32_e32 v98, s70
	v_mov_b32_e32 v113, s68
	v_cndmask_b32_e32 v98, v98, v113, vcc
	v_lshlrev_b64 v[96:97], 12, v[96:97]
	v_lshl_add_u64 v[98:99], v[98:99], 0, v[96:97]
	v_mov_b32_e32 v133, v149
	v_lshl_add_u64 v[98:99], v[98:99], 0, v[132:133]
	v_cndmask_b32_e64 v113, 0, v98, s[8:9]
	v_cndmask_b32_e64 v114, 0, v99, s[8:9]
	v_mov_b32_e32 v98, s77
	v_mov_b32_e32 v99, s74
	v_cndmask_b32_e32 v99, v98, v99, vcc
	v_mov_b32_e32 v98, s76
	v_mov_b32_e32 v115, s73
	v_cndmask_b32_e32 v98, v98, v115, vcc
	v_lshl_add_u64 v[96:97], v[98:99], 0, v[96:97]
	v_lshl_add_u64 v[96:97], v[96:97], 0, v[132:133]
	v_cndmask_b32_e64 v115, v114, v97, s[10:11]
	v_cndmask_b32_e64 v114, v113, v96, s[10:11]
	v_lshlrev_b64 v[96:97], 11, v[174:175]
	v_lshl_add_u64 v[120:121], v[134:135], 0, v[96:97]
	v_pk_mul_f32 v[96:97], v[116:117], v[112:113] op_sel_hi:[1,0]
	v_pk_mul_f32 v[116:117], v[118:119], v[112:113] op_sel_hi:[1,0]
	v_cmp_ne_u64_e32 vcc, 0, v[114:115]
	v_pk_mul_f32 v[98:99], v[62:63], v[96:97]
	v_pk_mul_f32 v[96:97], v[60:61], v[116:117]
	s_nop 0
	v_cvt_pk_bf16_f32 v232, v96, v97
	v_cvt_pk_bf16_f32 v233, v98, v99
	s_and_saveexec_b64 s[52:53], vcc
	s_cbranch_execz .LBB0_742
	global_store_dwordx4 v[114:115], v[96:99], off nt
.LBB0_742:
	s_or_b64 exec, exec, s[52:53]
	v_mov_b32_e32 v113, v112
	v_mov_b32_e32 v116, v112
	v_mov_b32_e32 v117, v112
	v_pk_mul_f32 v[96:97], v[108:109], v[116:117]
	v_pk_mul_f32 v[108:109], v[110:111], v[112:113]
	v_pk_mul_f32 v[98:99], v[54:55], v[96:97]
	v_pk_mul_f32 v[96:97], v[52:53], v[108:109]
	s_nop 0
	v_cvt_pk_bf16_f32 v234, v96, v97
	v_cvt_pk_bf16_f32 v235, v98, v99
	s_nop 1
	v_permlane16_swap_b32_e32 v232, v234
	v_permlane16_swap_b32_e32 v233, v235
	v_lshl_add_u64 v[236:237], v[120:121], 0, v[238:239]
	flat_store_dwordx4 v[236:237], v[232:235]
	s_nop 1
	s_and_saveexec_b64 s[52:53], vcc
	s_cbranch_execz .LBB0_744
	global_store_dwordx4 v[114:115], v[96:99], off offset:64 nt
.LBB0_744:
	s_or_b64 exec, exec, s[52:53]
	s_nop 0
	v_pk_mul_f32 v[96:97], v[104:105], v[116:117]
	v_pk_mul_f32 v[104:105], v[106:107], v[112:113]
	v_pk_mul_f32 v[98:99], v[58:59], v[96:97]
	v_pk_mul_f32 v[96:97], v[56:57], v[104:105]
	s_nop 0
	v_cvt_pk_bf16_f32 v232, v96, v97
	v_cvt_pk_bf16_f32 v233, v98, v99
	s_and_saveexec_b64 s[52:53], vcc
	s_cbranch_execz .LBB0_746
	global_store_dwordx4 v[114:115], v[96:99], off offset:128 nt
.LBB0_746:
	s_or_b64 exec, exec, s[52:53]
	s_nop 0
	v_mov_b32_e32 v96, v112
	v_mov_b32_e32 v97, v112
	v_pk_mul_f32 v[96:97], v[100:101], v[96:97]
	v_pk_mul_f32 v[100:101], v[102:103], v[112:113]
	v_pk_mul_f32 v[98:99], v[50:51], v[96:97]
	v_pk_mul_f32 v[96:97], v[48:49], v[100:101]
	s_nop 0
	v_cvt_pk_bf16_f32 v234, v96, v97
	v_cvt_pk_bf16_f32 v235, v98, v99
	s_nop 1
	v_permlane16_swap_b32_e32 v232, v234
	v_permlane16_swap_b32_e32 v233, v235
	v_lshl_add_u64 v[236:237], v[120:121], 0, v[238:239]
	flat_store_dwordx4 v[236:237], v[232:235] offset:64
	s_nop 1
	s_and_saveexec_b64 s[52:53], vcc
	s_cbranch_execz .LBB0_748
	global_store_dwordx4 v[114:115], v[96:99], off offset:192 nt

.LBB0_750:
	v_add_u32_e32 v80, 0xffff8030, v162
	v_cmp_gt_i32_e32 vcc, s83, v172
	v_mov_b32_e32 v82, s71
	v_mov_b32_e32 v83, s69
	v_cndmask_b32_e32 v81, 0, v173, vcc
	v_cndmask_b32_e32 v80, v80, v172, vcc
	v_cndmask_b32_e32 v83, v82, v83, vcc
	v_mov_b32_e32 v82, s70
	v_mov_b32_e32 v97, s68
	v_cndmask_b32_e32 v82, v82, v97, vcc
	v_lshlrev_b64 v[80:81], 12, v[80:81]
	v_lshl_add_u64 v[82:83], v[82:83], 0, v[80:81]
	v_mov_b32_e32 v133, v149
	v_lshl_add_u64 v[82:83], v[82:83], 0, v[132:133]
	v_cndmask_b32_e64 v97, 0, v82, s[8:9]
	v_cndmask_b32_e64 v98, 0, v83, s[8:9]
	v_mov_b32_e32 v82, s77
	v_mov_b32_e32 v83, s74
	v_cndmask_b32_e32 v83, v82, v83, vcc
	v_mov_b32_e32 v82, s76
	v_mov_b32_e32 v99, s73
	v_cndmask_b32_e32 v82, v82, v99, vcc
	v_lshl_add_u64 v[80:81], v[82:83], 0, v[80:81]
	v_lshl_add_u64 v[80:81], v[80:81], 0, v[132:133]
	v_cndmask_b32_e64 v99, v98, v81, s[10:11]
	v_cndmask_b32_e64 v98, v97, v80, s[10:11]
	v_lshlrev_b64 v[80:81], 11, v[172:173]
	v_lshl_add_u64 v[104:105], v[134:135], 0, v[80:81]
	v_pk_mul_f32 v[80:81], v[100:101], v[96:97] op_sel_hi:[1,0]
	v_pk_mul_f32 v[100:101], v[102:103], v[96:97] op_sel_hi:[1,0]
	v_cmp_ne_u64_e32 vcc, 0, v[98:99]
	v_pk_mul_f32 v[82:83], v[62:63], v[80:81]
	v_pk_mul_f32 v[80:81], v[60:61], v[100:101]
	s_nop 0
	v_cvt_pk_bf16_f32 v232, v80, v81
	v_cvt_pk_bf16_f32 v233, v82, v83
	s_and_saveexec_b64 s[52:53], vcc
	s_cbranch_execz .LBB0_752
	global_store_dwordx4 v[98:99], v[80:83], off nt
.LBB0_752:
	s_or_b64 exec, exec, s[52:53]
	v_mov_b32_e32 v97, v96
	v_mov_b32_e32 v100, v96
	v_mov_b32_e32 v101, v96
	v_pk_mul_f32 v[80:81], v[92:93], v[100:101]
	v_pk_mul_f32 v[92:93], v[94:95], v[96:97]
	v_pk_mul_f32 v[82:83], v[54:55], v[80:81]
	v_pk_mul_f32 v[80:81], v[52:53], v[92:93]
	s_nop 0
	v_cvt_pk_bf16_f32 v234, v80, v81
	v_cvt_pk_bf16_f32 v235, v82, v83
	s_nop 1
	v_permlane16_swap_b32_e32 v232, v234
	v_permlane16_swap_b32_e32 v233, v235
	v_lshl_add_u64 v[236:237], v[104:105], 0, v[238:239]
	flat_store_dwordx4 v[236:237], v[232:235]
	s_nop 1
	s_and_saveexec_b64 s[52:53], vcc
	s_cbranch_execz .LBB0_754
	global_store_dwordx4 v[98:99], v[80:83], off offset:64 nt
.LBB0_754:
	s_or_b64 exec, exec, s[52:53]
	s_nop 0
	v_pk_mul_f32 v[80:81], v[88:89], v[100:101]
	v_pk_mul_f32 v[88:89], v[90:91], v[96:97]
	v_pk_mul_f32 v[82:83], v[58:59], v[80:81]
	v_pk_mul_f32 v[80:81], v[56:57], v[88:89]
	s_nop 0
	v_cvt_pk_bf16_f32 v232, v80, v81
	v_cvt_pk_bf16_f32 v233, v82, v83
	s_and_saveexec_b64 s[52:53], vcc
	s_cbranch_execz .LBB0_756
	global_store_dwordx4 v[98:99], v[80:83], off offset:128 nt
.LBB0_756:
	s_or_b64 exec, exec, s[52:53]
	s_nop 0
	v_mov_b32_e32 v80, v96
	v_mov_b32_e32 v81, v96
	v_pk_mul_f32 v[80:81], v[84:85], v[80:81]
	v_pk_mul_f32 v[84:85], v[86:87], v[96:97]
	v_pk_mul_f32 v[82:83], v[50:51], v[80:81]
	v_pk_mul_f32 v[80:81], v[48:49], v[84:85]
	s_nop 0
	v_cvt_pk_bf16_f32 v234, v80, v81
	v_cvt_pk_bf16_f32 v235, v82, v83
	s_nop 1
	v_permlane16_swap_b32_e32 v232, v234
	v_permlane16_swap_b32_e32 v233, v235
	v_lshl_add_u64 v[236:237], v[104:105], 0, v[238:239]
	flat_store_dwordx4 v[236:237], v[232:235] offset:64
	s_nop 1
	s_and_saveexec_b64 s[52:53], vcc
	s_cbranch_execz .LBB0_758
	global_store_dwordx4 v[98:99], v[80:83], off offset:192 nt

.LBB0_760:
	v_add_u32_e32 v64, 0xffff8080, v162
	v_cmp_gt_i32_e32 vcc, s83, v170
	v_mov_b32_e32 v66, s71
	v_mov_b32_e32 v67, s69
	v_cndmask_b32_e32 v65, 0, v171, vcc
	v_cndmask_b32_e32 v64, v64, v170, vcc
	v_cndmask_b32_e32 v67, v66, v67, vcc
	v_mov_b32_e32 v66, s70
	v_mov_b32_e32 v81, s68
	v_cndmask_b32_e32 v66, v66, v81, vcc
	v_lshlrev_b64 v[64:65], 12, v[64:65]
	v_lshl_add_u64 v[66:67], v[66:67], 0, v[64:65]
	v_mov_b32_e32 v133, v149
	v_lshl_add_u64 v[66:67], v[66:67], 0, v[132:133]
	v_cndmask_b32_e64 v81, 0, v66, s[8:9]
	v_cndmask_b32_e64 v82, 0, v67, s[8:9]
	v_mov_b32_e32 v66, s77
	v_mov_b32_e32 v67, s74
	v_cndmask_b32_e32 v67, v66, v67, vcc
	v_mov_b32_e32 v66, s76
	v_mov_b32_e32 v83, s73
	v_cndmask_b32_e32 v66, v66, v83, vcc
	v_lshl_add_u64 v[64:65], v[66:67], 0, v[64:65]
	v_lshl_add_u64 v[64:65], v[64:65], 0, v[132:133]
	v_cndmask_b32_e64 v83, v82, v65, s[10:11]
	v_cndmask_b32_e64 v82, v81, v64, s[10:11]
	v_lshlrev_b64 v[64:65], 11, v[170:171]
	v_lshl_add_u64 v[88:89], v[134:135], 0, v[64:65]
	v_pk_mul_f32 v[64:65], v[84:85], v[80:81] op_sel_hi:[1,0]
	v_pk_mul_f32 v[84:85], v[86:87], v[80:81] op_sel_hi:[1,0]
	v_cmp_ne_u64_e32 vcc, 0, v[82:83]
	v_pk_mul_f32 v[66:67], v[62:63], v[64:65]
	v_pk_mul_f32 v[64:65], v[60:61], v[84:85]
	s_nop 0
	v_cvt_pk_bf16_f32 v232, v64, v65
	v_cvt_pk_bf16_f32 v233, v66, v67
	s_and_saveexec_b64 s[52:53], vcc
	s_cbranch_execz .LBB0_762
	global_store_dwordx4 v[82:83], v[64:67], off nt
.LBB0_762:
	s_or_b64 exec, exec, s[52:53]
	v_mov_b32_e32 v81, v80
	v_mov_b32_e32 v84, v80
	v_mov_b32_e32 v85, v80
	v_pk_mul_f32 v[64:65], v[76:77], v[84:85]
	v_pk_mul_f32 v[76:77], v[78:79], v[80:81]
	v_pk_mul_f32 v[66:67], v[54:55], v[64:65]
	v_pk_mul_f32 v[64:65], v[52:53], v[76:77]
	s_nop 0
	v_cvt_pk_bf16_f32 v234, v64, v65
	v_cvt_pk_bf16_f32 v235, v66, v67
	s_nop 1
	v_permlane16_swap_b32_e32 v232, v234
	v_permlane16_swap_b32_e32 v233, v235
	v_lshl_add_u64 v[236:237], v[88:89], 0, v[238:239]
	flat_store_dwordx4 v[236:237], v[232:235]
	s_nop 1
	s_and_saveexec_b64 s[52:53], vcc
	s_cbranch_execz .LBB0_764
	global_store_dwordx4 v[82:83], v[64:67], off offset:64 nt
.LBB0_764:
	s_or_b64 exec, exec, s[52:53]
	s_nop 0
	v_pk_mul_f32 v[64:65], v[72:73], v[84:85]
	v_pk_mul_f32 v[72:73], v[74:75], v[80:81]
	v_pk_mul_f32 v[66:67], v[58:59], v[64:65]
	v_pk_mul_f32 v[64:65], v[56:57], v[72:73]
	s_nop 0
	v_cvt_pk_bf16_f32 v232, v64, v65
	v_cvt_pk_bf16_f32 v233, v66, v67
	s_and_saveexec_b64 s[52:53], vcc
	s_cbranch_execz .LBB0_766
	global_store_dwordx4 v[82:83], v[64:67], off offset:128 nt
.LBB0_766:
	s_or_b64 exec, exec, s[52:53]
	s_nop 0
	v_mov_b32_e32 v64, v80
	v_mov_b32_e32 v65, v80
	v_pk_mul_f32 v[64:65], v[68:69], v[64:65]
	v_pk_mul_f32 v[68:69], v[70:71], v[80:81]
	v_pk_mul_f32 v[66:67], v[50:51], v[64:65]
	v_pk_mul_f32 v[64:65], v[48:49], v[68:69]
	s_nop 0
	v_cvt_pk_bf16_f32 v234, v64, v65
	v_cvt_pk_bf16_f32 v235, v66, v67
	s_nop 1
	v_permlane16_swap_b32_e32 v232, v234
	v_permlane16_swap_b32_e32 v233, v235
	v_lshl_add_u64 v[236:237], v[88:89], 0, v[238:239]
	flat_store_dwordx4 v[236:237], v[232:235] offset:64
	s_nop 1
	s_and_saveexec_b64 s[52:53], vcc
	s_cbranch_execz .LBB0_768
	global_store_dwordx4 v[82:83], v[64:67], off offset:192 nt

.LBB0_770:
	v_add_u32_e32 v32, 0xffff8090, v162
	v_cmp_gt_i32_e32 vcc, s83, v168
	v_mov_b32_e32 v34, s71
	v_mov_b32_e32 v35, s69
	v_cndmask_b32_e32 v33, 0, v169, vcc
	v_cndmask_b32_e32 v32, v32, v168, vcc
	v_cndmask_b32_e32 v35, v34, v35, vcc
	v_mov_b32_e32 v34, s70
	v_mov_b32_e32 v65, s68
	v_cndmask_b32_e32 v34, v34, v65, vcc
	v_lshlrev_b64 v[32:33], 12, v[32:33]
	v_lshl_add_u64 v[34:35], v[34:35], 0, v[32:33]
	v_mov_b32_e32 v133, v149
	v_lshl_add_u64 v[34:35], v[34:35], 0, v[132:133]
	v_cndmask_b32_e64 v65, 0, v34, s[8:9]
	v_cndmask_b32_e64 v66, 0, v35, s[8:9]
	v_mov_b32_e32 v34, s77
	v_mov_b32_e32 v35, s74
	v_cndmask_b32_e32 v35, v34, v35, vcc
	v_mov_b32_e32 v34, s76
	v_mov_b32_e32 v67, s73
	v_cndmask_b32_e32 v34, v34, v67, vcc
	v_lshl_add_u64 v[32:33], v[34:35], 0, v[32:33]
	v_lshl_add_u64 v[32:33], v[32:33], 0, v[132:133]
	v_cndmask_b32_e64 v67, v66, v33, s[10:11]
	v_cndmask_b32_e64 v66, v65, v32, s[10:11]
	v_lshlrev_b64 v[32:33], 11, v[168:169]
	v_lshl_add_u64 v[72:73], v[134:135], 0, v[32:33]
	v_pk_mul_f32 v[32:33], v[68:69], v[64:65] op_sel_hi:[1,0]
	v_pk_mul_f32 v[68:69], v[70:71], v[64:65] op_sel_hi:[1,0]
	v_cmp_ne_u64_e32 vcc, 0, v[66:67]
	v_pk_mul_f32 v[34:35], v[62:63], v[32:33]
	v_pk_mul_f32 v[32:33], v[60:61], v[68:69]
	s_nop 0
	v_cvt_pk_bf16_f32 v232, v32, v33
	v_cvt_pk_bf16_f32 v233, v34, v35
	s_and_saveexec_b64 s[52:53], vcc
	s_cbranch_execz .LBB0_772
	global_store_dwordx4 v[66:67], v[32:35], off nt
.LBB0_772:
	s_or_b64 exec, exec, s[52:53]
	v_mov_b32_e32 v65, v64
	v_mov_b32_e32 v68, v64
	v_mov_b32_e32 v69, v64
	v_pk_mul_f32 v[32:33], v[44:45], v[68:69]
	v_pk_mul_f32 v[44:45], v[46:47], v[64:65]
	v_pk_mul_f32 v[34:35], v[54:55], v[32:33]
	v_pk_mul_f32 v[32:33], v[52:53], v[44:45]
	s_nop 0
	v_cvt_pk_bf16_f32 v234, v32, v33
	v_cvt_pk_bf16_f32 v235, v34, v35
	s_nop 1
	v_permlane16_swap_b32_e32 v232, v234
	v_permlane16_swap_b32_e32 v233, v235
	v_lshl_add_u64 v[236:237], v[72:73], 0, v[238:239]
	flat_store_dwordx4 v[236:237], v[232:235]
	s_nop 1
	s_and_saveexec_b64 s[52:53], vcc
	s_cbranch_execz .LBB0_774
	global_store_dwordx4 v[66:67], v[32:35], off offset:64 nt
.LBB0_774:
	s_or_b64 exec, exec, s[52:53]
	s_nop 0
	v_pk_mul_f32 v[32:33], v[40:41], v[68:69]
	v_pk_mul_f32 v[40:41], v[42:43], v[64:65]
	v_pk_mul_f32 v[34:35], v[58:59], v[32:33]
	v_pk_mul_f32 v[32:33], v[56:57], v[40:41]
	s_nop 0
	v_cvt_pk_bf16_f32 v232, v32, v33
	v_cvt_pk_bf16_f32 v233, v34, v35
	s_and_saveexec_b64 s[52:53], vcc
	s_cbranch_execz .LBB0_776
	global_store_dwordx4 v[66:67], v[32:35], off offset:128 nt
.LBB0_776:
	s_or_b64 exec, exec, s[52:53]
	s_nop 0
	v_mov_b32_e32 v32, v64
	v_mov_b32_e32 v33, v64
	v_pk_mul_f32 v[32:33], v[36:37], v[32:33]
	v_pk_mul_f32 v[36:37], v[38:39], v[64:65]
	v_pk_mul_f32 v[34:35], v[50:51], v[32:33]
	v_pk_mul_f32 v[32:33], v[48:49], v[36:37]
	s_nop 0
	v_cvt_pk_bf16_f32 v234, v32, v33
	v_cvt_pk_bf16_f32 v235, v34, v35
	s_nop 1
	v_permlane16_swap_b32_e32 v232, v234
	v_permlane16_swap_b32_e32 v233, v235
	v_lshl_add_u64 v[236:237], v[72:73], 0, v[238:239]
	flat_store_dwordx4 v[236:237], v[232:235] offset:64
	s_nop 1
	s_and_saveexec_b64 s[52:53], vcc
	s_cbranch_execz .LBB0_778
	global_store_dwordx4 v[66:67], v[32:35], off offset:192 nt

.LBB0_780:
	v_add_u32_e32 v16, 0xffff80a0, v162
	v_cmp_gt_i32_e32 vcc, s83, v166
	v_mov_b32_e32 v18, s71
	v_mov_b32_e32 v19, s69
	v_cndmask_b32_e32 v17, 0, v167, vcc
	v_cndmask_b32_e32 v16, v16, v166, vcc
	v_cndmask_b32_e32 v19, v18, v19, vcc
	v_mov_b32_e32 v18, s70
	v_mov_b32_e32 v33, s68
	v_cndmask_b32_e32 v18, v18, v33, vcc
	v_lshlrev_b64 v[16:17], 12, v[16:17]
	v_lshl_add_u64 v[18:19], v[18:19], 0, v[16:17]
	v_mov_b32_e32 v133, v149
	v_lshl_add_u64 v[18:19], v[18:19], 0, v[132:133]
	v_cndmask_b32_e64 v33, 0, v18, s[8:9]
	v_cndmask_b32_e64 v34, 0, v19, s[8:9]
	v_mov_b32_e32 v18, s77
	v_mov_b32_e32 v19, s74
	v_cndmask_b32_e32 v19, v18, v19, vcc
	v_mov_b32_e32 v18, s76
	v_mov_b32_e32 v35, s73
	v_cndmask_b32_e32 v18, v18, v35, vcc
	v_lshl_add_u64 v[16:17], v[18:19], 0, v[16:17]
	v_lshl_add_u64 v[16:17], v[16:17], 0, v[132:133]
	v_cndmask_b32_e64 v35, v34, v17, s[10:11]
	v_cndmask_b32_e64 v34, v33, v16, s[10:11]
	v_lshlrev_b64 v[16:17], 11, v[166:167]
	v_lshl_add_u64 v[40:41], v[134:135], 0, v[16:17]
	v_pk_mul_f32 v[16:17], v[36:37], v[32:33] op_sel_hi:[1,0]
	v_pk_mul_f32 v[36:37], v[38:39], v[32:33] op_sel_hi:[1,0]
	v_cmp_ne_u64_e32 vcc, 0, v[34:35]
	v_pk_mul_f32 v[18:19], v[62:63], v[16:17]
	v_pk_mul_f32 v[16:17], v[60:61], v[36:37]
	s_nop 0
	v_cvt_pk_bf16_f32 v232, v16, v17
	v_cvt_pk_bf16_f32 v233, v18, v19
	s_and_saveexec_b64 s[52:53], vcc
	s_cbranch_execz .LBB0_782
	global_store_dwordx4 v[34:35], v[16:19], off nt
.LBB0_782:
	s_or_b64 exec, exec, s[52:53]
	v_mov_b32_e32 v33, v32
	v_mov_b32_e32 v36, v32
	v_mov_b32_e32 v37, v32
	v_pk_mul_f32 v[16:17], v[28:29], v[36:37]
	v_pk_mul_f32 v[28:29], v[30:31], v[32:33]
	v_pk_mul_f32 v[18:19], v[54:55], v[16:17]
	v_pk_mul_f32 v[16:17], v[52:53], v[28:29]
	s_nop 0
	v_cvt_pk_bf16_f32 v234, v16, v17
	v_cvt_pk_bf16_f32 v235, v18, v19
	s_nop 1
	v_permlane16_swap_b32_e32 v232, v234
	v_permlane16_swap_b32_e32 v233, v235
	v_lshl_add_u64 v[236:237], v[40:41], 0, v[238:239]
	flat_store_dwordx4 v[236:237], v[232:235]
	s_nop 1
	s_and_saveexec_b64 s[52:53], vcc
	s_cbranch_execz .LBB0_784
	global_store_dwordx4 v[34:35], v[16:19], off offset:64 nt
.LBB0_784:
	s_or_b64 exec, exec, s[52:53]
	s_nop 0
	v_pk_mul_f32 v[16:17], v[24:25], v[36:37]
	v_pk_mul_f32 v[24:25], v[26:27], v[32:33]
	v_pk_mul_f32 v[18:19], v[58:59], v[16:17]
	v_pk_mul_f32 v[16:17], v[56:57], v[24:25]
	s_nop 0
	v_cvt_pk_bf16_f32 v232, v16, v17
	v_cvt_pk_bf16_f32 v233, v18, v19
	s_and_saveexec_b64 s[52:53], vcc
	s_cbranch_execz .LBB0_786
	global_store_dwordx4 v[34:35], v[16:19], off offset:128 nt
.LBB0_786:
	s_or_b64 exec, exec, s[52:53]
	s_nop 0
	v_mov_b32_e32 v16, v32
	v_mov_b32_e32 v17, v32
	v_pk_mul_f32 v[16:17], v[20:21], v[16:17]
	v_pk_mul_f32 v[20:21], v[22:23], v[32:33]
	v_pk_mul_f32 v[18:19], v[50:51], v[16:17]
	v_pk_mul_f32 v[16:17], v[48:49], v[20:21]
	s_nop 0
	v_cvt_pk_bf16_f32 v234, v16, v17
	v_cvt_pk_bf16_f32 v235, v18, v19
	s_nop 1
	v_permlane16_swap_b32_e32 v232, v234
	v_permlane16_swap_b32_e32 v233, v235
	v_lshl_add_u64 v[236:237], v[40:41], 0, v[238:239]
	flat_store_dwordx4 v[236:237], v[232:235] offset:64
	s_nop 1
	s_and_saveexec_b64 s[52:53], vcc
	s_cbranch_execz .LBB0_788
	global_store_dwordx4 v[34:35], v[16:19], off offset:192 nt

.LBB0_790:
	v_add_u32_e32 v0, 0xffff80b0, v162
	v_cmp_gt_i32_e32 vcc, s83, v164
	v_mov_b32_e32 v2, s71
	v_mov_b32_e32 v3, s69
	v_cndmask_b32_e32 v1, 0, v165, vcc
	v_cndmask_b32_e32 v0, v0, v164, vcc
	v_cndmask_b32_e32 v3, v2, v3, vcc
	v_mov_b32_e32 v2, s70
	v_mov_b32_e32 v17, s68
	v_cndmask_b32_e32 v2, v2, v17, vcc
	v_lshlrev_b64 v[0:1], 12, v[0:1]
	v_lshl_add_u64 v[2:3], v[2:3], 0, v[0:1]
	v_mov_b32_e32 v133, v149
	v_lshl_add_u64 v[2:3], v[2:3], 0, v[132:133]
	v_cndmask_b32_e64 v17, 0, v2, s[8:9]
	v_cndmask_b32_e64 v18, 0, v3, s[8:9]
	v_mov_b32_e32 v2, s77
	v_mov_b32_e32 v3, s74
	v_cndmask_b32_e32 v3, v2, v3, vcc
	v_mov_b32_e32 v2, s76
	v_mov_b32_e32 v19, s73
	v_cndmask_b32_e32 v2, v2, v19, vcc
	v_lshl_add_u64 v[0:1], v[2:3], 0, v[0:1]
	v_lshl_add_u64 v[0:1], v[0:1], 0, v[132:133]
	v_cndmask_b32_e64 v19, v18, v1, s[10:11]
	v_cndmask_b32_e64 v18, v17, v0, s[10:11]
	v_lshlrev_b64 v[0:1], 11, v[164:165]
	v_lshl_add_u64 v[24:25], v[134:135], 0, v[0:1]
	v_pk_mul_f32 v[0:1], v[20:21], v[16:17] op_sel_hi:[1,0]
	v_pk_mul_f32 v[20:21], v[22:23], v[16:17] op_sel_hi:[1,0]
	v_cmp_ne_u64_e32 vcc, 0, v[18:19]
	v_pk_mul_f32 v[2:3], v[62:63], v[0:1]
	v_pk_mul_f32 v[0:1], v[60:61], v[20:21]
	s_nop 0
	v_cvt_pk_bf16_f32 v232, v0, v1
	v_cvt_pk_bf16_f32 v233, v2, v3
	s_and_saveexec_b64 s[4:5], vcc
	s_cbranch_execz .LBB0_792
	global_store_dwordx4 v[18:19], v[0:3], off nt
.LBB0_792:
	s_or_b64 exec, exec, s[4:5]
	v_mov_b32_e32 v17, v16
	v_mov_b32_e32 v20, v16
	v_mov_b32_e32 v21, v16
	v_pk_mul_f32 v[0:1], v[12:13], v[20:21]
	v_pk_mul_f32 v[12:13], v[14:15], v[16:17]
	v_pk_mul_f32 v[2:3], v[54:55], v[0:1]
	v_pk_mul_f32 v[0:1], v[52:53], v[12:13]
	s_nop 0
	v_cvt_pk_bf16_f32 v234, v0, v1
	v_cvt_pk_bf16_f32 v235, v2, v3
	s_nop 1
	v_permlane16_swap_b32_e32 v232, v234
	v_permlane16_swap_b32_e32 v233, v235
	v_lshl_add_u64 v[236:237], v[24:25], 0, v[238:239]
	flat_store_dwordx4 v[236:237], v[232:235]
	s_nop 1
	s_and_saveexec_b64 s[4:5], vcc
	s_cbranch_execz .LBB0_794
	global_store_dwordx4 v[18:19], v[0:3], off offset:64 nt
.LBB0_794:
	s_or_b64 exec, exec, s[4:5]
	s_nop 0
	v_pk_mul_f32 v[0:1], v[8:9], v[20:21]
	v_pk_mul_f32 v[8:9], v[10:11], v[16:17]
	v_pk_mul_f32 v[2:3], v[58:59], v[0:1]
	v_pk_mul_f32 v[0:1], v[56:57], v[8:9]
	s_nop 0
	v_cvt_pk_bf16_f32 v232, v0, v1
	v_cvt_pk_bf16_f32 v233, v2, v3
	s_and_saveexec_b64 s[4:5], vcc
	s_cbranch_execz .LBB0_796
	global_store_dwordx4 v[18:19], v[0:3], off offset:128 nt
.LBB0_796:
	s_or_b64 exec, exec, s[4:5]
	s_nop 0
	v_mov_b32_e32 v0, v16
	v_mov_b32_e32 v1, v16
	v_pk_mul_f32 v[0:1], v[4:5], v[0:1]
	v_pk_mul_f32 v[4:5], v[6:7], v[16:17]
	v_pk_mul_f32 v[2:3], v[50:51], v[0:1]
	v_pk_mul_f32 v[0:1], v[48:49], v[4:5]
	s_nop 0
	v_cvt_pk_bf16_f32 v234, v0, v1
	v_cvt_pk_bf16_f32 v235, v2, v3
	s_nop 1
	v_permlane16_swap_b32_e32 v232, v234
	v_permlane16_swap_b32_e32 v233, v235
	v_lshl_add_u64 v[236:237], v[24:25], 0, v[238:239]
	flat_store_dwordx4 v[236:237], v[232:235] offset:64
	s_nop 1
	s_and_saveexec_b64 s[4:5], vcc
	s_cbranch_execz .LBB0_798
	global_store_dwordx4 v[18:19], v[0:3], off offset:192 nt
